# static priority: all per-segment s_setprio toggles removed from the GEMM K-loops (load segments carry no VALU any more)
# speedup vs baseline: 1.0024x; 1.0024x over previous
.LBB0_438:
	s_ashr_i32 s57, s56, 31
	s_lshl_b64 s[58:59], s[56:57], 19
	s_add_u32 s58, s0, s58
	s_addc_u32 s59, s1, s59
	s_and_b64 s[60:61], s[10:11], exec
	s_cselect_b32 s53, s59, s65
	s_cselect_b32 s57, s58, s64
	s_ashr_i32 s55, s54, 31
	s_lshl_b64 s[60:61], s[54:55], 19
	s_add_u32 s60, s3, s60
	s_addc_u32 s61, s22, s61
	s_and_b64 s[68:69], s[10:11], exec
	s_cselect_b32 s55, s61, s67
	s_cselect_b32 s63, s60, s66
	s_add_u32 s64, s64, 0x40080
	s_addc_u32 s65, s65, 0
	s_add_u32 s84, s66, 0x100
	s_addc_u32 s85, s67, 0
	s_mov_b32 s86, -2
	ds_read_b128 v[128:131], v192
	ds_read_b128 v[132:135], v192 offset:1024
	ds_read_b128 v[136:139], v192 offset:2048
	ds_read_b128 v[158:161], v192 offset:3072
	ds_read_b128 v[168:171], v193
	ds_read_b128 v[172:175], v193 offset:1024
	ds_read_b128 v[196:199], v193 offset:2048
	ds_read_b128 v[200:203], v193 offset:3072
	s_add_u32 s66, s64, 0xfffc0080
	s_addc_u32 s67, s65, -1
	s_cmp_eq_u32 s86, 12
	s_cselect_b32 s69, s53, s67
	s_cselect_b32 s68, s57, s66
	s_cselect_b32 s67, s55, s85
	s_cselect_b32 s66, s63, s84
	s_cselect_b32 s98, 1, 0
	s_add_i32 m0, s70, 0xc000
	ds_read_b128 v[204:207], v194
	ds_read_b128 v[208:211], v194 offset:1024
	ds_read_b128 v[212:215], v194 offset:2048
	ds_read_b128 v[216:219], v194 offset:3072
	ds_read_b128 v[220:223], v194 offset:4096
	ds_read_b128 v[224:227], v194 offset:5120
	ds_read_b128 v[228:231], v194 offset:6144
	ds_read_b128 v[232:235], v194 offset:7168
	global_load_lds_dwordx4 v150, s[64:65]
	s_add_i32 m0, s70, 0xe000
	s_nop 0
	global_load_lds_dwordx4 v152, s[64:65]
	s_waitcnt vmcnt(8)
	s_waitcnt lgkmcnt(0)
	s_cmp_lg_u32 s98, 0
	s_cbranch_scc0 .Lg1_nopf_pk
	s_lshl_b32 s99, s52, 8
	v_add_u32_e32 v240, s99, v165
	v_ashrrev_i32_e32 v241, 31, v240
	v_lshl_add_u64 v[240:241], v[240:241], 2, s[20:21]
	global_load_dword v242, v[240:241], off
	global_load_dword v243, v[240:241], off offset:64
	global_load_dword v244, v[240:241], off offset:128
	global_load_dword v245, v[240:241], off offset:192
	global_load_dword v246, v[240:241], off offset:512
	global_load_dword v248, v[240:241], off offset:576
	global_load_dword v249, v[240:241], off offset:640
	global_load_dword v250, v[240:241], off offset:704
.Lg1_nopf_pk:
	s_barrier
	v_mfma_f32_16x16x32_bf16 v[124:127], v[128:131], v[204:207], 0
	v_mfma_f32_16x16x32_bf16 v[120:123], v[136:139], v[204:207], 0
	v_mfma_f32_16x16x32_bf16 v[96:99], v[128:131], v[212:215], 0
	v_mfma_f32_16x16x32_bf16 v[88:91], v[136:139], v[212:215], 0
	v_mfma_f32_16x16x32_bf16 v[76:79], v[128:131], v[220:223], 0
	v_mfma_f32_16x16x32_bf16 v[72:75], v[136:139], v[220:223], 0
	v_mfma_f32_16x16x32_bf16 v[60:63], v[128:131], v[228:231], 0
	v_mfma_f32_16x16x32_bf16 v[108:111], v[136:139], v[228:231], 0
	v_mfma_f32_16x16x32_bf16 v[124:127], v[132:135], v[208:211], v[124:127]
	v_mfma_f32_16x16x32_bf16 v[120:123], v[158:161], v[208:211], v[120:123]
	v_mfma_f32_16x16x32_bf16 v[96:99], v[132:135], v[216:219], v[96:99]
	v_mfma_f32_16x16x32_bf16 v[88:91], v[158:161], v[216:219], v[88:91]
	v_mfma_f32_16x16x32_bf16 v[76:79], v[132:135], v[224:227], v[76:79]
	v_mfma_f32_16x16x32_bf16 v[72:75], v[158:161], v[224:227], v[72:75]
	v_mfma_f32_16x16x32_bf16 v[60:63], v[132:135], v[232:235], v[60:63]
	v_mfma_f32_16x16x32_bf16 v[108:111], v[158:161], v[232:235], v[108:111]
	v_mfma_f32_16x16x32_bf16 v[116:119], v[168:171], v[204:207], 0
	v_mfma_f32_16x16x32_bf16 v[112:115], v[196:199], v[204:207], 0
	v_mfma_f32_16x16x32_bf16 v[84:87], v[168:171], v[212:215], 0
	v_mfma_f32_16x16x32_bf16 v[80:83], v[196:199], v[212:215], 0
	v_mfma_f32_16x16x32_bf16 v[68:71], v[168:171], v[220:223], 0
	v_mfma_f32_16x16x32_bf16 v[64:67], v[196:199], v[220:223], 0
	v_mfma_f32_16x16x32_bf16 v[104:107], v[168:171], v[228:231], 0
	v_mfma_f32_16x16x32_bf16 v[56:59], v[196:199], v[228:231], 0
	v_mfma_f32_16x16x32_bf16 v[116:119], v[172:175], v[208:211], v[116:119]
	v_mfma_f32_16x16x32_bf16 v[112:115], v[200:203], v[208:211], v[112:115]
	v_mfma_f32_16x16x32_bf16 v[84:87], v[172:175], v[216:219], v[84:87]
	v_mfma_f32_16x16x32_bf16 v[80:83], v[200:203], v[216:219], v[80:83]
	v_mfma_f32_16x16x32_bf16 v[68:71], v[172:175], v[224:227], v[68:71]
	v_mfma_f32_16x16x32_bf16 v[64:67], v[200:203], v[224:227], v[64:67]
	v_mfma_f32_16x16x32_bf16 v[104:107], v[172:175], v[232:235], v[104:107]
	v_mfma_f32_16x16x32_bf16 v[56:59], v[200:203], v[232:235], v[56:59]
	s_barrier
	s_add_i32 s87, s82, s23
	s_add_u32 s98, s66, 0x80
	s_addc_u32 s99, s67, 0
	s_mov_b32 m0, s87
	ds_read_b128 v[204:207], v194 offset:16384
	ds_read_b128 v[208:211], v194 offset:17408
	ds_read_b128 v[212:215], v194 offset:18432
	ds_read_b128 v[216:219], v194 offset:19456
	ds_read_b128 v[220:223], v194 offset:20480
	ds_read_b128 v[224:227], v194 offset:21504
	ds_read_b128 v[228:231], v194 offset:22528
	ds_read_b128 v[232:235], v194 offset:23552
	global_load_lds_dwordx4 v140, s[66:67]
	s_add_i32 m0, s87, 0x2000
	s_add_u32 s88, s66, 0x40000
	s_addc_u32 s89, s67, 0
	s_add_i32 s87, s83, s23
	global_load_lds_dwordx4 v142, s[66:67]
	s_mov_b32 m0, s87
	s_add_u32 s100, s68, 0x80
	s_addc_u32 s101, s69, 0
	global_load_lds_dwordx4 v140, s[88:89]
	s_add_i32 m0, s87, 0x2000
	s_nop 0
	global_load_lds_dwordx4 v142, s[88:89]
	s_mov_b32 m0, s70
	s_nop 0
	global_load_lds_dwordx4 v140, s[68:69]
	s_mov_b32 m0, s71
	s_nop 0
	global_load_lds_dwordx4 v142, s[68:69]
	s_waitcnt vmcnt(8)
	s_waitcnt lgkmcnt(0)
	s_barrier
	v_mfma_f32_16x16x32_bf16 v[52:55], v[128:131], v[204:207], 0
	v_mfma_f32_16x16x32_bf16 v[48:51], v[136:139], v[204:207], 0
	v_mfma_f32_16x16x32_bf16 v[16:19], v[128:131], v[212:215], 0
	v_mfma_f32_16x16x32_bf16 v[8:11], v[136:139], v[212:215], 0
	v_mfma_f32_16x16x32_bf16 v[28:31], v[128:131], v[220:223], 0
	v_mfma_f32_16x16x32_bf16 v[24:27], v[136:139], v[220:223], 0
	v_mfma_f32_16x16x32_bf16 v[36:39], v[128:131], v[228:231], 0
	v_mfma_f32_16x16x32_bf16 v[100:103], v[136:139], v[228:231], 0
	v_mfma_f32_16x16x32_bf16 v[52:55], v[132:135], v[208:211], v[52:55]
	v_mfma_f32_16x16x32_bf16 v[48:51], v[158:161], v[208:211], v[48:51]
	v_mfma_f32_16x16x32_bf16 v[16:19], v[132:135], v[216:219], v[16:19]
	v_mfma_f32_16x16x32_bf16 v[8:11], v[158:161], v[216:219], v[8:11]
	v_mfma_f32_16x16x32_bf16 v[28:31], v[132:135], v[224:227], v[28:31]
	v_mfma_f32_16x16x32_bf16 v[24:27], v[158:161], v[224:227], v[24:27]
	v_mfma_f32_16x16x32_bf16 v[36:39], v[132:135], v[232:235], v[36:39]
	v_mfma_f32_16x16x32_bf16 v[100:103], v[158:161], v[232:235], v[100:103]
	v_mfma_f32_16x16x32_bf16 v[44:47], v[168:171], v[204:207], 0
	v_mfma_f32_16x16x32_bf16 v[40:43], v[196:199], v[204:207], 0
	v_mfma_f32_16x16x32_bf16 v[0:3], v[168:171], v[212:215], 0
	v_mfma_f32_16x16x32_bf16 v[4:7], v[196:199], v[212:215], 0
	v_mfma_f32_16x16x32_bf16 v[12:15], v[168:171], v[220:223], 0
	v_mfma_f32_16x16x32_bf16 v[20:23], v[196:199], v[220:223], 0
	v_mfma_f32_16x16x32_bf16 v[92:95], v[168:171], v[228:231], 0
	v_mfma_f32_16x16x32_bf16 v[32:35], v[196:199], v[228:231], 0
	v_mfma_f32_16x16x32_bf16 v[44:47], v[172:175], v[208:211], v[44:47]
	v_mfma_f32_16x16x32_bf16 v[40:43], v[200:203], v[208:211], v[40:43]
	v_mfma_f32_16x16x32_bf16 v[0:3], v[172:175], v[216:219], v[0:3]
	v_mfma_f32_16x16x32_bf16 v[4:7], v[200:203], v[216:219], v[4:7]
	v_mfma_f32_16x16x32_bf16 v[12:15], v[172:175], v[224:227], v[12:15]
	v_mfma_f32_16x16x32_bf16 v[20:23], v[200:203], v[224:227], v[20:23]
	v_mfma_f32_16x16x32_bf16 v[92:95], v[172:175], v[232:235], v[92:95]
	v_mfma_f32_16x16x32_bf16 v[32:35], v[200:203], v[232:235], v[32:35]
	s_barrier
	s_add_i32 s87, 0, 0x18000
	s_add_i32 s88, 0, 0x1c000
	v_add_u32_e32 v158, s87, v167
	v_add_u32_e32 v164, s88, v167
	ds_read_b128 v[128:131], v158
	ds_read_b128 v[132:135], v158 offset:1024
	ds_read_b128 v[136:139], v158 offset:2048
	ds_read_b128 v[158:161], v158 offset:3072
	ds_read_b128 v[168:171], v164
	ds_read_b128 v[172:175], v164 offset:1024
	ds_read_b128 v[196:199], v164 offset:2048
	ds_read_b128 v[200:203], v164 offset:3072
	s_add_u32 s68, s68, 0x40000
	s_addc_u32 s69, s69, 0
	s_mov_b32 m0, s72
	ds_read_b128 v[204:207], v194 offset:32768
	ds_read_b128 v[208:211], v194 offset:33792
	ds_read_b128 v[212:215], v194 offset:34816
	ds_read_b128 v[216:219], v194 offset:35840
	ds_read_b128 v[220:223], v194 offset:36864
	ds_read_b128 v[224:227], v194 offset:37888
	ds_read_b128 v[228:231], v194 offset:38912
	ds_read_b128 v[232:235], v194 offset:39936
	global_load_lds_dwordx4 v140, s[68:69]
	s_mov_b32 m0, s73
	s_nop 0
	global_load_lds_dwordx4 v142, s[68:69]
	s_waitcnt vmcnt(8)
	s_waitcnt lgkmcnt(0)
	s_barrier
	v_mfma_f32_16x16x32_bf16 v[124:127], v[128:131], v[204:207], v[124:127]
	v_mfma_f32_16x16x32_bf16 v[120:123], v[136:139], v[204:207], v[120:123]
	v_mfma_f32_16x16x32_bf16 v[96:99], v[128:131], v[212:215], v[96:99]
	v_mfma_f32_16x16x32_bf16 v[88:91], v[136:139], v[212:215], v[88:91]
	v_mfma_f32_16x16x32_bf16 v[76:79], v[128:131], v[220:223], v[76:79]
	v_mfma_f32_16x16x32_bf16 v[72:75], v[136:139], v[220:223], v[72:75]
	v_mfma_f32_16x16x32_bf16 v[60:63], v[128:131], v[228:231], v[60:63]
	v_mfma_f32_16x16x32_bf16 v[108:111], v[136:139], v[228:231], v[108:111]
	v_mfma_f32_16x16x32_bf16 v[124:127], v[132:135], v[208:211], v[124:127]
	v_mfma_f32_16x16x32_bf16 v[120:123], v[158:161], v[208:211], v[120:123]
	v_mfma_f32_16x16x32_bf16 v[96:99], v[132:135], v[216:219], v[96:99]
	v_mfma_f32_16x16x32_bf16 v[88:91], v[158:161], v[216:219], v[88:91]
	v_mfma_f32_16x16x32_bf16 v[76:79], v[132:135], v[224:227], v[76:79]
	v_mfma_f32_16x16x32_bf16 v[72:75], v[158:161], v[224:227], v[72:75]
	v_mfma_f32_16x16x32_bf16 v[60:63], v[132:135], v[232:235], v[60:63]
	v_mfma_f32_16x16x32_bf16 v[108:111], v[158:161], v[232:235], v[108:111]
	v_mfma_f32_16x16x32_bf16 v[116:119], v[168:171], v[204:207], v[116:119]
	v_mfma_f32_16x16x32_bf16 v[112:115], v[196:199], v[204:207], v[112:115]
	v_mfma_f32_16x16x32_bf16 v[84:87], v[168:171], v[212:215], v[84:87]
	v_mfma_f32_16x16x32_bf16 v[80:83], v[196:199], v[212:215], v[80:83]
	v_mfma_f32_16x16x32_bf16 v[68:71], v[168:171], v[220:223], v[68:71]
	v_mfma_f32_16x16x32_bf16 v[64:67], v[196:199], v[220:223], v[64:67]
	v_mfma_f32_16x16x32_bf16 v[104:107], v[168:171], v[228:231], v[104:107]
	v_mfma_f32_16x16x32_bf16 v[56:59], v[196:199], v[228:231], v[56:59]
	v_mfma_f32_16x16x32_bf16 v[116:119], v[172:175], v[208:211], v[116:119]
	v_mfma_f32_16x16x32_bf16 v[112:115], v[200:203], v[208:211], v[112:115]
	v_mfma_f32_16x16x32_bf16 v[84:87], v[172:175], v[216:219], v[84:87]
	v_mfma_f32_16x16x32_bf16 v[80:83], v[200:203], v[216:219], v[80:83]
	v_mfma_f32_16x16x32_bf16 v[68:71], v[172:175], v[224:227], v[68:71]
	v_mfma_f32_16x16x32_bf16 v[64:67], v[200:203], v[224:227], v[64:67]
	v_mfma_f32_16x16x32_bf16 v[104:107], v[172:175], v[232:235], v[104:107]
	v_mfma_f32_16x16x32_bf16 v[56:59], v[200:203], v[232:235], v[56:59]
	s_barrier
	s_add_i32 s68, s87, s23
	s_mov_b32 m0, s68
	ds_read_b128 v[204:207], v194 offset:49152
	ds_read_b128 v[208:211], v194 offset:50176
	ds_read_b128 v[212:215], v194 offset:51200
	ds_read_b128 v[216:219], v194 offset:52224
	ds_read_b128 v[220:223], v194 offset:53248
	ds_read_b128 v[224:227], v194 offset:54272
	ds_read_b128 v[228:231], v194 offset:55296
	ds_read_b128 v[232:235], v194 offset:56320
	global_load_lds_dwordx4 v140, s[98:99]
	s_add_i32 m0, s68, 0x2000
	s_add_u32 s66, s66, 0x40080
	s_addc_u32 s67, s67, 0
	s_add_i32 s68, s88, s23
	global_load_lds_dwordx4 v142, s[98:99]
	s_mov_b32 m0, s68
	s_nop 0
	global_load_lds_dwordx4 v140, s[66:67]
	s_add_i32 m0, s68, 0x2000
	s_nop 0
	global_load_lds_dwordx4 v142, s[66:67]
	s_mov_b32 m0, s80
	s_nop 0
	global_load_lds_dwordx4 v140, s[100:101]
	s_mov_b32 m0, s81
	s_nop 0
	global_load_lds_dwordx4 v142, s[100:101]
	s_waitcnt vmcnt(8)
	s_waitcnt lgkmcnt(0)
	s_barrier
	v_mfma_f32_16x16x32_bf16 v[52:55], v[128:131], v[204:207], v[52:55]
	v_mfma_f32_16x16x32_bf16 v[48:51], v[136:139], v[204:207], v[48:51]
	v_mfma_f32_16x16x32_bf16 v[16:19], v[128:131], v[212:215], v[16:19]
	v_mfma_f32_16x16x32_bf16 v[8:11], v[136:139], v[212:215], v[8:11]
	v_mfma_f32_16x16x32_bf16 v[28:31], v[128:131], v[220:223], v[28:31]
	v_mfma_f32_16x16x32_bf16 v[24:27], v[136:139], v[220:223], v[24:27]
	v_mfma_f32_16x16x32_bf16 v[36:39], v[128:131], v[228:231], v[36:39]
	v_mfma_f32_16x16x32_bf16 v[100:103], v[136:139], v[228:231], v[100:103]
	v_mfma_f32_16x16x32_bf16 v[52:55], v[132:135], v[208:211], v[52:55]
	v_mfma_f32_16x16x32_bf16 v[48:51], v[158:161], v[208:211], v[48:51]
	v_mfma_f32_16x16x32_bf16 v[16:19], v[132:135], v[216:219], v[16:19]
	v_mfma_f32_16x16x32_bf16 v[8:11], v[158:161], v[216:219], v[8:11]
	v_mfma_f32_16x16x32_bf16 v[28:31], v[132:135], v[224:227], v[28:31]
	v_mfma_f32_16x16x32_bf16 v[24:27], v[158:161], v[224:227], v[24:27]
	v_mfma_f32_16x16x32_bf16 v[36:39], v[132:135], v[232:235], v[36:39]
	v_mfma_f32_16x16x32_bf16 v[100:103], v[158:161], v[232:235], v[100:103]
	v_mfma_f32_16x16x32_bf16 v[44:47], v[168:171], v[204:207], v[44:47]
	v_mfma_f32_16x16x32_bf16 v[40:43], v[196:199], v[204:207], v[40:43]
	v_mfma_f32_16x16x32_bf16 v[0:3], v[168:171], v[212:215], v[0:3]
	v_mfma_f32_16x16x32_bf16 v[4:7], v[196:199], v[212:215], v[4:7]
	v_mfma_f32_16x16x32_bf16 v[12:15], v[168:171], v[220:223], v[12:15]
	v_mfma_f32_16x16x32_bf16 v[20:23], v[196:199], v[220:223], v[20:23]
	v_mfma_f32_16x16x32_bf16 v[92:95], v[168:171], v[228:231], v[92:95]
	v_mfma_f32_16x16x32_bf16 v[32:35], v[196:199], v[228:231], v[32:35]
	v_mfma_f32_16x16x32_bf16 v[44:47], v[172:175], v[208:211], v[44:47]
	v_mfma_f32_16x16x32_bf16 v[40:43], v[200:203], v[208:211], v[40:43]
	v_mfma_f32_16x16x32_bf16 v[0:3], v[172:175], v[216:219], v[0:3]
	v_mfma_f32_16x16x32_bf16 v[4:7], v[200:203], v[216:219], v[4:7]
	v_mfma_f32_16x16x32_bf16 v[12:15], v[172:175], v[224:227], v[12:15]
	v_mfma_f32_16x16x32_bf16 v[20:23], v[200:203], v[224:227], v[20:23]
	v_mfma_f32_16x16x32_bf16 v[92:95], v[172:175], v[232:235], v[92:95]
	v_mfma_f32_16x16x32_bf16 v[32:35], v[200:203], v[232:235], v[32:35]
	s_barrier
	s_add_i32 s86, s86, 2
	s_add_u32 s64, s64, 0x100
	s_addc_u32 s65, s65, 0
	s_add_u32 s84, s84, 0x100
	s_addc_u32 s85, s85, 0
	s_cmp_gt_u32 s86, 13
	s_cbranch_scc1 .Lkx_439
.LBB0_439:
	ds_read_b128 v[128:131], v192
	ds_read_b128 v[132:135], v192 offset:1024
	ds_read_b128 v[136:139], v192 offset:2048
	ds_read_b128 v[158:161], v192 offset:3072
	ds_read_b128 v[168:171], v193
	ds_read_b128 v[172:175], v193 offset:1024
	ds_read_b128 v[196:199], v193 offset:2048
	ds_read_b128 v[200:203], v193 offset:3072
	s_add_u32 s66, s64, 0xfffc0080
	s_addc_u32 s67, s65, -1
	s_cmp_eq_u32 s86, 12
	s_cselect_b32 s69, s53, s67
	s_cselect_b32 s68, s57, s66
	s_cselect_b32 s67, s55, s85
	s_cselect_b32 s66, s63, s84
	s_cselect_b32 s98, 1, 0
	s_add_i32 m0, s70, 0xc000
	ds_read_b128 v[204:207], v194
	ds_read_b128 v[208:211], v194 offset:1024
	ds_read_b128 v[212:215], v194 offset:2048
	ds_read_b128 v[216:219], v194 offset:3072
	ds_read_b128 v[220:223], v194 offset:4096
	ds_read_b128 v[224:227], v194 offset:5120
	ds_read_b128 v[228:231], v194 offset:6144
	ds_read_b128 v[232:235], v194 offset:7168
	global_load_lds_dwordx4 v150, s[64:65]
	s_add_i32 m0, s70, 0xe000
	s_nop 0
	global_load_lds_dwordx4 v152, s[64:65]
	s_waitcnt vmcnt(8)
	s_waitcnt lgkmcnt(0)
	s_cmp_lg_u32 s98, 0
	s_cbranch_scc0 .Lg1_nopf
	s_lshl_b32 s99, s52, 8
	v_add_u32_e32 v240, s99, v165
	v_ashrrev_i32_e32 v241, 31, v240
	v_lshl_add_u64 v[240:241], v[240:241], 2, s[20:21]
	global_load_dword v242, v[240:241], off
	global_load_dword v243, v[240:241], off offset:64
	global_load_dword v244, v[240:241], off offset:128
	global_load_dword v245, v[240:241], off offset:192
	global_load_dword v246, v[240:241], off offset:512
	global_load_dword v248, v[240:241], off offset:576
	global_load_dword v249, v[240:241], off offset:640
	global_load_dword v250, v[240:241], off offset:704
.Lg1_nopf:
	s_barrier
	v_mfma_f32_16x16x32_bf16 v[124:127], v[128:131], v[204:207], v[124:127]
	v_mfma_f32_16x16x32_bf16 v[120:123], v[136:139], v[204:207], v[120:123]
	v_mfma_f32_16x16x32_bf16 v[96:99], v[128:131], v[212:215], v[96:99]
	v_mfma_f32_16x16x32_bf16 v[88:91], v[136:139], v[212:215], v[88:91]
	v_mfma_f32_16x16x32_bf16 v[76:79], v[128:131], v[220:223], v[76:79]
	v_mfma_f32_16x16x32_bf16 v[72:75], v[136:139], v[220:223], v[72:75]
	v_mfma_f32_16x16x32_bf16 v[60:63], v[128:131], v[228:231], v[60:63]
	v_mfma_f32_16x16x32_bf16 v[108:111], v[136:139], v[228:231], v[108:111]
	v_mfma_f32_16x16x32_bf16 v[124:127], v[132:135], v[208:211], v[124:127]
	v_mfma_f32_16x16x32_bf16 v[120:123], v[158:161], v[208:211], v[120:123]
	v_mfma_f32_16x16x32_bf16 v[96:99], v[132:135], v[216:219], v[96:99]
	v_mfma_f32_16x16x32_bf16 v[88:91], v[158:161], v[216:219], v[88:91]
	v_mfma_f32_16x16x32_bf16 v[76:79], v[132:135], v[224:227], v[76:79]
	v_mfma_f32_16x16x32_bf16 v[72:75], v[158:161], v[224:227], v[72:75]
	v_mfma_f32_16x16x32_bf16 v[60:63], v[132:135], v[232:235], v[60:63]
	v_mfma_f32_16x16x32_bf16 v[108:111], v[158:161], v[232:235], v[108:111]
	v_mfma_f32_16x16x32_bf16 v[116:119], v[168:171], v[204:207], v[116:119]
	v_mfma_f32_16x16x32_bf16 v[112:115], v[196:199], v[204:207], v[112:115]
	v_mfma_f32_16x16x32_bf16 v[84:87], v[168:171], v[212:215], v[84:87]
	v_mfma_f32_16x16x32_bf16 v[80:83], v[196:199], v[212:215], v[80:83]
	v_mfma_f32_16x16x32_bf16 v[68:71], v[168:171], v[220:223], v[68:71]
	v_mfma_f32_16x16x32_bf16 v[64:67], v[196:199], v[220:223], v[64:67]
	v_mfma_f32_16x16x32_bf16 v[104:107], v[168:171], v[228:231], v[104:107]
	v_mfma_f32_16x16x32_bf16 v[56:59], v[196:199], v[228:231], v[56:59]
	v_mfma_f32_16x16x32_bf16 v[116:119], v[172:175], v[208:211], v[116:119]
	v_mfma_f32_16x16x32_bf16 v[112:115], v[200:203], v[208:211], v[112:115]
	v_mfma_f32_16x16x32_bf16 v[84:87], v[172:175], v[216:219], v[84:87]
	v_mfma_f32_16x16x32_bf16 v[80:83], v[200:203], v[216:219], v[80:83]
	v_mfma_f32_16x16x32_bf16 v[68:71], v[172:175], v[224:227], v[68:71]
	v_mfma_f32_16x16x32_bf16 v[64:67], v[200:203], v[224:227], v[64:67]
	v_mfma_f32_16x16x32_bf16 v[104:107], v[172:175], v[232:235], v[104:107]
	v_mfma_f32_16x16x32_bf16 v[56:59], v[200:203], v[232:235], v[56:59]
	s_barrier
	s_add_i32 s87, s82, s23
	s_add_u32 s98, s66, 0x80
	s_addc_u32 s99, s67, 0
	s_mov_b32 m0, s87
	ds_read_b128 v[204:207], v194 offset:16384
	ds_read_b128 v[208:211], v194 offset:17408
	ds_read_b128 v[212:215], v194 offset:18432
	ds_read_b128 v[216:219], v194 offset:19456
	ds_read_b128 v[220:223], v194 offset:20480
	ds_read_b128 v[224:227], v194 offset:21504
	ds_read_b128 v[228:231], v194 offset:22528
	ds_read_b128 v[232:235], v194 offset:23552
	global_load_lds_dwordx4 v140, s[66:67]
	s_add_i32 m0, s87, 0x2000
	s_add_u32 s88, s66, 0x40000
	s_addc_u32 s89, s67, 0
	s_add_i32 s87, s83, s23
	global_load_lds_dwordx4 v142, s[66:67]
	s_mov_b32 m0, s87
	s_add_u32 s100, s68, 0x80
	s_addc_u32 s101, s69, 0
	global_load_lds_dwordx4 v140, s[88:89]
	s_add_i32 m0, s87, 0x2000
	s_nop 0
	global_load_lds_dwordx4 v142, s[88:89]
	s_mov_b32 m0, s70
	s_nop 0
	global_load_lds_dwordx4 v140, s[68:69]
	s_mov_b32 m0, s71
	s_nop 0
	global_load_lds_dwordx4 v142, s[68:69]
	s_waitcnt vmcnt(8)
	s_waitcnt lgkmcnt(0)
	s_barrier
	v_mfma_f32_16x16x32_bf16 v[52:55], v[128:131], v[204:207], v[52:55]
	v_mfma_f32_16x16x32_bf16 v[48:51], v[136:139], v[204:207], v[48:51]
	v_mfma_f32_16x16x32_bf16 v[16:19], v[128:131], v[212:215], v[16:19]
	v_mfma_f32_16x16x32_bf16 v[8:11], v[136:139], v[212:215], v[8:11]
	v_mfma_f32_16x16x32_bf16 v[28:31], v[128:131], v[220:223], v[28:31]
	v_mfma_f32_16x16x32_bf16 v[24:27], v[136:139], v[220:223], v[24:27]
	v_mfma_f32_16x16x32_bf16 v[36:39], v[128:131], v[228:231], v[36:39]
	v_mfma_f32_16x16x32_bf16 v[100:103], v[136:139], v[228:231], v[100:103]
	v_mfma_f32_16x16x32_bf16 v[52:55], v[132:135], v[208:211], v[52:55]
	v_mfma_f32_16x16x32_bf16 v[48:51], v[158:161], v[208:211], v[48:51]
	v_mfma_f32_16x16x32_bf16 v[16:19], v[132:135], v[216:219], v[16:19]
	v_mfma_f32_16x16x32_bf16 v[8:11], v[158:161], v[216:219], v[8:11]
	v_mfma_f32_16x16x32_bf16 v[28:31], v[132:135], v[224:227], v[28:31]
	v_mfma_f32_16x16x32_bf16 v[24:27], v[158:161], v[224:227], v[24:27]
	v_mfma_f32_16x16x32_bf16 v[36:39], v[132:135], v[232:235], v[36:39]
	v_mfma_f32_16x16x32_bf16 v[100:103], v[158:161], v[232:235], v[100:103]
	v_mfma_f32_16x16x32_bf16 v[44:47], v[168:171], v[204:207], v[44:47]
	v_mfma_f32_16x16x32_bf16 v[40:43], v[196:199], v[204:207], v[40:43]
	v_mfma_f32_16x16x32_bf16 v[0:3], v[168:171], v[212:215], v[0:3]
	v_mfma_f32_16x16x32_bf16 v[4:7], v[196:199], v[212:215], v[4:7]
	v_mfma_f32_16x16x32_bf16 v[12:15], v[168:171], v[220:223], v[12:15]
	v_mfma_f32_16x16x32_bf16 v[20:23], v[196:199], v[220:223], v[20:23]
	v_mfma_f32_16x16x32_bf16 v[92:95], v[168:171], v[228:231], v[92:95]
	v_mfma_f32_16x16x32_bf16 v[32:35], v[196:199], v[228:231], v[32:35]
	v_mfma_f32_16x16x32_bf16 v[44:47], v[172:175], v[208:211], v[44:47]
	v_mfma_f32_16x16x32_bf16 v[40:43], v[200:203], v[208:211], v[40:43]
	v_mfma_f32_16x16x32_bf16 v[0:3], v[172:175], v[216:219], v[0:3]
	v_mfma_f32_16x16x32_bf16 v[4:7], v[200:203], v[216:219], v[4:7]
	v_mfma_f32_16x16x32_bf16 v[12:15], v[172:175], v[224:227], v[12:15]
	v_mfma_f32_16x16x32_bf16 v[20:23], v[200:203], v[224:227], v[20:23]
	v_mfma_f32_16x16x32_bf16 v[92:95], v[172:175], v[232:235], v[92:95]
	v_mfma_f32_16x16x32_bf16 v[32:35], v[200:203], v[232:235], v[32:35]
	s_barrier
	s_add_i32 s87, 0, 0x18000
	s_add_i32 s88, 0, 0x1c000
	v_add_u32_e32 v158, s87, v167
	v_add_u32_e32 v164, s88, v167
	ds_read_b128 v[128:131], v158
	ds_read_b128 v[132:135], v158 offset:1024
	ds_read_b128 v[136:139], v158 offset:2048
	ds_read_b128 v[158:161], v158 offset:3072
	ds_read_b128 v[168:171], v164
	ds_read_b128 v[172:175], v164 offset:1024
	ds_read_b128 v[196:199], v164 offset:2048
	ds_read_b128 v[200:203], v164 offset:3072
	s_add_u32 s68, s68, 0x40000
	s_addc_u32 s69, s69, 0
	s_mov_b32 m0, s72
	ds_read_b128 v[204:207], v194 offset:32768
	ds_read_b128 v[208:211], v194 offset:33792
	ds_read_b128 v[212:215], v194 offset:34816
	ds_read_b128 v[216:219], v194 offset:35840
	ds_read_b128 v[220:223], v194 offset:36864
	ds_read_b128 v[224:227], v194 offset:37888
	ds_read_b128 v[228:231], v194 offset:38912
	ds_read_b128 v[232:235], v194 offset:39936
	global_load_lds_dwordx4 v140, s[68:69]
	s_mov_b32 m0, s73
	s_nop 0
	global_load_lds_dwordx4 v142, s[68:69]
	s_waitcnt vmcnt(8)
	s_waitcnt lgkmcnt(0)
	s_barrier
	v_mfma_f32_16x16x32_bf16 v[124:127], v[128:131], v[204:207], v[124:127]
	v_mfma_f32_16x16x32_bf16 v[120:123], v[136:139], v[204:207], v[120:123]
	v_mfma_f32_16x16x32_bf16 v[96:99], v[128:131], v[212:215], v[96:99]
	v_mfma_f32_16x16x32_bf16 v[88:91], v[136:139], v[212:215], v[88:91]
	v_mfma_f32_16x16x32_bf16 v[76:79], v[128:131], v[220:223], v[76:79]
	v_mfma_f32_16x16x32_bf16 v[72:75], v[136:139], v[220:223], v[72:75]
	v_mfma_f32_16x16x32_bf16 v[60:63], v[128:131], v[228:231], v[60:63]
	v_mfma_f32_16x16x32_bf16 v[108:111], v[136:139], v[228:231], v[108:111]
	v_mfma_f32_16x16x32_bf16 v[124:127], v[132:135], v[208:211], v[124:127]
	v_mfma_f32_16x16x32_bf16 v[120:123], v[158:161], v[208:211], v[120:123]
	v_mfma_f32_16x16x32_bf16 v[96:99], v[132:135], v[216:219], v[96:99]
	v_mfma_f32_16x16x32_bf16 v[88:91], v[158:161], v[216:219], v[88:91]
	v_mfma_f32_16x16x32_bf16 v[76:79], v[132:135], v[224:227], v[76:79]
	v_mfma_f32_16x16x32_bf16 v[72:75], v[158:161], v[224:227], v[72:75]
	v_mfma_f32_16x16x32_bf16 v[60:63], v[132:135], v[232:235], v[60:63]
	v_mfma_f32_16x16x32_bf16 v[108:111], v[158:161], v[232:235], v[108:111]
	v_mfma_f32_16x16x32_bf16 v[116:119], v[168:171], v[204:207], v[116:119]
	v_mfma_f32_16x16x32_bf16 v[112:115], v[196:199], v[204:207], v[112:115]
	v_mfma_f32_16x16x32_bf16 v[84:87], v[168:171], v[212:215], v[84:87]
	v_mfma_f32_16x16x32_bf16 v[80:83], v[196:199], v[212:215], v[80:83]
	v_mfma_f32_16x16x32_bf16 v[68:71], v[168:171], v[220:223], v[68:71]
	v_mfma_f32_16x16x32_bf16 v[64:67], v[196:199], v[220:223], v[64:67]
	v_mfma_f32_16x16x32_bf16 v[104:107], v[168:171], v[228:231], v[104:107]
	v_mfma_f32_16x16x32_bf16 v[56:59], v[196:199], v[228:231], v[56:59]
	v_mfma_f32_16x16x32_bf16 v[116:119], v[172:175], v[208:211], v[116:119]
	v_mfma_f32_16x16x32_bf16 v[112:115], v[200:203], v[208:211], v[112:115]
	v_mfma_f32_16x16x32_bf16 v[84:87], v[172:175], v[216:219], v[84:87]
	v_mfma_f32_16x16x32_bf16 v[80:83], v[200:203], v[216:219], v[80:83]
	v_mfma_f32_16x16x32_bf16 v[68:71], v[172:175], v[224:227], v[68:71]
	v_mfma_f32_16x16x32_bf16 v[64:67], v[200:203], v[224:227], v[64:67]
	v_mfma_f32_16x16x32_bf16 v[104:107], v[172:175], v[232:235], v[104:107]
	v_mfma_f32_16x16x32_bf16 v[56:59], v[200:203], v[232:235], v[56:59]
	s_barrier
	s_add_i32 s68, s87, s23
	s_mov_b32 m0, s68
	ds_read_b128 v[204:207], v194 offset:49152
	ds_read_b128 v[208:211], v194 offset:50176
	ds_read_b128 v[212:215], v194 offset:51200
	ds_read_b128 v[216:219], v194 offset:52224
	ds_read_b128 v[220:223], v194 offset:53248
	ds_read_b128 v[224:227], v194 offset:54272
	ds_read_b128 v[228:231], v194 offset:55296
	ds_read_b128 v[232:235], v194 offset:56320
	global_load_lds_dwordx4 v140, s[98:99]
	s_add_i32 m0, s68, 0x2000
	s_add_u32 s66, s66, 0x40080
	s_addc_u32 s67, s67, 0
	s_add_i32 s68, s88, s23
	global_load_lds_dwordx4 v142, s[98:99]
	s_mov_b32 m0, s68
	s_nop 0
	global_load_lds_dwordx4 v140, s[66:67]
	s_add_i32 m0, s68, 0x2000
	s_nop 0
	global_load_lds_dwordx4 v142, s[66:67]
	s_mov_b32 m0, s80
	s_nop 0
	global_load_lds_dwordx4 v140, s[100:101]
	s_mov_b32 m0, s81
	s_nop 0
	global_load_lds_dwordx4 v142, s[100:101]
	s_waitcnt vmcnt(8)
	s_waitcnt lgkmcnt(0)
	s_barrier
	v_mfma_f32_16x16x32_bf16 v[52:55], v[128:131], v[204:207], v[52:55]
	v_mfma_f32_16x16x32_bf16 v[48:51], v[136:139], v[204:207], v[48:51]
	v_mfma_f32_16x16x32_bf16 v[16:19], v[128:131], v[212:215], v[16:19]
	v_mfma_f32_16x16x32_bf16 v[8:11], v[136:139], v[212:215], v[8:11]
	v_mfma_f32_16x16x32_bf16 v[28:31], v[128:131], v[220:223], v[28:31]
	v_mfma_f32_16x16x32_bf16 v[24:27], v[136:139], v[220:223], v[24:27]
	v_mfma_f32_16x16x32_bf16 v[36:39], v[128:131], v[228:231], v[36:39]
	v_mfma_f32_16x16x32_bf16 v[100:103], v[136:139], v[228:231], v[100:103]
	v_mfma_f32_16x16x32_bf16 v[52:55], v[132:135], v[208:211], v[52:55]
	v_mfma_f32_16x16x32_bf16 v[48:51], v[158:161], v[208:211], v[48:51]
	v_mfma_f32_16x16x32_bf16 v[16:19], v[132:135], v[216:219], v[16:19]
	v_mfma_f32_16x16x32_bf16 v[8:11], v[158:161], v[216:219], v[8:11]
	v_mfma_f32_16x16x32_bf16 v[28:31], v[132:135], v[224:227], v[28:31]
	v_mfma_f32_16x16x32_bf16 v[24:27], v[158:161], v[224:227], v[24:27]
	v_mfma_f32_16x16x32_bf16 v[36:39], v[132:135], v[232:235], v[36:39]
	v_mfma_f32_16x16x32_bf16 v[100:103], v[158:161], v[232:235], v[100:103]
	v_mfma_f32_16x16x32_bf16 v[44:47], v[168:171], v[204:207], v[44:47]
	v_mfma_f32_16x16x32_bf16 v[40:43], v[196:199], v[204:207], v[40:43]
	v_mfma_f32_16x16x32_bf16 v[0:3], v[168:171], v[212:215], v[0:3]
	v_mfma_f32_16x16x32_bf16 v[4:7], v[196:199], v[212:215], v[4:7]
	v_mfma_f32_16x16x32_bf16 v[12:15], v[168:171], v[220:223], v[12:15]
	v_mfma_f32_16x16x32_bf16 v[20:23], v[196:199], v[220:223], v[20:23]
	v_mfma_f32_16x16x32_bf16 v[92:95], v[168:171], v[228:231], v[92:95]
	v_mfma_f32_16x16x32_bf16 v[32:35], v[196:199], v[228:231], v[32:35]
	v_mfma_f32_16x16x32_bf16 v[44:47], v[172:175], v[208:211], v[44:47]
	v_mfma_f32_16x16x32_bf16 v[40:43], v[200:203], v[208:211], v[40:43]
	v_mfma_f32_16x16x32_bf16 v[0:3], v[172:175], v[216:219], v[0:3]
	v_mfma_f32_16x16x32_bf16 v[4:7], v[200:203], v[216:219], v[4:7]
	v_mfma_f32_16x16x32_bf16 v[12:15], v[172:175], v[224:227], v[12:15]
	v_mfma_f32_16x16x32_bf16 v[20:23], v[200:203], v[224:227], v[20:23]
	v_mfma_f32_16x16x32_bf16 v[92:95], v[172:175], v[232:235], v[92:95]
	v_mfma_f32_16x16x32_bf16 v[32:35], v[200:203], v[232:235], v[32:35]
	s_barrier
	s_add_i32 s86, s86, 2
	s_add_u32 s64, s64, 0x100
	s_addc_u32 s65, s65, 0
	s_add_u32 s84, s84, 0x100
	s_addc_u32 s85, s85, 0
	s_cmp_gt_u32 s86, 13
	s_cbranch_scc0 .LBB0_439

.LBB0_503:
	s_ashr_i32 s39, s38, 31
	s_lshl_b64 s[40:41], s[38:39], 19
	s_add_u32 s40, s0, s40
	s_addc_u32 s41, s1, s41
	s_and_b64 s[42:43], s[6:7], exec
	s_cselect_b32 s39, s41, s47
	s_cselect_b32 s45, s40, s46
	s_ashr_i32 s37, s36, 31
	s_lshl_b64 s[42:43], s[36:37], 19
	s_add_u32 s42, s22, s42
	s_addc_u32 s43, s23, s43
	s_and_b64 s[50:51], s[6:7], exec
	s_cselect_b32 s37, s43, s49
	s_cselect_b32 s84, s42, s48
	s_add_u32 s46, s46, 0x40080
	s_addc_u32 s47, s47, 0
	s_add_u32 s85, s48, 0x100
	s_addc_u32 s86, s49, 0
	s_mov_b32 s87, -2
	ds_read_b128 v[104:107], v200
	ds_read_b128 v[108:111], v200 offset:1024
	ds_read_b128 v[124:127], v200 offset:2048
	ds_read_b128 v[128:131], v200 offset:3072
	ds_read_b128 v[144:147], v201
	ds_read_b128 v[148:151], v201 offset:1024
	ds_read_b128 v[152:155], v201 offset:2048
	ds_read_b128 v[156:159], v201 offset:3072
	s_add_u32 s48, s46, 0xfffc0080
	s_addc_u32 s49, s47, -1
	s_cmp_eq_u32 s87, 12
	s_cselect_b32 s51, s39, s49
	s_cselect_b32 s50, s45, s48
	s_cselect_b32 s49, s37, s86
	s_cselect_b32 s48, s84, s85
	s_add_i32 m0, s52, 0xc000
	ds_read_b128 v[160:163], v202
	ds_read_b128 v[164:167], v202 offset:1024
	ds_read_b128 v[168:171], v202 offset:2048
	ds_read_b128 v[172:175], v202 offset:3072
	ds_read_b128 v[176:179], v202 offset:4096
	ds_read_b128 v[180:183], v202 offset:5120
	ds_read_b128 v[206:209], v202 offset:6144
	ds_read_b128 v[210:213], v202 offset:7168
	global_load_lds_dwordx4 v188, s[46:47]
	s_add_i32 m0, s52, 0xe000
	s_nop 0
	global_load_lds_dwordx4 v190, s[46:47]
	s_waitcnt vmcnt(8)
	s_waitcnt lgkmcnt(0)
	s_barrier
	v_mfma_f32_16x16x32_bf16 v[140:143], v[104:107], v[160:163], 0
	v_mfma_f32_16x16x32_bf16 v[136:139], v[124:127], v[160:163], 0
	v_mfma_f32_16x16x32_bf16 v[116:119], v[104:107], v[168:171], 0
	v_mfma_f32_16x16x32_bf16 v[112:115], v[124:127], v[168:171], 0
	v_mfma_f32_16x16x32_bf16 v[92:95], v[104:107], v[176:179], 0
	v_mfma_f32_16x16x32_bf16 v[88:91], v[124:127], v[176:179], 0
	v_mfma_f32_16x16x32_bf16 v[76:79], v[104:107], v[206:209], 0
	v_mfma_f32_16x16x32_bf16 v[72:75], v[124:127], v[206:209], 0
	v_mfma_f32_16x16x32_bf16 v[140:143], v[108:111], v[164:167], v[140:143]
	v_mfma_f32_16x16x32_bf16 v[136:139], v[128:131], v[164:167], v[136:139]
	v_mfma_f32_16x16x32_bf16 v[116:119], v[108:111], v[172:175], v[116:119]
	v_mfma_f32_16x16x32_bf16 v[112:115], v[128:131], v[172:175], v[112:115]
	v_mfma_f32_16x16x32_bf16 v[92:95], v[108:111], v[180:183], v[92:95]
	v_mfma_f32_16x16x32_bf16 v[88:91], v[128:131], v[180:183], v[88:91]
	v_mfma_f32_16x16x32_bf16 v[76:79], v[108:111], v[210:213], v[76:79]
	v_mfma_f32_16x16x32_bf16 v[72:75], v[128:131], v[210:213], v[72:75]
	v_mfma_f32_16x16x32_bf16 v[132:135], v[144:147], v[160:163], 0
	v_mfma_f32_16x16x32_bf16 v[120:123], v[152:155], v[160:163], 0
	v_mfma_f32_16x16x32_bf16 v[100:103], v[144:147], v[168:171], 0
	v_mfma_f32_16x16x32_bf16 v[96:99], v[152:155], v[168:171], 0
	v_mfma_f32_16x16x32_bf16 v[84:87], v[144:147], v[176:179], 0
	v_mfma_f32_16x16x32_bf16 v[80:83], v[152:155], v[176:179], 0
	v_mfma_f32_16x16x32_bf16 v[68:71], v[144:147], v[206:209], 0
	v_mfma_f32_16x16x32_bf16 v[64:67], v[152:155], v[206:209], 0
	v_mfma_f32_16x16x32_bf16 v[132:135], v[148:151], v[164:167], v[132:135]
	v_mfma_f32_16x16x32_bf16 v[120:123], v[156:159], v[164:167], v[120:123]
	v_mfma_f32_16x16x32_bf16 v[100:103], v[148:151], v[172:175], v[100:103]
	v_mfma_f32_16x16x32_bf16 v[96:99], v[156:159], v[172:175], v[96:99]
	v_mfma_f32_16x16x32_bf16 v[84:87], v[148:151], v[180:183], v[84:87]
	v_mfma_f32_16x16x32_bf16 v[80:83], v[156:159], v[180:183], v[80:83]
	v_mfma_f32_16x16x32_bf16 v[68:71], v[148:151], v[210:213], v[68:71]
	v_mfma_f32_16x16x32_bf16 v[64:67], v[156:159], v[210:213], v[64:67]
	s_barrier
	s_add_i32 s88, s69, s13
	s_add_u32 s98, s48, 0x80
	s_addc_u32 s99, s49, 0
	s_mov_b32 m0, s88
	ds_read_b128 v[160:163], v202 offset:16384
	ds_read_b128 v[164:167], v202 offset:17408
	ds_read_b128 v[168:171], v202 offset:18432
	ds_read_b128 v[172:175], v202 offset:19456
	ds_read_b128 v[176:179], v202 offset:20480
	ds_read_b128 v[180:183], v202 offset:21504
	ds_read_b128 v[206:209], v202 offset:22528
	ds_read_b128 v[210:213], v202 offset:23552
	global_load_lds_dwordx4 v184, s[48:49]
	s_add_i32 m0, s88, 0x2000
	s_add_u32 s88, s48, 0x40000
	s_addc_u32 s89, s49, 0
	s_add_i32 s90, s70, s13
	global_load_lds_dwordx4 v186, s[48:49]
	s_mov_b32 m0, s90
	s_add_u32 s100, s50, 0x80
	s_addc_u32 s101, s51, 0
	global_load_lds_dwordx4 v184, s[88:89]
	s_add_i32 m0, s90, 0x2000
	s_nop 0
	global_load_lds_dwordx4 v186, s[88:89]
	s_mov_b32 m0, s52
	s_nop 0
	global_load_lds_dwordx4 v184, s[50:51]
	s_mov_b32 m0, s53
	s_nop 0
	global_load_lds_dwordx4 v186, s[50:51]
	s_waitcnt vmcnt(8)
	s_waitcnt lgkmcnt(0)
	s_barrier
	v_mfma_f32_16x16x32_bf16 v[60:63], v[104:107], v[160:163], 0
	v_mfma_f32_16x16x32_bf16 v[56:59], v[124:127], v[160:163], 0
	v_mfma_f32_16x16x32_bf16 v[44:47], v[104:107], v[168:171], 0
	v_mfma_f32_16x16x32_bf16 v[40:43], v[124:127], v[168:171], 0
	v_mfma_f32_16x16x32_bf16 v[28:31], v[104:107], v[176:179], 0
	v_mfma_f32_16x16x32_bf16 v[24:27], v[124:127], v[176:179], 0
	v_mfma_f32_16x16x32_bf16 v[12:15], v[104:107], v[206:209], 0
	v_mfma_f32_16x16x32_bf16 v[8:11], v[124:127], v[206:209], 0
	v_mfma_f32_16x16x32_bf16 v[60:63], v[108:111], v[164:167], v[60:63]
	v_mfma_f32_16x16x32_bf16 v[56:59], v[128:131], v[164:167], v[56:59]
	v_mfma_f32_16x16x32_bf16 v[44:47], v[108:111], v[172:175], v[44:47]
	v_mfma_f32_16x16x32_bf16 v[40:43], v[128:131], v[172:175], v[40:43]
	v_mfma_f32_16x16x32_bf16 v[28:31], v[108:111], v[180:183], v[28:31]
	v_mfma_f32_16x16x32_bf16 v[24:27], v[128:131], v[180:183], v[24:27]
	v_mfma_f32_16x16x32_bf16 v[12:15], v[108:111], v[210:213], v[12:15]
	v_mfma_f32_16x16x32_bf16 v[8:11], v[128:131], v[210:213], v[8:11]
	v_mfma_f32_16x16x32_bf16 v[52:55], v[144:147], v[160:163], 0
	v_mfma_f32_16x16x32_bf16 v[48:51], v[152:155], v[160:163], 0
	v_mfma_f32_16x16x32_bf16 v[36:39], v[144:147], v[168:171], 0
	v_mfma_f32_16x16x32_bf16 v[32:35], v[152:155], v[168:171], 0
	v_mfma_f32_16x16x32_bf16 v[20:23], v[144:147], v[176:179], 0
	v_mfma_f32_16x16x32_bf16 v[16:19], v[152:155], v[176:179], 0
	v_mfma_f32_16x16x32_bf16 v[4:7], v[144:147], v[206:209], 0
	v_mfma_f32_16x16x32_bf16 v[0:3], v[152:155], v[206:209], 0
	v_mfma_f32_16x16x32_bf16 v[52:55], v[148:151], v[164:167], v[52:55]
	v_mfma_f32_16x16x32_bf16 v[48:51], v[156:159], v[164:167], v[48:51]
	v_mfma_f32_16x16x32_bf16 v[36:39], v[148:151], v[172:175], v[36:39]
	v_mfma_f32_16x16x32_bf16 v[32:35], v[156:159], v[172:175], v[32:35]
	v_mfma_f32_16x16x32_bf16 v[20:23], v[148:151], v[180:183], v[20:23]
	v_mfma_f32_16x16x32_bf16 v[16:19], v[156:159], v[180:183], v[16:19]
	v_mfma_f32_16x16x32_bf16 v[4:7], v[148:151], v[210:213], v[4:7]
	v_mfma_f32_16x16x32_bf16 v[0:3], v[156:159], v[210:213], v[0:3]
	s_barrier
	s_add_i32 s88, 0, 0x18000
	s_add_i32 s89, 0, 0x1c000
	v_add_u32_e32 v128, s88, v199
	v_add_u32_e32 v156, s89, v199
	ds_read_b128 v[104:107], v128
	ds_read_b128 v[108:111], v128 offset:1024
	ds_read_b128 v[124:127], v128 offset:2048
	ds_read_b128 v[128:131], v128 offset:3072
	ds_read_b128 v[144:147], v156
	ds_read_b128 v[148:151], v156 offset:1024
	ds_read_b128 v[152:155], v156 offset:2048
	ds_read_b128 v[156:159], v156 offset:3072
	s_add_u32 s50, s50, 0x40000
	s_addc_u32 s51, s51, 0
	s_mov_b32 m0, s54
	ds_read_b128 v[160:163], v202 offset:32768
	ds_read_b128 v[164:167], v202 offset:33792
	ds_read_b128 v[168:171], v202 offset:34816
	ds_read_b128 v[172:175], v202 offset:35840
	ds_read_b128 v[176:179], v202 offset:36864
	ds_read_b128 v[180:183], v202 offset:37888
	ds_read_b128 v[206:209], v202 offset:38912
	ds_read_b128 v[210:213], v202 offset:39936
	global_load_lds_dwordx4 v184, s[50:51]
	s_mov_b32 m0, s55
	s_nop 0
	global_load_lds_dwordx4 v186, s[50:51]
	s_waitcnt vmcnt(8)
	s_waitcnt lgkmcnt(0)
	s_barrier
	v_mfma_f32_16x16x32_bf16 v[140:143], v[104:107], v[160:163], v[140:143]
	v_mfma_f32_16x16x32_bf16 v[136:139], v[124:127], v[160:163], v[136:139]
	v_mfma_f32_16x16x32_bf16 v[116:119], v[104:107], v[168:171], v[116:119]
	v_mfma_f32_16x16x32_bf16 v[112:115], v[124:127], v[168:171], v[112:115]
	v_mfma_f32_16x16x32_bf16 v[92:95], v[104:107], v[176:179], v[92:95]
	v_mfma_f32_16x16x32_bf16 v[88:91], v[124:127], v[176:179], v[88:91]
	v_mfma_f32_16x16x32_bf16 v[76:79], v[104:107], v[206:209], v[76:79]
	v_mfma_f32_16x16x32_bf16 v[72:75], v[124:127], v[206:209], v[72:75]
	v_mfma_f32_16x16x32_bf16 v[140:143], v[108:111], v[164:167], v[140:143]
	v_mfma_f32_16x16x32_bf16 v[136:139], v[128:131], v[164:167], v[136:139]
	v_mfma_f32_16x16x32_bf16 v[116:119], v[108:111], v[172:175], v[116:119]
	v_mfma_f32_16x16x32_bf16 v[112:115], v[128:131], v[172:175], v[112:115]
	v_mfma_f32_16x16x32_bf16 v[92:95], v[108:111], v[180:183], v[92:95]
	v_mfma_f32_16x16x32_bf16 v[88:91], v[128:131], v[180:183], v[88:91]
	v_mfma_f32_16x16x32_bf16 v[76:79], v[108:111], v[210:213], v[76:79]
	v_mfma_f32_16x16x32_bf16 v[72:75], v[128:131], v[210:213], v[72:75]
	v_mfma_f32_16x16x32_bf16 v[132:135], v[144:147], v[160:163], v[132:135]
	v_mfma_f32_16x16x32_bf16 v[120:123], v[152:155], v[160:163], v[120:123]
	v_mfma_f32_16x16x32_bf16 v[100:103], v[144:147], v[168:171], v[100:103]
	v_mfma_f32_16x16x32_bf16 v[96:99], v[152:155], v[168:171], v[96:99]
	v_mfma_f32_16x16x32_bf16 v[84:87], v[144:147], v[176:179], v[84:87]
	v_mfma_f32_16x16x32_bf16 v[80:83], v[152:155], v[176:179], v[80:83]
	v_mfma_f32_16x16x32_bf16 v[68:71], v[144:147], v[206:209], v[68:71]
	v_mfma_f32_16x16x32_bf16 v[64:67], v[152:155], v[206:209], v[64:67]
	v_mfma_f32_16x16x32_bf16 v[132:135], v[148:151], v[164:167], v[132:135]
	v_mfma_f32_16x16x32_bf16 v[120:123], v[156:159], v[164:167], v[120:123]
	v_mfma_f32_16x16x32_bf16 v[100:103], v[148:151], v[172:175], v[100:103]
	v_mfma_f32_16x16x32_bf16 v[96:99], v[156:159], v[172:175], v[96:99]
	v_mfma_f32_16x16x32_bf16 v[84:87], v[148:151], v[180:183], v[84:87]
	v_mfma_f32_16x16x32_bf16 v[80:83], v[156:159], v[180:183], v[80:83]
	v_mfma_f32_16x16x32_bf16 v[68:71], v[148:151], v[210:213], v[68:71]
	v_mfma_f32_16x16x32_bf16 v[64:67], v[156:159], v[210:213], v[64:67]
	s_barrier
	s_add_i32 s50, s88, s13
	s_mov_b32 m0, s50
	ds_read_b128 v[160:163], v202 offset:49152
	ds_read_b128 v[164:167], v202 offset:50176
	ds_read_b128 v[168:171], v202 offset:51200
	ds_read_b128 v[172:175], v202 offset:52224
	ds_read_b128 v[176:179], v202 offset:53248
	ds_read_b128 v[180:183], v202 offset:54272
	ds_read_b128 v[206:209], v202 offset:55296
	ds_read_b128 v[210:213], v202 offset:56320
	global_load_lds_dwordx4 v184, s[98:99]
	s_add_i32 m0, s50, 0x2000
	s_add_u32 s48, s48, 0x40080
	s_addc_u32 s49, s49, 0
	s_add_i32 s50, s89, s13
	global_load_lds_dwordx4 v186, s[98:99]
	s_mov_b32 m0, s50
	s_nop 0
	global_load_lds_dwordx4 v184, s[48:49]
	s_add_i32 m0, s50, 0x2000
	s_nop 0
	global_load_lds_dwordx4 v186, s[48:49]
	s_mov_b32 m0, s61
	s_nop 0
	global_load_lds_dwordx4 v184, s[100:101]
	s_mov_b32 m0, s62
	s_nop 0
	global_load_lds_dwordx4 v186, s[100:101]
	s_waitcnt vmcnt(8)
	s_waitcnt lgkmcnt(0)
	s_barrier
	v_mfma_f32_16x16x32_bf16 v[60:63], v[104:107], v[160:163], v[60:63]
	v_mfma_f32_16x16x32_bf16 v[56:59], v[124:127], v[160:163], v[56:59]
	v_mfma_f32_16x16x32_bf16 v[44:47], v[104:107], v[168:171], v[44:47]
	v_mfma_f32_16x16x32_bf16 v[40:43], v[124:127], v[168:171], v[40:43]
	v_mfma_f32_16x16x32_bf16 v[28:31], v[104:107], v[176:179], v[28:31]
	v_mfma_f32_16x16x32_bf16 v[24:27], v[124:127], v[176:179], v[24:27]
	v_mfma_f32_16x16x32_bf16 v[12:15], v[104:107], v[206:209], v[12:15]
	v_mfma_f32_16x16x32_bf16 v[8:11], v[124:127], v[206:209], v[8:11]
	v_mfma_f32_16x16x32_bf16 v[60:63], v[108:111], v[164:167], v[60:63]
	v_mfma_f32_16x16x32_bf16 v[56:59], v[128:131], v[164:167], v[56:59]
	v_mfma_f32_16x16x32_bf16 v[44:47], v[108:111], v[172:175], v[44:47]
	v_mfma_f32_16x16x32_bf16 v[40:43], v[128:131], v[172:175], v[40:43]
	v_mfma_f32_16x16x32_bf16 v[28:31], v[108:111], v[180:183], v[28:31]
	v_mfma_f32_16x16x32_bf16 v[24:27], v[128:131], v[180:183], v[24:27]
	v_mfma_f32_16x16x32_bf16 v[12:15], v[108:111], v[210:213], v[12:15]
	v_mfma_f32_16x16x32_bf16 v[8:11], v[128:131], v[210:213], v[8:11]
	v_mfma_f32_16x16x32_bf16 v[52:55], v[144:147], v[160:163], v[52:55]
	v_mfma_f32_16x16x32_bf16 v[48:51], v[152:155], v[160:163], v[48:51]
	v_mfma_f32_16x16x32_bf16 v[36:39], v[144:147], v[168:171], v[36:39]
	v_mfma_f32_16x16x32_bf16 v[32:35], v[152:155], v[168:171], v[32:35]
	v_mfma_f32_16x16x32_bf16 v[20:23], v[144:147], v[176:179], v[20:23]
	v_mfma_f32_16x16x32_bf16 v[16:19], v[152:155], v[176:179], v[16:19]
	v_mfma_f32_16x16x32_bf16 v[4:7], v[144:147], v[206:209], v[4:7]
	v_mfma_f32_16x16x32_bf16 v[0:3], v[152:155], v[206:209], v[0:3]
	v_mfma_f32_16x16x32_bf16 v[52:55], v[148:151], v[164:167], v[52:55]
	v_mfma_f32_16x16x32_bf16 v[48:51], v[156:159], v[164:167], v[48:51]
	v_mfma_f32_16x16x32_bf16 v[36:39], v[148:151], v[172:175], v[36:39]
	v_mfma_f32_16x16x32_bf16 v[32:35], v[156:159], v[172:175], v[32:35]
	v_mfma_f32_16x16x32_bf16 v[20:23], v[148:151], v[180:183], v[20:23]
	v_mfma_f32_16x16x32_bf16 v[16:19], v[156:159], v[180:183], v[16:19]
	v_mfma_f32_16x16x32_bf16 v[4:7], v[148:151], v[210:213], v[4:7]
	v_mfma_f32_16x16x32_bf16 v[0:3], v[156:159], v[210:213], v[0:3]
	s_barrier
	s_add_i32 s87, s87, 2
	s_add_u32 s46, s46, 0x100
	s_addc_u32 s47, s47, 0
	s_add_u32 s85, s85, 0x100
	s_addc_u32 s86, s86, 0
	s_cmp_gt_u32 s87, 13
	s_cbranch_scc1 .Lkx_504
.LBB0_504:
	ds_read_b128 v[104:107], v200
	ds_read_b128 v[108:111], v200 offset:1024
	ds_read_b128 v[124:127], v200 offset:2048
	ds_read_b128 v[128:131], v200 offset:3072
	ds_read_b128 v[144:147], v201
	ds_read_b128 v[148:151], v201 offset:1024
	ds_read_b128 v[152:155], v201 offset:2048
	ds_read_b128 v[156:159], v201 offset:3072
	s_add_u32 s48, s46, 0xfffc0080
	s_addc_u32 s49, s47, -1
	s_cmp_eq_u32 s87, 12
	s_cselect_b32 s51, s39, s49
	s_cselect_b32 s50, s45, s48
	s_cselect_b32 s49, s37, s86
	s_cselect_b32 s48, s84, s85
	s_add_i32 m0, s52, 0xc000
	ds_read_b128 v[160:163], v202
	ds_read_b128 v[164:167], v202 offset:1024
	ds_read_b128 v[168:171], v202 offset:2048
	ds_read_b128 v[172:175], v202 offset:3072
	ds_read_b128 v[176:179], v202 offset:4096
	ds_read_b128 v[180:183], v202 offset:5120
	ds_read_b128 v[206:209], v202 offset:6144
	ds_read_b128 v[210:213], v202 offset:7168
	global_load_lds_dwordx4 v188, s[46:47]
	s_add_i32 m0, s52, 0xe000
	s_nop 0
	global_load_lds_dwordx4 v190, s[46:47]
	s_waitcnt vmcnt(8)
	s_waitcnt lgkmcnt(0)
	s_barrier
	v_mfma_f32_16x16x32_bf16 v[140:143], v[104:107], v[160:163], v[140:143]
	v_mfma_f32_16x16x32_bf16 v[136:139], v[124:127], v[160:163], v[136:139]
	v_mfma_f32_16x16x32_bf16 v[116:119], v[104:107], v[168:171], v[116:119]
	v_mfma_f32_16x16x32_bf16 v[112:115], v[124:127], v[168:171], v[112:115]
	v_mfma_f32_16x16x32_bf16 v[92:95], v[104:107], v[176:179], v[92:95]
	v_mfma_f32_16x16x32_bf16 v[88:91], v[124:127], v[176:179], v[88:91]
	v_mfma_f32_16x16x32_bf16 v[76:79], v[104:107], v[206:209], v[76:79]
	v_mfma_f32_16x16x32_bf16 v[72:75], v[124:127], v[206:209], v[72:75]
	v_mfma_f32_16x16x32_bf16 v[140:143], v[108:111], v[164:167], v[140:143]
	v_mfma_f32_16x16x32_bf16 v[136:139], v[128:131], v[164:167], v[136:139]
	v_mfma_f32_16x16x32_bf16 v[116:119], v[108:111], v[172:175], v[116:119]
	v_mfma_f32_16x16x32_bf16 v[112:115], v[128:131], v[172:175], v[112:115]
	v_mfma_f32_16x16x32_bf16 v[92:95], v[108:111], v[180:183], v[92:95]
	v_mfma_f32_16x16x32_bf16 v[88:91], v[128:131], v[180:183], v[88:91]
	v_mfma_f32_16x16x32_bf16 v[76:79], v[108:111], v[210:213], v[76:79]
	v_mfma_f32_16x16x32_bf16 v[72:75], v[128:131], v[210:213], v[72:75]
	v_mfma_f32_16x16x32_bf16 v[132:135], v[144:147], v[160:163], v[132:135]
	v_mfma_f32_16x16x32_bf16 v[120:123], v[152:155], v[160:163], v[120:123]
	v_mfma_f32_16x16x32_bf16 v[100:103], v[144:147], v[168:171], v[100:103]
	v_mfma_f32_16x16x32_bf16 v[96:99], v[152:155], v[168:171], v[96:99]
	v_mfma_f32_16x16x32_bf16 v[84:87], v[144:147], v[176:179], v[84:87]
	v_mfma_f32_16x16x32_bf16 v[80:83], v[152:155], v[176:179], v[80:83]
	v_mfma_f32_16x16x32_bf16 v[68:71], v[144:147], v[206:209], v[68:71]
	v_mfma_f32_16x16x32_bf16 v[64:67], v[152:155], v[206:209], v[64:67]
	v_mfma_f32_16x16x32_bf16 v[132:135], v[148:151], v[164:167], v[132:135]
	v_mfma_f32_16x16x32_bf16 v[120:123], v[156:159], v[164:167], v[120:123]
	v_mfma_f32_16x16x32_bf16 v[100:103], v[148:151], v[172:175], v[100:103]
	v_mfma_f32_16x16x32_bf16 v[96:99], v[156:159], v[172:175], v[96:99]
	v_mfma_f32_16x16x32_bf16 v[84:87], v[148:151], v[180:183], v[84:87]
	v_mfma_f32_16x16x32_bf16 v[80:83], v[156:159], v[180:183], v[80:83]
	v_mfma_f32_16x16x32_bf16 v[68:71], v[148:151], v[210:213], v[68:71]
	v_mfma_f32_16x16x32_bf16 v[64:67], v[156:159], v[210:213], v[64:67]
	s_barrier
	s_add_i32 s88, s69, s13
	s_add_u32 s98, s48, 0x80
	s_addc_u32 s99, s49, 0
	s_mov_b32 m0, s88
	ds_read_b128 v[160:163], v202 offset:16384
	ds_read_b128 v[164:167], v202 offset:17408
	ds_read_b128 v[168:171], v202 offset:18432
	ds_read_b128 v[172:175], v202 offset:19456
	ds_read_b128 v[176:179], v202 offset:20480
	ds_read_b128 v[180:183], v202 offset:21504
	ds_read_b128 v[206:209], v202 offset:22528
	ds_read_b128 v[210:213], v202 offset:23552
	global_load_lds_dwordx4 v184, s[48:49]
	s_add_i32 m0, s88, 0x2000
	s_add_u32 s88, s48, 0x40000
	s_addc_u32 s89, s49, 0
	s_add_i32 s90, s70, s13
	global_load_lds_dwordx4 v186, s[48:49]
	s_mov_b32 m0, s90
	s_add_u32 s100, s50, 0x80
	s_addc_u32 s101, s51, 0
	global_load_lds_dwordx4 v184, s[88:89]
	s_add_i32 m0, s90, 0x2000
	s_nop 0
	global_load_lds_dwordx4 v186, s[88:89]
	s_mov_b32 m0, s52
	s_nop 0
	global_load_lds_dwordx4 v184, s[50:51]
	s_mov_b32 m0, s53
	s_nop 0
	global_load_lds_dwordx4 v186, s[50:51]
	s_waitcnt vmcnt(8)
	s_waitcnt lgkmcnt(0)
	s_barrier
	v_mfma_f32_16x16x32_bf16 v[60:63], v[104:107], v[160:163], v[60:63]
	v_mfma_f32_16x16x32_bf16 v[56:59], v[124:127], v[160:163], v[56:59]
	v_mfma_f32_16x16x32_bf16 v[44:47], v[104:107], v[168:171], v[44:47]
	v_mfma_f32_16x16x32_bf16 v[40:43], v[124:127], v[168:171], v[40:43]
	v_mfma_f32_16x16x32_bf16 v[28:31], v[104:107], v[176:179], v[28:31]
	v_mfma_f32_16x16x32_bf16 v[24:27], v[124:127], v[176:179], v[24:27]
	v_mfma_f32_16x16x32_bf16 v[12:15], v[104:107], v[206:209], v[12:15]
	v_mfma_f32_16x16x32_bf16 v[8:11], v[124:127], v[206:209], v[8:11]
	v_mfma_f32_16x16x32_bf16 v[60:63], v[108:111], v[164:167], v[60:63]
	v_mfma_f32_16x16x32_bf16 v[56:59], v[128:131], v[164:167], v[56:59]
	v_mfma_f32_16x16x32_bf16 v[44:47], v[108:111], v[172:175], v[44:47]
	v_mfma_f32_16x16x32_bf16 v[40:43], v[128:131], v[172:175], v[40:43]
	v_mfma_f32_16x16x32_bf16 v[28:31], v[108:111], v[180:183], v[28:31]
	v_mfma_f32_16x16x32_bf16 v[24:27], v[128:131], v[180:183], v[24:27]
	v_mfma_f32_16x16x32_bf16 v[12:15], v[108:111], v[210:213], v[12:15]
	v_mfma_f32_16x16x32_bf16 v[8:11], v[128:131], v[210:213], v[8:11]
	v_mfma_f32_16x16x32_bf16 v[52:55], v[144:147], v[160:163], v[52:55]
	v_mfma_f32_16x16x32_bf16 v[48:51], v[152:155], v[160:163], v[48:51]
	v_mfma_f32_16x16x32_bf16 v[36:39], v[144:147], v[168:171], v[36:39]
	v_mfma_f32_16x16x32_bf16 v[32:35], v[152:155], v[168:171], v[32:35]
	v_mfma_f32_16x16x32_bf16 v[20:23], v[144:147], v[176:179], v[20:23]
	v_mfma_f32_16x16x32_bf16 v[16:19], v[152:155], v[176:179], v[16:19]
	v_mfma_f32_16x16x32_bf16 v[4:7], v[144:147], v[206:209], v[4:7]
	v_mfma_f32_16x16x32_bf16 v[0:3], v[152:155], v[206:209], v[0:3]
	v_mfma_f32_16x16x32_bf16 v[52:55], v[148:151], v[164:167], v[52:55]
	v_mfma_f32_16x16x32_bf16 v[48:51], v[156:159], v[164:167], v[48:51]
	v_mfma_f32_16x16x32_bf16 v[36:39], v[148:151], v[172:175], v[36:39]
	v_mfma_f32_16x16x32_bf16 v[32:35], v[156:159], v[172:175], v[32:35]
	v_mfma_f32_16x16x32_bf16 v[20:23], v[148:151], v[180:183], v[20:23]
	v_mfma_f32_16x16x32_bf16 v[16:19], v[156:159], v[180:183], v[16:19]
	v_mfma_f32_16x16x32_bf16 v[4:7], v[148:151], v[210:213], v[4:7]
	v_mfma_f32_16x16x32_bf16 v[0:3], v[156:159], v[210:213], v[0:3]
	s_barrier
	s_add_i32 s88, 0, 0x18000
	s_add_i32 s89, 0, 0x1c000
	v_add_u32_e32 v128, s88, v199
	v_add_u32_e32 v156, s89, v199
	ds_read_b128 v[104:107], v128
	ds_read_b128 v[108:111], v128 offset:1024
	ds_read_b128 v[124:127], v128 offset:2048
	ds_read_b128 v[128:131], v128 offset:3072
	ds_read_b128 v[144:147], v156
	ds_read_b128 v[148:151], v156 offset:1024
	ds_read_b128 v[152:155], v156 offset:2048
	ds_read_b128 v[156:159], v156 offset:3072
	s_add_u32 s50, s50, 0x40000
	s_addc_u32 s51, s51, 0
	s_mov_b32 m0, s54
	ds_read_b128 v[160:163], v202 offset:32768
	ds_read_b128 v[164:167], v202 offset:33792
	ds_read_b128 v[168:171], v202 offset:34816
	ds_read_b128 v[172:175], v202 offset:35840
	ds_read_b128 v[176:179], v202 offset:36864
	ds_read_b128 v[180:183], v202 offset:37888
	ds_read_b128 v[206:209], v202 offset:38912
	ds_read_b128 v[210:213], v202 offset:39936
	global_load_lds_dwordx4 v184, s[50:51]
	s_mov_b32 m0, s55
	s_nop 0
	global_load_lds_dwordx4 v186, s[50:51]
	s_waitcnt vmcnt(8)
	s_waitcnt lgkmcnt(0)
	s_barrier
	v_mfma_f32_16x16x32_bf16 v[140:143], v[104:107], v[160:163], v[140:143]
	v_mfma_f32_16x16x32_bf16 v[136:139], v[124:127], v[160:163], v[136:139]
	v_mfma_f32_16x16x32_bf16 v[116:119], v[104:107], v[168:171], v[116:119]
	v_mfma_f32_16x16x32_bf16 v[112:115], v[124:127], v[168:171], v[112:115]
	v_mfma_f32_16x16x32_bf16 v[92:95], v[104:107], v[176:179], v[92:95]
	v_mfma_f32_16x16x32_bf16 v[88:91], v[124:127], v[176:179], v[88:91]
	v_mfma_f32_16x16x32_bf16 v[76:79], v[104:107], v[206:209], v[76:79]
	v_mfma_f32_16x16x32_bf16 v[72:75], v[124:127], v[206:209], v[72:75]
	v_mfma_f32_16x16x32_bf16 v[140:143], v[108:111], v[164:167], v[140:143]
	v_mfma_f32_16x16x32_bf16 v[136:139], v[128:131], v[164:167], v[136:139]
	v_mfma_f32_16x16x32_bf16 v[116:119], v[108:111], v[172:175], v[116:119]
	v_mfma_f32_16x16x32_bf16 v[112:115], v[128:131], v[172:175], v[112:115]
	v_mfma_f32_16x16x32_bf16 v[92:95], v[108:111], v[180:183], v[92:95]
	v_mfma_f32_16x16x32_bf16 v[88:91], v[128:131], v[180:183], v[88:91]
	v_mfma_f32_16x16x32_bf16 v[76:79], v[108:111], v[210:213], v[76:79]
	v_mfma_f32_16x16x32_bf16 v[72:75], v[128:131], v[210:213], v[72:75]
	v_mfma_f32_16x16x32_bf16 v[132:135], v[144:147], v[160:163], v[132:135]
	v_mfma_f32_16x16x32_bf16 v[120:123], v[152:155], v[160:163], v[120:123]
	v_mfma_f32_16x16x32_bf16 v[100:103], v[144:147], v[168:171], v[100:103]
	v_mfma_f32_16x16x32_bf16 v[96:99], v[152:155], v[168:171], v[96:99]
	v_mfma_f32_16x16x32_bf16 v[84:87], v[144:147], v[176:179], v[84:87]
	v_mfma_f32_16x16x32_bf16 v[80:83], v[152:155], v[176:179], v[80:83]
	v_mfma_f32_16x16x32_bf16 v[68:71], v[144:147], v[206:209], v[68:71]
	v_mfma_f32_16x16x32_bf16 v[64:67], v[152:155], v[206:209], v[64:67]
	v_mfma_f32_16x16x32_bf16 v[132:135], v[148:151], v[164:167], v[132:135]
	v_mfma_f32_16x16x32_bf16 v[120:123], v[156:159], v[164:167], v[120:123]
	v_mfma_f32_16x16x32_bf16 v[100:103], v[148:151], v[172:175], v[100:103]
	v_mfma_f32_16x16x32_bf16 v[96:99], v[156:159], v[172:175], v[96:99]
	v_mfma_f32_16x16x32_bf16 v[84:87], v[148:151], v[180:183], v[84:87]
	v_mfma_f32_16x16x32_bf16 v[80:83], v[156:159], v[180:183], v[80:83]
	v_mfma_f32_16x16x32_bf16 v[68:71], v[148:151], v[210:213], v[68:71]
	v_mfma_f32_16x16x32_bf16 v[64:67], v[156:159], v[210:213], v[64:67]
	s_barrier
	s_add_i32 s50, s88, s13
	s_mov_b32 m0, s50
	ds_read_b128 v[160:163], v202 offset:49152
	ds_read_b128 v[164:167], v202 offset:50176
	ds_read_b128 v[168:171], v202 offset:51200
	ds_read_b128 v[172:175], v202 offset:52224
	ds_read_b128 v[176:179], v202 offset:53248
	ds_read_b128 v[180:183], v202 offset:54272
	ds_read_b128 v[206:209], v202 offset:55296
	ds_read_b128 v[210:213], v202 offset:56320
	global_load_lds_dwordx4 v184, s[98:99]
	s_add_i32 m0, s50, 0x2000
	s_add_u32 s48, s48, 0x40080
	s_addc_u32 s49, s49, 0
	s_add_i32 s50, s89, s13
	global_load_lds_dwordx4 v186, s[98:99]
	s_mov_b32 m0, s50
	s_nop 0
	global_load_lds_dwordx4 v184, s[48:49]
	s_add_i32 m0, s50, 0x2000
	s_nop 0
	global_load_lds_dwordx4 v186, s[48:49]
	s_mov_b32 m0, s61
	s_nop 0
	global_load_lds_dwordx4 v184, s[100:101]
	s_mov_b32 m0, s62
	s_nop 0
	global_load_lds_dwordx4 v186, s[100:101]
	s_waitcnt vmcnt(8)
	s_waitcnt lgkmcnt(0)
	s_barrier
	v_mfma_f32_16x16x32_bf16 v[60:63], v[104:107], v[160:163], v[60:63]
	v_mfma_f32_16x16x32_bf16 v[56:59], v[124:127], v[160:163], v[56:59]
	v_mfma_f32_16x16x32_bf16 v[44:47], v[104:107], v[168:171], v[44:47]
	v_mfma_f32_16x16x32_bf16 v[40:43], v[124:127], v[168:171], v[40:43]
	v_mfma_f32_16x16x32_bf16 v[28:31], v[104:107], v[176:179], v[28:31]
	v_mfma_f32_16x16x32_bf16 v[24:27], v[124:127], v[176:179], v[24:27]
	v_mfma_f32_16x16x32_bf16 v[12:15], v[104:107], v[206:209], v[12:15]
	v_mfma_f32_16x16x32_bf16 v[8:11], v[124:127], v[206:209], v[8:11]
	v_mfma_f32_16x16x32_bf16 v[60:63], v[108:111], v[164:167], v[60:63]
	v_mfma_f32_16x16x32_bf16 v[56:59], v[128:131], v[164:167], v[56:59]
	v_mfma_f32_16x16x32_bf16 v[44:47], v[108:111], v[172:175], v[44:47]
	v_mfma_f32_16x16x32_bf16 v[40:43], v[128:131], v[172:175], v[40:43]
	v_mfma_f32_16x16x32_bf16 v[28:31], v[108:111], v[180:183], v[28:31]
	v_mfma_f32_16x16x32_bf16 v[24:27], v[128:131], v[180:183], v[24:27]
	v_mfma_f32_16x16x32_bf16 v[12:15], v[108:111], v[210:213], v[12:15]
	v_mfma_f32_16x16x32_bf16 v[8:11], v[128:131], v[210:213], v[8:11]
	v_mfma_f32_16x16x32_bf16 v[52:55], v[144:147], v[160:163], v[52:55]
	v_mfma_f32_16x16x32_bf16 v[48:51], v[152:155], v[160:163], v[48:51]
	v_mfma_f32_16x16x32_bf16 v[36:39], v[144:147], v[168:171], v[36:39]
	v_mfma_f32_16x16x32_bf16 v[32:35], v[152:155], v[168:171], v[32:35]
	v_mfma_f32_16x16x32_bf16 v[20:23], v[144:147], v[176:179], v[20:23]
	v_mfma_f32_16x16x32_bf16 v[16:19], v[152:155], v[176:179], v[16:19]
	v_mfma_f32_16x16x32_bf16 v[4:7], v[144:147], v[206:209], v[4:7]
	v_mfma_f32_16x16x32_bf16 v[0:3], v[152:155], v[206:209], v[0:3]
	v_mfma_f32_16x16x32_bf16 v[52:55], v[148:151], v[164:167], v[52:55]
	v_mfma_f32_16x16x32_bf16 v[48:51], v[156:159], v[164:167], v[48:51]
	v_mfma_f32_16x16x32_bf16 v[36:39], v[148:151], v[172:175], v[36:39]
	v_mfma_f32_16x16x32_bf16 v[32:35], v[156:159], v[172:175], v[32:35]
	v_mfma_f32_16x16x32_bf16 v[20:23], v[148:151], v[180:183], v[20:23]
	v_mfma_f32_16x16x32_bf16 v[16:19], v[156:159], v[180:183], v[16:19]
	v_mfma_f32_16x16x32_bf16 v[4:7], v[148:151], v[210:213], v[4:7]
	v_mfma_f32_16x16x32_bf16 v[0:3], v[156:159], v[210:213], v[0:3]
	s_barrier
	s_add_i32 s87, s87, 2
	s_add_u32 s46, s46, 0x100
	s_addc_u32 s47, s47, 0
	s_add_u32 s85, s85, 0x100
	s_addc_u32 s86, s86, 0
	s_cmp_gt_u32 s87, 13
	s_cbranch_scc0 .LBB0_504

.LBB0_551:
	s_ashr_i32 s57, s56, 31
	s_lshl_b64 s[22:23], s[56:57], 19
	s_add_u32 s58, s3, s22
	s_addc_u32 s59, s81, s23
	s_and_b64 s[22:23], s[6:7], exec
	s_cselect_b32 s9, s59, s63
	s_cselect_b32 s11, s58, s62
	s_ashr_i32 s55, s54, 31
	s_lshl_b64 s[22:23], s[54:55], 19
	s_add_u32 s60, s82, s22
	s_addc_u32 s61, s83, s23
	s_and_b64 s[22:23], s[6:7], exec
	s_cselect_b32 s13, s61, s65
	s_cselect_b32 s16, s60, s64
	s_add_u32 s62, s62, 0x40080
	s_addc_u32 s63, s63, 0
	s_add_u32 s22, s64, 0x100
	s_waitcnt lgkmcnt(0)
	s_addc_u32 s23, s65, 0
	s_mov_b32 s55, -2
	ds_read_b128 v[128:131], v173
	ds_read_b128 v[132:135], v173 offset:1024
	ds_read_b128 v[136:139], v173 offset:2048
	ds_read_b128 v[140:143], v173 offset:3072
	ds_read_b128 v[160:163], v179
	ds_read_b128 v[174:177], v179 offset:1024
	ds_read_b128 v[194:197], v179 offset:2048
	ds_read_b128 v[198:201], v179 offset:3072
	s_add_u32 s57, s62, 0xfffc0080
	s_addc_u32 s64, s63, -1
	s_cmp_eq_u32 s55, 12
	s_cselect_b32 s67, s9, s64
	s_cselect_b32 s66, s11, s57
	s_cselect_b32 s65, s13, s23
	s_cselect_b32 s64, s16, s22
	s_add_i32 m0, s86, 0xc000
	ds_read_b128 v[202:205], v183
	ds_read_b128 v[206:209], v183 offset:1024
	ds_read_b128 v[210:213], v183 offset:2048
	ds_read_b128 v[214:217], v183 offset:3072
	ds_read_b128 v[218:221], v183 offset:4096
	ds_read_b128 v[222:225], v183 offset:5120
	ds_read_b128 v[226:229], v183 offset:6144
	ds_read_b128 v[230:233], v183 offset:7168
	global_load_lds_dwordx4 v152, s[62:63]
	s_add_i32 m0, s86, 0xe000
	s_nop 0
	global_load_lds_dwordx4 v154, s[62:63]
	s_waitcnt vmcnt(8)
	s_waitcnt lgkmcnt(0)
	s_barrier
	v_mfma_f32_16x16x32_bf16 v[124:127], v[128:131], v[202:205], 0
	v_mfma_f32_16x16x32_bf16 v[120:123], v[136:139], v[202:205], 0
	v_mfma_f32_16x16x32_bf16 v[108:111], v[128:131], v[210:213], 0
	v_mfma_f32_16x16x32_bf16 v[104:107], v[136:139], v[210:213], 0
	v_mfma_f32_16x16x32_bf16 v[92:95], v[128:131], v[218:221], 0
	v_mfma_f32_16x16x32_bf16 v[88:91], v[136:139], v[218:221], 0
	v_mfma_f32_16x16x32_bf16 v[76:79], v[128:131], v[226:229], 0
	v_mfma_f32_16x16x32_bf16 v[72:75], v[136:139], v[226:229], 0
	v_mfma_f32_16x16x32_bf16 v[124:127], v[132:135], v[206:209], v[124:127]
	v_mfma_f32_16x16x32_bf16 v[120:123], v[140:143], v[206:209], v[120:123]
	v_mfma_f32_16x16x32_bf16 v[108:111], v[132:135], v[214:217], v[108:111]
	v_mfma_f32_16x16x32_bf16 v[104:107], v[140:143], v[214:217], v[104:107]
	v_mfma_f32_16x16x32_bf16 v[92:95], v[132:135], v[222:225], v[92:95]
	v_mfma_f32_16x16x32_bf16 v[88:91], v[140:143], v[222:225], v[88:91]
	v_mfma_f32_16x16x32_bf16 v[76:79], v[132:135], v[230:233], v[76:79]
	v_mfma_f32_16x16x32_bf16 v[72:75], v[140:143], v[230:233], v[72:75]
	v_mfma_f32_16x16x32_bf16 v[116:119], v[160:163], v[202:205], 0
	v_mfma_f32_16x16x32_bf16 v[112:115], v[194:197], v[202:205], 0
	v_mfma_f32_16x16x32_bf16 v[100:103], v[160:163], v[210:213], 0
	v_mfma_f32_16x16x32_bf16 v[96:99], v[194:197], v[210:213], 0
	v_mfma_f32_16x16x32_bf16 v[84:87], v[160:163], v[218:221], 0
	v_mfma_f32_16x16x32_bf16 v[80:83], v[194:197], v[218:221], 0
	v_mfma_f32_16x16x32_bf16 v[68:71], v[160:163], v[226:229], 0
	v_mfma_f32_16x16x32_bf16 v[64:67], v[194:197], v[226:229], 0
	v_mfma_f32_16x16x32_bf16 v[116:119], v[174:177], v[206:209], v[116:119]
	v_mfma_f32_16x16x32_bf16 v[112:115], v[198:201], v[206:209], v[112:115]
	v_mfma_f32_16x16x32_bf16 v[100:103], v[174:177], v[214:217], v[100:103]
	v_mfma_f32_16x16x32_bf16 v[96:99], v[198:201], v[214:217], v[96:99]
	v_mfma_f32_16x16x32_bf16 v[84:87], v[174:177], v[222:225], v[84:87]
	v_mfma_f32_16x16x32_bf16 v[80:83], v[198:201], v[222:225], v[80:83]
	v_mfma_f32_16x16x32_bf16 v[68:71], v[174:177], v[230:233], v[68:71]
	v_mfma_f32_16x16x32_bf16 v[64:67], v[198:201], v[230:233], v[64:67]
	s_barrier
	s_add_i32 s57, s0, s85
	s_add_u32 s98, s64, 0x80
	s_addc_u32 s99, s65, 0
	s_mov_b32 m0, s57
	ds_read_b128 v[202:205], v183 offset:16384
	ds_read_b128 v[206:209], v183 offset:17408
	ds_read_b128 v[210:213], v183 offset:18432
	ds_read_b128 v[214:217], v183 offset:19456
	ds_read_b128 v[218:221], v183 offset:20480
	ds_read_b128 v[222:225], v183 offset:21504
	ds_read_b128 v[226:229], v183 offset:22528
	ds_read_b128 v[230:233], v183 offset:23552
	global_load_lds_dwordx4 v144, s[64:65]
	s_add_i32 m0, s57, 0x2000
	s_add_u32 s68, s64, 0x40000
	s_addc_u32 s69, s65, 0
	s_add_i32 s57, s1, s85
	global_load_lds_dwordx4 v146, s[64:65]
	s_mov_b32 m0, s57
	s_add_u32 s100, s66, 0x80
	s_addc_u32 s101, s67, 0
	global_load_lds_dwordx4 v144, s[68:69]
	s_add_i32 m0, s57, 0x2000
	s_nop 0
	global_load_lds_dwordx4 v146, s[68:69]
	s_mov_b32 m0, s86
	s_nop 0
	global_load_lds_dwordx4 v144, s[66:67]
	s_mov_b32 m0, s87
	s_nop 0
	global_load_lds_dwordx4 v146, s[66:67]
	s_waitcnt vmcnt(8)
	s_waitcnt lgkmcnt(0)
	s_barrier
	v_mfma_f32_16x16x32_bf16 v[60:63], v[128:131], v[202:205], 0
	v_mfma_f32_16x16x32_bf16 v[56:59], v[136:139], v[202:205], 0
	v_mfma_f32_16x16x32_bf16 v[44:47], v[128:131], v[210:213], 0
	v_mfma_f32_16x16x32_bf16 v[40:43], v[136:139], v[210:213], 0
	v_mfma_f32_16x16x32_bf16 v[28:31], v[128:131], v[218:221], 0
	v_mfma_f32_16x16x32_bf16 v[24:27], v[136:139], v[218:221], 0
	v_mfma_f32_16x16x32_bf16 v[12:15], v[128:131], v[226:229], 0
	v_mfma_f32_16x16x32_bf16 v[8:11], v[136:139], v[226:229], 0
	v_mfma_f32_16x16x32_bf16 v[60:63], v[132:135], v[206:209], v[60:63]
	v_mfma_f32_16x16x32_bf16 v[56:59], v[140:143], v[206:209], v[56:59]
	v_mfma_f32_16x16x32_bf16 v[44:47], v[132:135], v[214:217], v[44:47]
	v_mfma_f32_16x16x32_bf16 v[40:43], v[140:143], v[214:217], v[40:43]
	v_mfma_f32_16x16x32_bf16 v[28:31], v[132:135], v[222:225], v[28:31]
	v_mfma_f32_16x16x32_bf16 v[24:27], v[140:143], v[222:225], v[24:27]
	v_mfma_f32_16x16x32_bf16 v[12:15], v[132:135], v[230:233], v[12:15]
	v_mfma_f32_16x16x32_bf16 v[8:11], v[140:143], v[230:233], v[8:11]
	v_mfma_f32_16x16x32_bf16 v[52:55], v[160:163], v[202:205], 0
	v_mfma_f32_16x16x32_bf16 v[48:51], v[194:197], v[202:205], 0
	v_mfma_f32_16x16x32_bf16 v[36:39], v[160:163], v[210:213], 0
	v_mfma_f32_16x16x32_bf16 v[32:35], v[194:197], v[210:213], 0
	v_mfma_f32_16x16x32_bf16 v[20:23], v[160:163], v[218:221], 0
	v_mfma_f32_16x16x32_bf16 v[16:19], v[194:197], v[218:221], 0
	v_mfma_f32_16x16x32_bf16 v[4:7], v[160:163], v[226:229], 0
	v_mfma_f32_16x16x32_bf16 v[0:3], v[194:197], v[226:229], 0
	v_mfma_f32_16x16x32_bf16 v[52:55], v[174:177], v[206:209], v[52:55]
	v_mfma_f32_16x16x32_bf16 v[48:51], v[198:201], v[206:209], v[48:51]
	v_mfma_f32_16x16x32_bf16 v[36:39], v[174:177], v[214:217], v[36:39]
	v_mfma_f32_16x16x32_bf16 v[32:35], v[198:201], v[214:217], v[32:35]
	v_mfma_f32_16x16x32_bf16 v[20:23], v[174:177], v[222:225], v[20:23]
	v_mfma_f32_16x16x32_bf16 v[16:19], v[198:201], v[222:225], v[16:19]
	v_mfma_f32_16x16x32_bf16 v[4:7], v[174:177], v[230:233], v[4:7]
	v_mfma_f32_16x16x32_bf16 v[0:3], v[198:201], v[230:233], v[0:3]
	s_barrier
	s_add_i32 s57, 0, 0x18000
	s_add_i32 s68, 0, 0x1c000
	v_add_u32_e32 v140, s57, v169
	v_add_u32_e32 v148, s68, v169
	ds_read_b128 v[128:131], v140
	ds_read_b128 v[132:135], v140 offset:1024
	ds_read_b128 v[136:139], v140 offset:2048
	ds_read_b128 v[140:143], v140 offset:3072
	ds_read_b128 v[160:163], v148
	ds_read_b128 v[174:177], v148 offset:1024
	ds_read_b128 v[194:197], v148 offset:2048
	ds_read_b128 v[198:201], v148 offset:3072
	s_add_u32 s66, s66, 0x40000
	s_addc_u32 s67, s67, 0
	s_mov_b32 m0, s88
	ds_read_b128 v[202:205], v183 offset:32768
	ds_read_b128 v[206:209], v183 offset:33792
	ds_read_b128 v[210:213], v183 offset:34816
	ds_read_b128 v[214:217], v183 offset:35840
	ds_read_b128 v[218:221], v183 offset:36864
	ds_read_b128 v[222:225], v183 offset:37888
	ds_read_b128 v[226:229], v183 offset:38912
	ds_read_b128 v[230:233], v183 offset:39936
	global_load_lds_dwordx4 v144, s[66:67]
	s_mov_b32 m0, s89
	s_nop 0
	global_load_lds_dwordx4 v146, s[66:67]
	s_waitcnt vmcnt(8)
	s_waitcnt lgkmcnt(0)
	s_barrier
	v_mfma_f32_16x16x32_bf16 v[124:127], v[128:131], v[202:205], v[124:127]
	v_mfma_f32_16x16x32_bf16 v[120:123], v[136:139], v[202:205], v[120:123]
	v_mfma_f32_16x16x32_bf16 v[108:111], v[128:131], v[210:213], v[108:111]
	v_mfma_f32_16x16x32_bf16 v[104:107], v[136:139], v[210:213], v[104:107]
	v_mfma_f32_16x16x32_bf16 v[92:95], v[128:131], v[218:221], v[92:95]
	v_mfma_f32_16x16x32_bf16 v[88:91], v[136:139], v[218:221], v[88:91]
	v_mfma_f32_16x16x32_bf16 v[76:79], v[128:131], v[226:229], v[76:79]
	v_mfma_f32_16x16x32_bf16 v[72:75], v[136:139], v[226:229], v[72:75]
	v_mfma_f32_16x16x32_bf16 v[124:127], v[132:135], v[206:209], v[124:127]
	v_mfma_f32_16x16x32_bf16 v[120:123], v[140:143], v[206:209], v[120:123]
	v_mfma_f32_16x16x32_bf16 v[108:111], v[132:135], v[214:217], v[108:111]
	v_mfma_f32_16x16x32_bf16 v[104:107], v[140:143], v[214:217], v[104:107]
	v_mfma_f32_16x16x32_bf16 v[92:95], v[132:135], v[222:225], v[92:95]
	v_mfma_f32_16x16x32_bf16 v[88:91], v[140:143], v[222:225], v[88:91]
	v_mfma_f32_16x16x32_bf16 v[76:79], v[132:135], v[230:233], v[76:79]
	v_mfma_f32_16x16x32_bf16 v[72:75], v[140:143], v[230:233], v[72:75]
	v_mfma_f32_16x16x32_bf16 v[116:119], v[160:163], v[202:205], v[116:119]
	v_mfma_f32_16x16x32_bf16 v[112:115], v[194:197], v[202:205], v[112:115]
	v_mfma_f32_16x16x32_bf16 v[100:103], v[160:163], v[210:213], v[100:103]
	v_mfma_f32_16x16x32_bf16 v[96:99], v[194:197], v[210:213], v[96:99]
	v_mfma_f32_16x16x32_bf16 v[84:87], v[160:163], v[218:221], v[84:87]
	v_mfma_f32_16x16x32_bf16 v[80:83], v[194:197], v[218:221], v[80:83]
	v_mfma_f32_16x16x32_bf16 v[68:71], v[160:163], v[226:229], v[68:71]
	v_mfma_f32_16x16x32_bf16 v[64:67], v[194:197], v[226:229], v[64:67]
	v_mfma_f32_16x16x32_bf16 v[116:119], v[174:177], v[206:209], v[116:119]
	v_mfma_f32_16x16x32_bf16 v[112:115], v[198:201], v[206:209], v[112:115]
	v_mfma_f32_16x16x32_bf16 v[100:103], v[174:177], v[214:217], v[100:103]
	v_mfma_f32_16x16x32_bf16 v[96:99], v[198:201], v[214:217], v[96:99]
	v_mfma_f32_16x16x32_bf16 v[84:87], v[174:177], v[222:225], v[84:87]
	v_mfma_f32_16x16x32_bf16 v[80:83], v[198:201], v[222:225], v[80:83]
	v_mfma_f32_16x16x32_bf16 v[68:71], v[174:177], v[230:233], v[68:71]
	v_mfma_f32_16x16x32_bf16 v[64:67], v[198:201], v[230:233], v[64:67]
	s_barrier
	s_add_i32 s57, s57, s85
	s_mov_b32 m0, s57
	ds_read_b128 v[202:205], v183 offset:49152
	ds_read_b128 v[206:209], v183 offset:50176
	ds_read_b128 v[210:213], v183 offset:51200
	ds_read_b128 v[214:217], v183 offset:52224
	ds_read_b128 v[218:221], v183 offset:53248
	ds_read_b128 v[222:225], v183 offset:54272
	ds_read_b128 v[226:229], v183 offset:55296
	ds_read_b128 v[230:233], v183 offset:56320
	global_load_lds_dwordx4 v144, s[98:99]
	s_add_i32 m0, s57, 0x2000
	s_add_u32 s64, s64, 0x40080
	s_addc_u32 s65, s65, 0
	s_add_i32 s57, s68, s85
	global_load_lds_dwordx4 v146, s[98:99]
	s_mov_b32 m0, s57
	s_nop 0
	global_load_lds_dwordx4 v144, s[64:65]
	s_add_i32 m0, s57, 0x2000
	s_nop 0
	global_load_lds_dwordx4 v146, s[64:65]
	s_mov_b32 m0, s94
	s_nop 0
	global_load_lds_dwordx4 v144, s[100:101]
	s_mov_b32 m0, s95
	s_nop 0
	global_load_lds_dwordx4 v146, s[100:101]
	s_waitcnt vmcnt(8)
	s_waitcnt lgkmcnt(0)
	s_barrier
	v_mfma_f32_16x16x32_bf16 v[60:63], v[128:131], v[202:205], v[60:63]
	v_mfma_f32_16x16x32_bf16 v[56:59], v[136:139], v[202:205], v[56:59]
	v_mfma_f32_16x16x32_bf16 v[44:47], v[128:131], v[210:213], v[44:47]
	v_mfma_f32_16x16x32_bf16 v[40:43], v[136:139], v[210:213], v[40:43]
	v_mfma_f32_16x16x32_bf16 v[28:31], v[128:131], v[218:221], v[28:31]
	v_mfma_f32_16x16x32_bf16 v[24:27], v[136:139], v[218:221], v[24:27]
	v_mfma_f32_16x16x32_bf16 v[12:15], v[128:131], v[226:229], v[12:15]
	v_mfma_f32_16x16x32_bf16 v[8:11], v[136:139], v[226:229], v[8:11]
	v_mfma_f32_16x16x32_bf16 v[60:63], v[132:135], v[206:209], v[60:63]
	v_mfma_f32_16x16x32_bf16 v[56:59], v[140:143], v[206:209], v[56:59]
	v_mfma_f32_16x16x32_bf16 v[44:47], v[132:135], v[214:217], v[44:47]
	v_mfma_f32_16x16x32_bf16 v[40:43], v[140:143], v[214:217], v[40:43]
	v_mfma_f32_16x16x32_bf16 v[28:31], v[132:135], v[222:225], v[28:31]
	v_mfma_f32_16x16x32_bf16 v[24:27], v[140:143], v[222:225], v[24:27]
	v_mfma_f32_16x16x32_bf16 v[12:15], v[132:135], v[230:233], v[12:15]
	v_mfma_f32_16x16x32_bf16 v[8:11], v[140:143], v[230:233], v[8:11]
	v_mfma_f32_16x16x32_bf16 v[52:55], v[160:163], v[202:205], v[52:55]
	v_mfma_f32_16x16x32_bf16 v[48:51], v[194:197], v[202:205], v[48:51]
	v_mfma_f32_16x16x32_bf16 v[36:39], v[160:163], v[210:213], v[36:39]
	v_mfma_f32_16x16x32_bf16 v[32:35], v[194:197], v[210:213], v[32:35]
	v_mfma_f32_16x16x32_bf16 v[20:23], v[160:163], v[218:221], v[20:23]
	v_mfma_f32_16x16x32_bf16 v[16:19], v[194:197], v[218:221], v[16:19]
	v_mfma_f32_16x16x32_bf16 v[4:7], v[160:163], v[226:229], v[4:7]
	v_mfma_f32_16x16x32_bf16 v[0:3], v[194:197], v[226:229], v[0:3]
	v_mfma_f32_16x16x32_bf16 v[52:55], v[174:177], v[206:209], v[52:55]
	v_mfma_f32_16x16x32_bf16 v[48:51], v[198:201], v[206:209], v[48:51]
	v_mfma_f32_16x16x32_bf16 v[36:39], v[174:177], v[214:217], v[36:39]
	v_mfma_f32_16x16x32_bf16 v[32:35], v[198:201], v[214:217], v[32:35]
	v_mfma_f32_16x16x32_bf16 v[20:23], v[174:177], v[222:225], v[20:23]
	v_mfma_f32_16x16x32_bf16 v[16:19], v[198:201], v[222:225], v[16:19]
	v_mfma_f32_16x16x32_bf16 v[4:7], v[174:177], v[230:233], v[4:7]
	v_mfma_f32_16x16x32_bf16 v[0:3], v[198:201], v[230:233], v[0:3]
	s_barrier
	s_add_i32 s55, s55, 2
	s_add_u32 s62, s62, 0x100
	s_addc_u32 s63, s63, 0
	s_add_u32 s22, s22, 0x100
	s_addc_u32 s23, s23, 0
	s_cmp_gt_u32 s55, 13
	s_cbranch_scc1 .Lkx_552
.LBB0_552:
	ds_read_b128 v[128:131], v173
	ds_read_b128 v[132:135], v173 offset:1024
	ds_read_b128 v[136:139], v173 offset:2048
	ds_read_b128 v[140:143], v173 offset:3072
	ds_read_b128 v[160:163], v179
	ds_read_b128 v[174:177], v179 offset:1024
	ds_read_b128 v[194:197], v179 offset:2048
	ds_read_b128 v[198:201], v179 offset:3072
	s_add_u32 s57, s62, 0xfffc0080
	s_addc_u32 s64, s63, -1
	s_cmp_eq_u32 s55, 12
	s_cselect_b32 s67, s9, s64
	s_cselect_b32 s66, s11, s57
	s_cselect_b32 s65, s13, s23
	s_cselect_b32 s64, s16, s22
	s_add_i32 m0, s86, 0xc000
	ds_read_b128 v[202:205], v183
	ds_read_b128 v[206:209], v183 offset:1024
	ds_read_b128 v[210:213], v183 offset:2048
	ds_read_b128 v[214:217], v183 offset:3072
	ds_read_b128 v[218:221], v183 offset:4096
	ds_read_b128 v[222:225], v183 offset:5120
	ds_read_b128 v[226:229], v183 offset:6144
	ds_read_b128 v[230:233], v183 offset:7168
	global_load_lds_dwordx4 v152, s[62:63]
	s_add_i32 m0, s86, 0xe000
	s_nop 0
	global_load_lds_dwordx4 v154, s[62:63]
	s_waitcnt vmcnt(8)
	s_waitcnt lgkmcnt(0)
	s_barrier
	v_mfma_f32_16x16x32_bf16 v[124:127], v[128:131], v[202:205], v[124:127]
	v_mfma_f32_16x16x32_bf16 v[120:123], v[136:139], v[202:205], v[120:123]
	v_mfma_f32_16x16x32_bf16 v[108:111], v[128:131], v[210:213], v[108:111]
	v_mfma_f32_16x16x32_bf16 v[104:107], v[136:139], v[210:213], v[104:107]
	v_mfma_f32_16x16x32_bf16 v[92:95], v[128:131], v[218:221], v[92:95]
	v_mfma_f32_16x16x32_bf16 v[88:91], v[136:139], v[218:221], v[88:91]
	v_mfma_f32_16x16x32_bf16 v[76:79], v[128:131], v[226:229], v[76:79]
	v_mfma_f32_16x16x32_bf16 v[72:75], v[136:139], v[226:229], v[72:75]
	v_mfma_f32_16x16x32_bf16 v[124:127], v[132:135], v[206:209], v[124:127]
	v_mfma_f32_16x16x32_bf16 v[120:123], v[140:143], v[206:209], v[120:123]
	v_mfma_f32_16x16x32_bf16 v[108:111], v[132:135], v[214:217], v[108:111]
	v_mfma_f32_16x16x32_bf16 v[104:107], v[140:143], v[214:217], v[104:107]
	v_mfma_f32_16x16x32_bf16 v[92:95], v[132:135], v[222:225], v[92:95]
	v_mfma_f32_16x16x32_bf16 v[88:91], v[140:143], v[222:225], v[88:91]
	v_mfma_f32_16x16x32_bf16 v[76:79], v[132:135], v[230:233], v[76:79]
	v_mfma_f32_16x16x32_bf16 v[72:75], v[140:143], v[230:233], v[72:75]
	v_mfma_f32_16x16x32_bf16 v[116:119], v[160:163], v[202:205], v[116:119]
	v_mfma_f32_16x16x32_bf16 v[112:115], v[194:197], v[202:205], v[112:115]
	v_mfma_f32_16x16x32_bf16 v[100:103], v[160:163], v[210:213], v[100:103]
	v_mfma_f32_16x16x32_bf16 v[96:99], v[194:197], v[210:213], v[96:99]
	v_mfma_f32_16x16x32_bf16 v[84:87], v[160:163], v[218:221], v[84:87]
	v_mfma_f32_16x16x32_bf16 v[80:83], v[194:197], v[218:221], v[80:83]
	v_mfma_f32_16x16x32_bf16 v[68:71], v[160:163], v[226:229], v[68:71]
	v_mfma_f32_16x16x32_bf16 v[64:67], v[194:197], v[226:229], v[64:67]
	v_mfma_f32_16x16x32_bf16 v[116:119], v[174:177], v[206:209], v[116:119]
	v_mfma_f32_16x16x32_bf16 v[112:115], v[198:201], v[206:209], v[112:115]
	v_mfma_f32_16x16x32_bf16 v[100:103], v[174:177], v[214:217], v[100:103]
	v_mfma_f32_16x16x32_bf16 v[96:99], v[198:201], v[214:217], v[96:99]
	v_mfma_f32_16x16x32_bf16 v[84:87], v[174:177], v[222:225], v[84:87]
	v_mfma_f32_16x16x32_bf16 v[80:83], v[198:201], v[222:225], v[80:83]
	v_mfma_f32_16x16x32_bf16 v[68:71], v[174:177], v[230:233], v[68:71]
	v_mfma_f32_16x16x32_bf16 v[64:67], v[198:201], v[230:233], v[64:67]
	s_barrier
	s_add_i32 s57, s0, s85
	s_add_u32 s98, s64, 0x80
	s_addc_u32 s99, s65, 0
	s_mov_b32 m0, s57
	ds_read_b128 v[202:205], v183 offset:16384
	ds_read_b128 v[206:209], v183 offset:17408
	ds_read_b128 v[210:213], v183 offset:18432
	ds_read_b128 v[214:217], v183 offset:19456
	ds_read_b128 v[218:221], v183 offset:20480
	ds_read_b128 v[222:225], v183 offset:21504
	ds_read_b128 v[226:229], v183 offset:22528
	ds_read_b128 v[230:233], v183 offset:23552
	global_load_lds_dwordx4 v144, s[64:65]
	s_add_i32 m0, s57, 0x2000
	s_add_u32 s68, s64, 0x40000
	s_addc_u32 s69, s65, 0
	s_add_i32 s57, s1, s85
	global_load_lds_dwordx4 v146, s[64:65]
	s_mov_b32 m0, s57
	s_add_u32 s100, s66, 0x80
	s_addc_u32 s101, s67, 0
	global_load_lds_dwordx4 v144, s[68:69]
	s_add_i32 m0, s57, 0x2000
	s_nop 0
	global_load_lds_dwordx4 v146, s[68:69]
	s_mov_b32 m0, s86
	s_nop 0
	global_load_lds_dwordx4 v144, s[66:67]
	s_mov_b32 m0, s87
	s_nop 0
	global_load_lds_dwordx4 v146, s[66:67]
	s_waitcnt vmcnt(8)
	s_waitcnt lgkmcnt(0)
	s_barrier
	v_mfma_f32_16x16x32_bf16 v[60:63], v[128:131], v[202:205], v[60:63]
	v_mfma_f32_16x16x32_bf16 v[56:59], v[136:139], v[202:205], v[56:59]
	v_mfma_f32_16x16x32_bf16 v[44:47], v[128:131], v[210:213], v[44:47]
	v_mfma_f32_16x16x32_bf16 v[40:43], v[136:139], v[210:213], v[40:43]
	v_mfma_f32_16x16x32_bf16 v[28:31], v[128:131], v[218:221], v[28:31]
	v_mfma_f32_16x16x32_bf16 v[24:27], v[136:139], v[218:221], v[24:27]
	v_mfma_f32_16x16x32_bf16 v[12:15], v[128:131], v[226:229], v[12:15]
	v_mfma_f32_16x16x32_bf16 v[8:11], v[136:139], v[226:229], v[8:11]
	v_mfma_f32_16x16x32_bf16 v[60:63], v[132:135], v[206:209], v[60:63]
	v_mfma_f32_16x16x32_bf16 v[56:59], v[140:143], v[206:209], v[56:59]
	v_mfma_f32_16x16x32_bf16 v[44:47], v[132:135], v[214:217], v[44:47]
	v_mfma_f32_16x16x32_bf16 v[40:43], v[140:143], v[214:217], v[40:43]
	v_mfma_f32_16x16x32_bf16 v[28:31], v[132:135], v[222:225], v[28:31]
	v_mfma_f32_16x16x32_bf16 v[24:27], v[140:143], v[222:225], v[24:27]
	v_mfma_f32_16x16x32_bf16 v[12:15], v[132:135], v[230:233], v[12:15]
	v_mfma_f32_16x16x32_bf16 v[8:11], v[140:143], v[230:233], v[8:11]
	v_mfma_f32_16x16x32_bf16 v[52:55], v[160:163], v[202:205], v[52:55]
	v_mfma_f32_16x16x32_bf16 v[48:51], v[194:197], v[202:205], v[48:51]
	v_mfma_f32_16x16x32_bf16 v[36:39], v[160:163], v[210:213], v[36:39]
	v_mfma_f32_16x16x32_bf16 v[32:35], v[194:197], v[210:213], v[32:35]
	v_mfma_f32_16x16x32_bf16 v[20:23], v[160:163], v[218:221], v[20:23]
	v_mfma_f32_16x16x32_bf16 v[16:19], v[194:197], v[218:221], v[16:19]
	v_mfma_f32_16x16x32_bf16 v[4:7], v[160:163], v[226:229], v[4:7]
	v_mfma_f32_16x16x32_bf16 v[0:3], v[194:197], v[226:229], v[0:3]
	v_mfma_f32_16x16x32_bf16 v[52:55], v[174:177], v[206:209], v[52:55]
	v_mfma_f32_16x16x32_bf16 v[48:51], v[198:201], v[206:209], v[48:51]
	v_mfma_f32_16x16x32_bf16 v[36:39], v[174:177], v[214:217], v[36:39]
	v_mfma_f32_16x16x32_bf16 v[32:35], v[198:201], v[214:217], v[32:35]
	v_mfma_f32_16x16x32_bf16 v[20:23], v[174:177], v[222:225], v[20:23]
	v_mfma_f32_16x16x32_bf16 v[16:19], v[198:201], v[222:225], v[16:19]
	v_mfma_f32_16x16x32_bf16 v[4:7], v[174:177], v[230:233], v[4:7]
	v_mfma_f32_16x16x32_bf16 v[0:3], v[198:201], v[230:233], v[0:3]
	s_barrier
	s_add_i32 s57, 0, 0x18000
	s_add_i32 s68, 0, 0x1c000
	v_add_u32_e32 v140, s57, v169
	v_add_u32_e32 v148, s68, v169
	ds_read_b128 v[128:131], v140
	ds_read_b128 v[132:135], v140 offset:1024
	ds_read_b128 v[136:139], v140 offset:2048
	ds_read_b128 v[140:143], v140 offset:3072
	ds_read_b128 v[160:163], v148
	ds_read_b128 v[174:177], v148 offset:1024
	ds_read_b128 v[194:197], v148 offset:2048
	ds_read_b128 v[198:201], v148 offset:3072
	s_add_u32 s66, s66, 0x40000
	s_addc_u32 s67, s67, 0
	s_mov_b32 m0, s88
	ds_read_b128 v[202:205], v183 offset:32768
	ds_read_b128 v[206:209], v183 offset:33792
	ds_read_b128 v[210:213], v183 offset:34816
	ds_read_b128 v[214:217], v183 offset:35840
	ds_read_b128 v[218:221], v183 offset:36864
	ds_read_b128 v[222:225], v183 offset:37888
	ds_read_b128 v[226:229], v183 offset:38912
	ds_read_b128 v[230:233], v183 offset:39936
	global_load_lds_dwordx4 v144, s[66:67]
	s_mov_b32 m0, s89
	s_nop 0
	global_load_lds_dwordx4 v146, s[66:67]
	s_waitcnt vmcnt(8)
	s_waitcnt lgkmcnt(0)
	s_barrier
	v_mfma_f32_16x16x32_bf16 v[124:127], v[128:131], v[202:205], v[124:127]
	v_mfma_f32_16x16x32_bf16 v[120:123], v[136:139], v[202:205], v[120:123]
	v_mfma_f32_16x16x32_bf16 v[108:111], v[128:131], v[210:213], v[108:111]
	v_mfma_f32_16x16x32_bf16 v[104:107], v[136:139], v[210:213], v[104:107]
	v_mfma_f32_16x16x32_bf16 v[92:95], v[128:131], v[218:221], v[92:95]
	v_mfma_f32_16x16x32_bf16 v[88:91], v[136:139], v[218:221], v[88:91]
	v_mfma_f32_16x16x32_bf16 v[76:79], v[128:131], v[226:229], v[76:79]
	v_mfma_f32_16x16x32_bf16 v[72:75], v[136:139], v[226:229], v[72:75]
	v_mfma_f32_16x16x32_bf16 v[124:127], v[132:135], v[206:209], v[124:127]
	v_mfma_f32_16x16x32_bf16 v[120:123], v[140:143], v[206:209], v[120:123]
	v_mfma_f32_16x16x32_bf16 v[108:111], v[132:135], v[214:217], v[108:111]
	v_mfma_f32_16x16x32_bf16 v[104:107], v[140:143], v[214:217], v[104:107]
	v_mfma_f32_16x16x32_bf16 v[92:95], v[132:135], v[222:225], v[92:95]
	v_mfma_f32_16x16x32_bf16 v[88:91], v[140:143], v[222:225], v[88:91]
	v_mfma_f32_16x16x32_bf16 v[76:79], v[132:135], v[230:233], v[76:79]
	v_mfma_f32_16x16x32_bf16 v[72:75], v[140:143], v[230:233], v[72:75]
	v_mfma_f32_16x16x32_bf16 v[116:119], v[160:163], v[202:205], v[116:119]
	v_mfma_f32_16x16x32_bf16 v[112:115], v[194:197], v[202:205], v[112:115]
	v_mfma_f32_16x16x32_bf16 v[100:103], v[160:163], v[210:213], v[100:103]
	v_mfma_f32_16x16x32_bf16 v[96:99], v[194:197], v[210:213], v[96:99]
	v_mfma_f32_16x16x32_bf16 v[84:87], v[160:163], v[218:221], v[84:87]
	v_mfma_f32_16x16x32_bf16 v[80:83], v[194:197], v[218:221], v[80:83]
	v_mfma_f32_16x16x32_bf16 v[68:71], v[160:163], v[226:229], v[68:71]
	v_mfma_f32_16x16x32_bf16 v[64:67], v[194:197], v[226:229], v[64:67]
	v_mfma_f32_16x16x32_bf16 v[116:119], v[174:177], v[206:209], v[116:119]
	v_mfma_f32_16x16x32_bf16 v[112:115], v[198:201], v[206:209], v[112:115]
	v_mfma_f32_16x16x32_bf16 v[100:103], v[174:177], v[214:217], v[100:103]
	v_mfma_f32_16x16x32_bf16 v[96:99], v[198:201], v[214:217], v[96:99]
	v_mfma_f32_16x16x32_bf16 v[84:87], v[174:177], v[222:225], v[84:87]
	v_mfma_f32_16x16x32_bf16 v[80:83], v[198:201], v[222:225], v[80:83]
	v_mfma_f32_16x16x32_bf16 v[68:71], v[174:177], v[230:233], v[68:71]
	v_mfma_f32_16x16x32_bf16 v[64:67], v[198:201], v[230:233], v[64:67]
	s_barrier
	s_add_i32 s57, s57, s85
	s_mov_b32 m0, s57
	ds_read_b128 v[202:205], v183 offset:49152
	ds_read_b128 v[206:209], v183 offset:50176
	ds_read_b128 v[210:213], v183 offset:51200
	ds_read_b128 v[214:217], v183 offset:52224
	ds_read_b128 v[218:221], v183 offset:53248
	ds_read_b128 v[222:225], v183 offset:54272
	ds_read_b128 v[226:229], v183 offset:55296
	ds_read_b128 v[230:233], v183 offset:56320
	global_load_lds_dwordx4 v144, s[98:99]
	s_add_i32 m0, s57, 0x2000
	s_add_u32 s64, s64, 0x40080
	s_addc_u32 s65, s65, 0
	s_add_i32 s57, s68, s85
	global_load_lds_dwordx4 v146, s[98:99]
	s_mov_b32 m0, s57
	s_nop 0
	global_load_lds_dwordx4 v144, s[64:65]
	s_add_i32 m0, s57, 0x2000
	s_nop 0
	global_load_lds_dwordx4 v146, s[64:65]
	s_mov_b32 m0, s94
	s_nop 0
	global_load_lds_dwordx4 v144, s[100:101]
	s_mov_b32 m0, s95
	s_nop 0
	global_load_lds_dwordx4 v146, s[100:101]
	s_waitcnt vmcnt(8)
	s_waitcnt lgkmcnt(0)
	s_barrier
	v_mfma_f32_16x16x32_bf16 v[60:63], v[128:131], v[202:205], v[60:63]
	v_mfma_f32_16x16x32_bf16 v[56:59], v[136:139], v[202:205], v[56:59]
	v_mfma_f32_16x16x32_bf16 v[44:47], v[128:131], v[210:213], v[44:47]
	v_mfma_f32_16x16x32_bf16 v[40:43], v[136:139], v[210:213], v[40:43]
	v_mfma_f32_16x16x32_bf16 v[28:31], v[128:131], v[218:221], v[28:31]
	v_mfma_f32_16x16x32_bf16 v[24:27], v[136:139], v[218:221], v[24:27]
	v_mfma_f32_16x16x32_bf16 v[12:15], v[128:131], v[226:229], v[12:15]
	v_mfma_f32_16x16x32_bf16 v[8:11], v[136:139], v[226:229], v[8:11]
	v_mfma_f32_16x16x32_bf16 v[60:63], v[132:135], v[206:209], v[60:63]
	v_mfma_f32_16x16x32_bf16 v[56:59], v[140:143], v[206:209], v[56:59]
	v_mfma_f32_16x16x32_bf16 v[44:47], v[132:135], v[214:217], v[44:47]
	v_mfma_f32_16x16x32_bf16 v[40:43], v[140:143], v[214:217], v[40:43]
	v_mfma_f32_16x16x32_bf16 v[28:31], v[132:135], v[222:225], v[28:31]
	v_mfma_f32_16x16x32_bf16 v[24:27], v[140:143], v[222:225], v[24:27]
	v_mfma_f32_16x16x32_bf16 v[12:15], v[132:135], v[230:233], v[12:15]
	v_mfma_f32_16x16x32_bf16 v[8:11], v[140:143], v[230:233], v[8:11]
	v_mfma_f32_16x16x32_bf16 v[52:55], v[160:163], v[202:205], v[52:55]
	v_mfma_f32_16x16x32_bf16 v[48:51], v[194:197], v[202:205], v[48:51]
	v_mfma_f32_16x16x32_bf16 v[36:39], v[160:163], v[210:213], v[36:39]
	v_mfma_f32_16x16x32_bf16 v[32:35], v[194:197], v[210:213], v[32:35]
	v_mfma_f32_16x16x32_bf16 v[20:23], v[160:163], v[218:221], v[20:23]
	v_mfma_f32_16x16x32_bf16 v[16:19], v[194:197], v[218:221], v[16:19]
	v_mfma_f32_16x16x32_bf16 v[4:7], v[160:163], v[226:229], v[4:7]
	v_mfma_f32_16x16x32_bf16 v[0:3], v[194:197], v[226:229], v[0:3]
	v_mfma_f32_16x16x32_bf16 v[52:55], v[174:177], v[206:209], v[52:55]
	v_mfma_f32_16x16x32_bf16 v[48:51], v[198:201], v[206:209], v[48:51]
	v_mfma_f32_16x16x32_bf16 v[36:39], v[174:177], v[214:217], v[36:39]
	v_mfma_f32_16x16x32_bf16 v[32:35], v[198:201], v[214:217], v[32:35]
	v_mfma_f32_16x16x32_bf16 v[20:23], v[174:177], v[222:225], v[20:23]
	v_mfma_f32_16x16x32_bf16 v[16:19], v[198:201], v[222:225], v[16:19]
	v_mfma_f32_16x16x32_bf16 v[4:7], v[174:177], v[230:233], v[4:7]
	v_mfma_f32_16x16x32_bf16 v[0:3], v[198:201], v[230:233], v[0:3]
	s_barrier
	s_add_i32 s55, s55, 2
	s_add_u32 s62, s62, 0x100
	s_addc_u32 s63, s63, 0
	s_add_u32 s22, s22, 0x100
	s_addc_u32 s23, s23, 0
	s_cmp_gt_u32 s55, 13
	s_cbranch_scc0 .LBB0_552

.LBB0_743:
	s_ashr_i32 s35, s34, 31
	s_lshl_b64 s[36:37], s[34:35], 17
	s_add_u32 s36, s13, s36
	s_addc_u32 s37, s22, s37
	s_and_b64 s[38:39], s[4:5], exec
	s_cselect_b32 s35, s37, s43
	s_cselect_b32 s82, s36, s42
	s_ashr_i32 s31, s30, 31
	s_lshl_b64 s[38:39], s[30:31], 17
	s_add_u32 s38, s23, s38
	s_addc_u32 s39, s58, s39
	s_and_b64 s[44:45], s[4:5], exec
	s_cselect_b32 s31, s39, s41
	s_cselect_b32 s83, s38, s40
	s_mov_b64 s[48:49], 0
	s_mov_b64 s[44:45], -1
	s_mov_b64 s[46:47], 0
	s_add_u32 s54, s42, s48
	s_addc_u32 s55, s43, s49
	s_add_u32 s52, s54, 0x100
	s_addc_u32 s53, s55, 0
	s_and_b64 s[50:51], s[46:47], exec
	s_cselect_b32 s51, s35, s53
	s_cselect_b32 s50, s82, s52
	s_add_u32 s48, s40, s48
	s_addc_u32 s49, s41, s49
	s_add_u32 s48, s48, 0x100
	s_addc_u32 s49, s49, 0
	s_and_b64 s[46:47], s[46:47], exec
	s_cselect_b32 s53, s31, s49
	s_cselect_b32 s52, s83, s48
	s_cselect_b32 s98, 1, 0
	s_add_u32 s56, s54, 0x10080
	ds_read_b128 v[150:153], v144
	ds_read_b128 v[154:157], v144 offset:1024
	ds_read_b128 v[158:161], v144 offset:2048
	ds_read_b128 v[162:165], v144 offset:3072
	ds_read_b128 v[166:169], v145
	ds_read_b128 v[170:173], v145 offset:1024
	ds_read_b128 v[174:177], v145 offset:2048
	ds_read_b128 v[178:181], v145 offset:3072
	s_addc_u32 s57, s55, 0
	s_add_i32 s93, s74, s60
	s_add_i32 m0, s61, 0xc000
	s_add_i32 s94, s61, 0xe000
	s_add_i32 s90, s93, 0x2000
	s_add_u32 s54, s52, 0x10000
	s_addc_u32 s55, s53, 0
	s_add_i32 s92, s75, s60
	s_add_i32 s91, s92, 0x2000
	s_add_i32 s89, 0, 0x18000
	s_add_i32 s88, 0, 0x1c000
	s_add_u32 s48, s50, 0x10000
	s_addc_u32 s49, s51, 0
	s_add_i32 s87, s89, s60
	s_add_i32 s85, s87, 0x2000
	s_add_u32 s46, s52, 0x10080
	s_addc_u32 s47, s53, 0
	s_add_i32 s86, s88, s60
	s_add_i32 s84, s86, 0x2000
	v_lshl_add_u64 v[138:139], s[56:57], 0, v[130:131]
	ds_read_b128 v[182:185], v146
	ds_read_b128 v[186:189], v146 offset:1024
	ds_read_b128 v[190:193], v146 offset:2048
	ds_read_b128 v[194:197], v146 offset:3072
	ds_read_b128 v[198:201], v146 offset:4096
	ds_read_b128 v[202:205], v146 offset:5120
	ds_read_b128 v[206:209], v146 offset:6144
	ds_read_b128 v[210:213], v146 offset:7168
	global_load_lds_dwordx4 v[138:139], off
	v_lshl_add_u64 v[138:139], s[56:57], 0, v[128:129]
	s_mov_b32 m0, s94
	s_nop 0
	global_load_lds_dwordx4 v[138:139], off
	s_waitcnt vmcnt(8)
	s_waitcnt lgkmcnt(0)
	s_cmp_lg_u32 s98, 0
	s_cbranch_scc0 .Lkv_nopf_pk
	v_lshl_add_u32 v138, s18, 8, v141
	v_ashrrev_i32_e32 v139, 31, v138
	v_lshl_add_u64 v[138:139], v[138:139], 4, s[14:15]
	global_load_dwordx4 v[222:225], v[138:139], off
	global_load_dwordx4 v[226:229], v[138:139], off offset:256
	global_load_dwordx4 v[230:233], v[138:139], off offset:512
	global_load_dwordx4 v[234:237], v[138:139], off offset:768
	global_load_dwordx4 v[238:241], v[138:139], off offset:2048
	global_load_dwordx4 v[242:245], v[138:139], off offset:2304
	global_load_dwordx4 v[248:251], v[138:139], off offset:2560
	global_load_dwordx4 v[252:255], v[138:139], off offset:2816
.Lkv_nopf_pk:
	s_barrier
	v_mfma_f32_16x16x32_bf16 v[124:127], v[150:153], v[182:185], 0
	v_mfma_f32_16x16x32_bf16 v[120:123], v[158:161], v[182:185], 0
	v_mfma_f32_16x16x32_bf16 v[108:111], v[150:153], v[190:193], 0
	v_mfma_f32_16x16x32_bf16 v[104:107], v[158:161], v[190:193], 0
	v_mfma_f32_16x16x32_bf16 v[92:95], v[150:153], v[198:201], 0
	v_mfma_f32_16x16x32_bf16 v[88:91], v[158:161], v[198:201], 0
	v_mfma_f32_16x16x32_bf16 v[76:79], v[150:153], v[206:209], 0
	v_mfma_f32_16x16x32_bf16 v[72:75], v[158:161], v[206:209], 0
	v_mfma_f32_16x16x32_bf16 v[124:127], v[154:157], v[186:189], v[124:127]
	v_mfma_f32_16x16x32_bf16 v[120:123], v[162:165], v[186:189], v[120:123]
	v_mfma_f32_16x16x32_bf16 v[108:111], v[154:157], v[194:197], v[108:111]
	v_mfma_f32_16x16x32_bf16 v[104:107], v[162:165], v[194:197], v[104:107]
	v_mfma_f32_16x16x32_bf16 v[92:95], v[154:157], v[202:205], v[92:95]
	v_mfma_f32_16x16x32_bf16 v[88:91], v[162:165], v[202:205], v[88:91]
	v_mfma_f32_16x16x32_bf16 v[76:79], v[154:157], v[210:213], v[76:79]
	v_mfma_f32_16x16x32_bf16 v[72:75], v[162:165], v[210:213], v[72:75]
	v_mfma_f32_16x16x32_bf16 v[116:119], v[166:169], v[182:185], 0
	v_mfma_f32_16x16x32_bf16 v[112:115], v[174:177], v[182:185], 0
	v_mfma_f32_16x16x32_bf16 v[100:103], v[166:169], v[190:193], 0
	v_mfma_f32_16x16x32_bf16 v[96:99], v[174:177], v[190:193], 0
	v_mfma_f32_16x16x32_bf16 v[84:87], v[166:169], v[198:201], 0
	v_mfma_f32_16x16x32_bf16 v[80:83], v[174:177], v[198:201], 0
	v_mfma_f32_16x16x32_bf16 v[68:71], v[166:169], v[206:209], 0
	v_mfma_f32_16x16x32_bf16 v[64:67], v[174:177], v[206:209], 0
	v_mfma_f32_16x16x32_bf16 v[116:119], v[170:173], v[186:189], v[116:119]
	v_mfma_f32_16x16x32_bf16 v[112:115], v[178:181], v[186:189], v[112:115]
	v_mfma_f32_16x16x32_bf16 v[100:103], v[170:173], v[194:197], v[100:103]
	v_mfma_f32_16x16x32_bf16 v[96:99], v[178:181], v[194:197], v[96:99]
	v_mfma_f32_16x16x32_bf16 v[84:87], v[170:173], v[202:205], v[84:87]
	v_mfma_f32_16x16x32_bf16 v[80:83], v[178:181], v[202:205], v[80:83]
	v_mfma_f32_16x16x32_bf16 v[68:71], v[170:173], v[210:213], v[68:71]
	v_mfma_f32_16x16x32_bf16 v[64:67], v[178:181], v[210:213], v[64:67]
	s_barrier
	s_mov_b32 m0, s93
	v_lshl_add_u64 v[138:139], s[52:53], 0, v[130:131]
	ds_read_b128 v[182:185], v146 offset:16384
	ds_read_b128 v[186:189], v146 offset:17408
	ds_read_b128 v[190:193], v146 offset:18432
	ds_read_b128 v[194:197], v146 offset:19456
	ds_read_b128 v[198:201], v146 offset:20480
	ds_read_b128 v[202:205], v146 offset:21504
	ds_read_b128 v[206:209], v146 offset:22528
	ds_read_b128 v[210:213], v146 offset:23552
	global_load_lds_dwordx4 v[138:139], off
	v_lshl_add_u64 v[214:215], s[52:53], 0, v[128:129]
	s_mov_b32 m0, s90
	v_lshl_add_u64 v[216:217], s[54:55], 0, v[130:131]
	global_load_lds_dwordx4 v[214:215], off
	s_mov_b32 m0, s92
	v_lshl_add_u64 v[218:219], s[50:51], 0, v[128:129]
	global_load_lds_dwordx4 v[216:217], off
	v_lshl_add_u64 v[216:217], s[54:55], 0, v[128:129]
	s_mov_b32 m0, s91
	s_nop 0
	global_load_lds_dwordx4 v[216:217], off
	v_lshl_add_u64 v[216:217], s[50:51], 0, v[130:131]
	s_mov_b32 m0, s61
	s_nop 0
	global_load_lds_dwordx4 v[216:217], off
	s_mov_b32 m0, s62
	s_nop 0
	global_load_lds_dwordx4 v[218:219], off
	s_waitcnt vmcnt(8)
	s_waitcnt lgkmcnt(0)
	s_barrier
	v_mfma_f32_16x16x32_bf16 v[60:63], v[150:153], v[182:185], 0
	v_mfma_f32_16x16x32_bf16 v[56:59], v[158:161], v[182:185], 0
	v_mfma_f32_16x16x32_bf16 v[44:47], v[150:153], v[190:193], 0
	v_mfma_f32_16x16x32_bf16 v[40:43], v[158:161], v[190:193], 0
	v_mfma_f32_16x16x32_bf16 v[28:31], v[150:153], v[198:201], 0
	v_mfma_f32_16x16x32_bf16 v[24:27], v[158:161], v[198:201], 0
	v_mfma_f32_16x16x32_bf16 v[12:15], v[150:153], v[206:209], 0
	v_mfma_f32_16x16x32_bf16 v[8:11], v[158:161], v[206:209], 0
	v_mfma_f32_16x16x32_bf16 v[60:63], v[154:157], v[186:189], v[60:63]
	v_mfma_f32_16x16x32_bf16 v[56:59], v[162:165], v[186:189], v[56:59]
	v_mfma_f32_16x16x32_bf16 v[44:47], v[154:157], v[194:197], v[44:47]
	v_mfma_f32_16x16x32_bf16 v[40:43], v[162:165], v[194:197], v[40:43]
	v_mfma_f32_16x16x32_bf16 v[28:31], v[154:157], v[202:205], v[28:31]
	v_mfma_f32_16x16x32_bf16 v[24:27], v[162:165], v[202:205], v[24:27]
	v_mfma_f32_16x16x32_bf16 v[12:15], v[154:157], v[210:213], v[12:15]
	v_mfma_f32_16x16x32_bf16 v[8:11], v[162:165], v[210:213], v[8:11]
	v_mfma_f32_16x16x32_bf16 v[52:55], v[166:169], v[182:185], 0
	v_mfma_f32_16x16x32_bf16 v[48:51], v[174:177], v[182:185], 0
	v_mfma_f32_16x16x32_bf16 v[36:39], v[166:169], v[190:193], 0
	v_mfma_f32_16x16x32_bf16 v[32:35], v[174:177], v[190:193], 0
	v_mfma_f32_16x16x32_bf16 v[20:23], v[166:169], v[198:201], 0
	v_mfma_f32_16x16x32_bf16 v[16:19], v[174:177], v[198:201], 0
	v_mfma_f32_16x16x32_bf16 v[4:7], v[166:169], v[206:209], 0
	v_mfma_f32_16x16x32_bf16 v[0:3], v[174:177], v[206:209], 0
	v_mfma_f32_16x16x32_bf16 v[52:55], v[170:173], v[186:189], v[52:55]
	v_mfma_f32_16x16x32_bf16 v[48:51], v[178:181], v[186:189], v[48:51]
	v_mfma_f32_16x16x32_bf16 v[36:39], v[170:173], v[194:197], v[36:39]
	v_mfma_f32_16x16x32_bf16 v[32:35], v[178:181], v[194:197], v[32:35]
	v_mfma_f32_16x16x32_bf16 v[20:23], v[170:173], v[202:205], v[20:23]
	v_mfma_f32_16x16x32_bf16 v[16:19], v[178:181], v[202:205], v[16:19]
	v_mfma_f32_16x16x32_bf16 v[4:7], v[170:173], v[210:213], v[4:7]
	v_mfma_f32_16x16x32_bf16 v[0:3], v[178:181], v[210:213], v[0:3]
	s_barrier
	v_add_u32_e32 v132, s89, v143
	ds_read_b128 v[150:153], v132
	ds_read_b128 v[154:157], v132 offset:1024
	ds_read_b128 v[158:161], v132 offset:2048
	ds_read_b128 v[162:165], v132 offset:3072
	v_add_u32_e32 v132, s88, v143
	ds_read_b128 v[166:169], v132
	ds_read_b128 v[170:173], v132 offset:1024
	ds_read_b128 v[174:177], v132 offset:2048
	ds_read_b128 v[178:181], v132 offset:3072
	s_mov_b32 m0, s63
	v_lshl_add_u64 v[220:221], s[48:49], 0, v[130:131]
	ds_read_b128 v[182:185], v146 offset:32768
	ds_read_b128 v[186:189], v146 offset:33792
	ds_read_b128 v[190:193], v146 offset:34816
	ds_read_b128 v[194:197], v146 offset:35840
	ds_read_b128 v[198:201], v146 offset:36864
	ds_read_b128 v[202:205], v146 offset:37888
	ds_read_b128 v[206:209], v146 offset:38912
	ds_read_b128 v[210:213], v146 offset:39936
	global_load_lds_dwordx4 v[220:221], off
	v_lshl_add_u64 v[220:221], s[48:49], 0, v[128:129]
	s_mov_b32 m0, s64
	s_nop 0
	global_load_lds_dwordx4 v[220:221], off
	s_waitcnt vmcnt(8)
	s_waitcnt lgkmcnt(0)
	s_barrier
	v_mfma_f32_16x16x32_bf16 v[124:127], v[150:153], v[182:185], v[124:127]
	v_mfma_f32_16x16x32_bf16 v[120:123], v[158:161], v[182:185], v[120:123]
	v_mfma_f32_16x16x32_bf16 v[108:111], v[150:153], v[190:193], v[108:111]
	v_mfma_f32_16x16x32_bf16 v[104:107], v[158:161], v[190:193], v[104:107]
	v_mfma_f32_16x16x32_bf16 v[92:95], v[150:153], v[198:201], v[92:95]
	v_mfma_f32_16x16x32_bf16 v[88:91], v[158:161], v[198:201], v[88:91]
	v_mfma_f32_16x16x32_bf16 v[76:79], v[150:153], v[206:209], v[76:79]
	v_mfma_f32_16x16x32_bf16 v[72:75], v[158:161], v[206:209], v[72:75]
	v_mfma_f32_16x16x32_bf16 v[124:127], v[154:157], v[186:189], v[124:127]
	v_mfma_f32_16x16x32_bf16 v[120:123], v[162:165], v[186:189], v[120:123]
	v_mfma_f32_16x16x32_bf16 v[108:111], v[154:157], v[194:197], v[108:111]
	v_mfma_f32_16x16x32_bf16 v[104:107], v[162:165], v[194:197], v[104:107]
	v_mfma_f32_16x16x32_bf16 v[92:95], v[154:157], v[202:205], v[92:95]
	v_mfma_f32_16x16x32_bf16 v[88:91], v[162:165], v[202:205], v[88:91]
	v_mfma_f32_16x16x32_bf16 v[76:79], v[154:157], v[210:213], v[76:79]
	v_mfma_f32_16x16x32_bf16 v[72:75], v[162:165], v[210:213], v[72:75]
	v_mfma_f32_16x16x32_bf16 v[116:119], v[166:169], v[182:185], v[116:119]
	v_mfma_f32_16x16x32_bf16 v[112:115], v[174:177], v[182:185], v[112:115]
	v_mfma_f32_16x16x32_bf16 v[100:103], v[166:169], v[190:193], v[100:103]
	v_mfma_f32_16x16x32_bf16 v[96:99], v[174:177], v[190:193], v[96:99]
	v_mfma_f32_16x16x32_bf16 v[84:87], v[166:169], v[198:201], v[84:87]
	v_mfma_f32_16x16x32_bf16 v[80:83], v[174:177], v[198:201], v[80:83]
	v_mfma_f32_16x16x32_bf16 v[68:71], v[166:169], v[206:209], v[68:71]
	v_mfma_f32_16x16x32_bf16 v[64:67], v[174:177], v[206:209], v[64:67]
	v_mfma_f32_16x16x32_bf16 v[116:119], v[170:173], v[186:189], v[116:119]
	v_mfma_f32_16x16x32_bf16 v[112:115], v[178:181], v[186:189], v[112:115]
	v_mfma_f32_16x16x32_bf16 v[100:103], v[170:173], v[194:197], v[100:103]
	v_mfma_f32_16x16x32_bf16 v[96:99], v[178:181], v[194:197], v[96:99]
	v_mfma_f32_16x16x32_bf16 v[84:87], v[170:173], v[202:205], v[84:87]
	v_mfma_f32_16x16x32_bf16 v[80:83], v[178:181], v[202:205], v[80:83]
	v_mfma_f32_16x16x32_bf16 v[68:71], v[170:173], v[210:213], v[68:71]
	v_mfma_f32_16x16x32_bf16 v[64:67], v[178:181], v[210:213], v[64:67]
	s_barrier
	s_mov_b32 m0, s87
	v_lshl_add_u64 v[138:139], v[138:139], 0, s[16:17]
	ds_read_b128 v[182:185], v146 offset:49152
	ds_read_b128 v[186:189], v146 offset:50176
	ds_read_b128 v[190:193], v146 offset:51200
	ds_read_b128 v[194:197], v146 offset:52224
	ds_read_b128 v[198:201], v146 offset:53248
	ds_read_b128 v[202:205], v146 offset:54272
	ds_read_b128 v[206:209], v146 offset:55296
	ds_read_b128 v[210:213], v146 offset:56320
	global_load_lds_dwordx4 v[138:139], off
	v_lshl_add_u64 v[138:139], v[214:215], 0, s[16:17]
	s_mov_b32 m0, s85
	s_nop 0
	global_load_lds_dwordx4 v[138:139], off
	v_lshl_add_u64 v[138:139], s[46:47], 0, v[130:131]
	s_mov_b32 m0, s86
	s_nop 0
	global_load_lds_dwordx4 v[138:139], off
	v_lshl_add_u64 v[138:139], s[46:47], 0, v[128:129]
	s_mov_b32 m0, s84
	s_nop 0
	global_load_lds_dwordx4 v[138:139], off
	v_lshl_add_u64 v[138:139], v[216:217], 0, s[16:17]
	s_mov_b32 m0, s70
	s_nop 0
	global_load_lds_dwordx4 v[138:139], off
	v_lshl_add_u64 v[138:139], v[218:219], 0, s[16:17]
	s_mov_b32 m0, s71
	s_nop 0
	global_load_lds_dwordx4 v[138:139], off
	s_waitcnt vmcnt(8)
	s_waitcnt lgkmcnt(0)
	s_barrier
	v_mfma_f32_16x16x32_bf16 v[60:63], v[150:153], v[182:185], v[60:63]
	v_mfma_f32_16x16x32_bf16 v[56:59], v[158:161], v[182:185], v[56:59]
	v_mfma_f32_16x16x32_bf16 v[44:47], v[150:153], v[190:193], v[44:47]
	v_mfma_f32_16x16x32_bf16 v[40:43], v[158:161], v[190:193], v[40:43]
	v_mfma_f32_16x16x32_bf16 v[28:31], v[150:153], v[198:201], v[28:31]
	v_mfma_f32_16x16x32_bf16 v[24:27], v[158:161], v[198:201], v[24:27]
	v_mfma_f32_16x16x32_bf16 v[12:15], v[150:153], v[206:209], v[12:15]
	v_mfma_f32_16x16x32_bf16 v[8:11], v[158:161], v[206:209], v[8:11]
	v_mfma_f32_16x16x32_bf16 v[60:63], v[154:157], v[186:189], v[60:63]
	v_mfma_f32_16x16x32_bf16 v[56:59], v[162:165], v[186:189], v[56:59]
	v_mfma_f32_16x16x32_bf16 v[44:47], v[154:157], v[194:197], v[44:47]
	v_mfma_f32_16x16x32_bf16 v[40:43], v[162:165], v[194:197], v[40:43]
	v_mfma_f32_16x16x32_bf16 v[28:31], v[154:157], v[202:205], v[28:31]
	v_mfma_f32_16x16x32_bf16 v[24:27], v[162:165], v[202:205], v[24:27]
	v_mfma_f32_16x16x32_bf16 v[12:15], v[154:157], v[210:213], v[12:15]
	v_mfma_f32_16x16x32_bf16 v[8:11], v[162:165], v[210:213], v[8:11]
	v_mfma_f32_16x16x32_bf16 v[52:55], v[166:169], v[182:185], v[52:55]
	v_mfma_f32_16x16x32_bf16 v[48:51], v[174:177], v[182:185], v[48:51]
	v_mfma_f32_16x16x32_bf16 v[36:39], v[166:169], v[190:193], v[36:39]
	v_mfma_f32_16x16x32_bf16 v[32:35], v[174:177], v[190:193], v[32:35]
	v_mfma_f32_16x16x32_bf16 v[20:23], v[166:169], v[198:201], v[20:23]
	v_mfma_f32_16x16x32_bf16 v[16:19], v[174:177], v[198:201], v[16:19]
	v_mfma_f32_16x16x32_bf16 v[4:7], v[166:169], v[206:209], v[4:7]
	v_mfma_f32_16x16x32_bf16 v[0:3], v[174:177], v[206:209], v[0:3]
	v_mfma_f32_16x16x32_bf16 v[52:55], v[170:173], v[186:189], v[52:55]
	v_mfma_f32_16x16x32_bf16 v[48:51], v[178:181], v[186:189], v[48:51]
	v_mfma_f32_16x16x32_bf16 v[36:39], v[170:173], v[194:197], v[36:39]
	v_mfma_f32_16x16x32_bf16 v[32:35], v[178:181], v[194:197], v[32:35]
	v_mfma_f32_16x16x32_bf16 v[20:23], v[170:173], v[202:205], v[20:23]
	v_mfma_f32_16x16x32_bf16 v[16:19], v[178:181], v[202:205], v[16:19]
	v_mfma_f32_16x16x32_bf16 v[4:7], v[170:173], v[210:213], v[4:7]
	v_mfma_f32_16x16x32_bf16 v[0:3], v[178:181], v[210:213], v[0:3]
	s_barrier
	s_andn2_b64 vcc, exec, s[44:45]
	s_mov_b64 s[46:47], -1
	s_mov_b64 s[44:45], 0
	s_mov_b64 s[48:49], 0x100
	s_cbranch_vccnz .Lkx_744
.LBB0_744:
	s_add_u32 s54, s42, s48
	s_addc_u32 s55, s43, s49
	s_add_u32 s52, s54, 0x100
	s_addc_u32 s53, s55, 0
	s_and_b64 s[50:51], s[46:47], exec
	s_cselect_b32 s51, s35, s53
	s_cselect_b32 s50, s82, s52
	s_add_u32 s48, s40, s48
	s_addc_u32 s49, s41, s49
	s_add_u32 s48, s48, 0x100
	s_addc_u32 s49, s49, 0
	s_and_b64 s[46:47], s[46:47], exec
	s_cselect_b32 s53, s31, s49
	s_cselect_b32 s52, s83, s48
	s_cselect_b32 s98, 1, 0
	s_add_u32 s56, s54, 0x10080
	ds_read_b128 v[150:153], v144
	ds_read_b128 v[154:157], v144 offset:1024
	ds_read_b128 v[158:161], v144 offset:2048
	ds_read_b128 v[162:165], v144 offset:3072
	ds_read_b128 v[166:169], v145
	ds_read_b128 v[170:173], v145 offset:1024
	ds_read_b128 v[174:177], v145 offset:2048
	ds_read_b128 v[178:181], v145 offset:3072
	s_addc_u32 s57, s55, 0
	s_add_i32 s93, s74, s60
	s_add_i32 m0, s61, 0xc000
	s_add_i32 s94, s61, 0xe000
	s_add_i32 s90, s93, 0x2000
	s_add_u32 s54, s52, 0x10000
	s_addc_u32 s55, s53, 0
	s_add_i32 s92, s75, s60
	s_add_i32 s91, s92, 0x2000
	s_add_i32 s89, 0, 0x18000
	s_add_i32 s88, 0, 0x1c000
	s_add_u32 s48, s50, 0x10000
	s_addc_u32 s49, s51, 0
	s_add_i32 s87, s89, s60
	s_add_i32 s85, s87, 0x2000
	s_add_u32 s46, s52, 0x10080
	s_addc_u32 s47, s53, 0
	s_add_i32 s86, s88, s60
	s_add_i32 s84, s86, 0x2000
	v_lshl_add_u64 v[138:139], s[56:57], 0, v[130:131]
	ds_read_b128 v[182:185], v146
	ds_read_b128 v[186:189], v146 offset:1024
	ds_read_b128 v[190:193], v146 offset:2048
	ds_read_b128 v[194:197], v146 offset:3072
	ds_read_b128 v[198:201], v146 offset:4096
	ds_read_b128 v[202:205], v146 offset:5120
	ds_read_b128 v[206:209], v146 offset:6144
	ds_read_b128 v[210:213], v146 offset:7168
	global_load_lds_dwordx4 v[138:139], off
	v_lshl_add_u64 v[138:139], s[56:57], 0, v[128:129]
	s_mov_b32 m0, s94
	s_nop 0
	global_load_lds_dwordx4 v[138:139], off
	s_waitcnt vmcnt(8)
	s_waitcnt lgkmcnt(0)
	s_cmp_lg_u32 s98, 0
	s_cbranch_scc0 .Lkv_nopf
	v_lshl_add_u32 v138, s18, 8, v141
	v_ashrrev_i32_e32 v139, 31, v138
	v_lshl_add_u64 v[138:139], v[138:139], 4, s[14:15]
	global_load_dwordx4 v[222:225], v[138:139], off
	global_load_dwordx4 v[226:229], v[138:139], off offset:256
	global_load_dwordx4 v[230:233], v[138:139], off offset:512
	global_load_dwordx4 v[234:237], v[138:139], off offset:768
	global_load_dwordx4 v[238:241], v[138:139], off offset:2048
	global_load_dwordx4 v[242:245], v[138:139], off offset:2304
	global_load_dwordx4 v[248:251], v[138:139], off offset:2560
	global_load_dwordx4 v[252:255], v[138:139], off offset:2816
.Lkv_nopf:
	s_barrier
	v_mfma_f32_16x16x32_bf16 v[124:127], v[150:153], v[182:185], v[124:127]
	v_mfma_f32_16x16x32_bf16 v[120:123], v[158:161], v[182:185], v[120:123]
	v_mfma_f32_16x16x32_bf16 v[108:111], v[150:153], v[190:193], v[108:111]
	v_mfma_f32_16x16x32_bf16 v[104:107], v[158:161], v[190:193], v[104:107]
	v_mfma_f32_16x16x32_bf16 v[92:95], v[150:153], v[198:201], v[92:95]
	v_mfma_f32_16x16x32_bf16 v[88:91], v[158:161], v[198:201], v[88:91]
	v_mfma_f32_16x16x32_bf16 v[76:79], v[150:153], v[206:209], v[76:79]
	v_mfma_f32_16x16x32_bf16 v[72:75], v[158:161], v[206:209], v[72:75]
	v_mfma_f32_16x16x32_bf16 v[124:127], v[154:157], v[186:189], v[124:127]
	v_mfma_f32_16x16x32_bf16 v[120:123], v[162:165], v[186:189], v[120:123]
	v_mfma_f32_16x16x32_bf16 v[108:111], v[154:157], v[194:197], v[108:111]
	v_mfma_f32_16x16x32_bf16 v[104:107], v[162:165], v[194:197], v[104:107]
	v_mfma_f32_16x16x32_bf16 v[92:95], v[154:157], v[202:205], v[92:95]
	v_mfma_f32_16x16x32_bf16 v[88:91], v[162:165], v[202:205], v[88:91]
	v_mfma_f32_16x16x32_bf16 v[76:79], v[154:157], v[210:213], v[76:79]
	v_mfma_f32_16x16x32_bf16 v[72:75], v[162:165], v[210:213], v[72:75]
	v_mfma_f32_16x16x32_bf16 v[116:119], v[166:169], v[182:185], v[116:119]
	v_mfma_f32_16x16x32_bf16 v[112:115], v[174:177], v[182:185], v[112:115]
	v_mfma_f32_16x16x32_bf16 v[100:103], v[166:169], v[190:193], v[100:103]
	v_mfma_f32_16x16x32_bf16 v[96:99], v[174:177], v[190:193], v[96:99]
	v_mfma_f32_16x16x32_bf16 v[84:87], v[166:169], v[198:201], v[84:87]
	v_mfma_f32_16x16x32_bf16 v[80:83], v[174:177], v[198:201], v[80:83]
	v_mfma_f32_16x16x32_bf16 v[68:71], v[166:169], v[206:209], v[68:71]
	v_mfma_f32_16x16x32_bf16 v[64:67], v[174:177], v[206:209], v[64:67]
	v_mfma_f32_16x16x32_bf16 v[116:119], v[170:173], v[186:189], v[116:119]
	v_mfma_f32_16x16x32_bf16 v[112:115], v[178:181], v[186:189], v[112:115]
	v_mfma_f32_16x16x32_bf16 v[100:103], v[170:173], v[194:197], v[100:103]
	v_mfma_f32_16x16x32_bf16 v[96:99], v[178:181], v[194:197], v[96:99]
	v_mfma_f32_16x16x32_bf16 v[84:87], v[170:173], v[202:205], v[84:87]
	v_mfma_f32_16x16x32_bf16 v[80:83], v[178:181], v[202:205], v[80:83]
	v_mfma_f32_16x16x32_bf16 v[68:71], v[170:173], v[210:213], v[68:71]
	v_mfma_f32_16x16x32_bf16 v[64:67], v[178:181], v[210:213], v[64:67]
	s_barrier
	s_mov_b32 m0, s93
	v_lshl_add_u64 v[138:139], s[52:53], 0, v[130:131]
	ds_read_b128 v[182:185], v146 offset:16384
	ds_read_b128 v[186:189], v146 offset:17408
	ds_read_b128 v[190:193], v146 offset:18432
	ds_read_b128 v[194:197], v146 offset:19456
	ds_read_b128 v[198:201], v146 offset:20480
	ds_read_b128 v[202:205], v146 offset:21504
	ds_read_b128 v[206:209], v146 offset:22528
	ds_read_b128 v[210:213], v146 offset:23552
	global_load_lds_dwordx4 v[138:139], off
	v_lshl_add_u64 v[214:215], s[52:53], 0, v[128:129]
	s_mov_b32 m0, s90
	v_lshl_add_u64 v[216:217], s[54:55], 0, v[130:131]
	global_load_lds_dwordx4 v[214:215], off
	s_mov_b32 m0, s92
	v_lshl_add_u64 v[218:219], s[50:51], 0, v[128:129]
	global_load_lds_dwordx4 v[216:217], off
	v_lshl_add_u64 v[216:217], s[54:55], 0, v[128:129]
	s_mov_b32 m0, s91
	s_nop 0
	global_load_lds_dwordx4 v[216:217], off
	v_lshl_add_u64 v[216:217], s[50:51], 0, v[130:131]
	s_mov_b32 m0, s61
	s_nop 0
	global_load_lds_dwordx4 v[216:217], off
	s_mov_b32 m0, s62
	s_nop 0
	global_load_lds_dwordx4 v[218:219], off
	s_waitcnt vmcnt(8)
	s_waitcnt lgkmcnt(0)
	s_barrier
	v_mfma_f32_16x16x32_bf16 v[60:63], v[150:153], v[182:185], v[60:63]
	v_mfma_f32_16x16x32_bf16 v[56:59], v[158:161], v[182:185], v[56:59]
	v_mfma_f32_16x16x32_bf16 v[44:47], v[150:153], v[190:193], v[44:47]
	v_mfma_f32_16x16x32_bf16 v[40:43], v[158:161], v[190:193], v[40:43]
	v_mfma_f32_16x16x32_bf16 v[28:31], v[150:153], v[198:201], v[28:31]
	v_mfma_f32_16x16x32_bf16 v[24:27], v[158:161], v[198:201], v[24:27]
	v_mfma_f32_16x16x32_bf16 v[12:15], v[150:153], v[206:209], v[12:15]
	v_mfma_f32_16x16x32_bf16 v[8:11], v[158:161], v[206:209], v[8:11]
	v_mfma_f32_16x16x32_bf16 v[60:63], v[154:157], v[186:189], v[60:63]
	v_mfma_f32_16x16x32_bf16 v[56:59], v[162:165], v[186:189], v[56:59]
	v_mfma_f32_16x16x32_bf16 v[44:47], v[154:157], v[194:197], v[44:47]
	v_mfma_f32_16x16x32_bf16 v[40:43], v[162:165], v[194:197], v[40:43]
	v_mfma_f32_16x16x32_bf16 v[28:31], v[154:157], v[202:205], v[28:31]
	v_mfma_f32_16x16x32_bf16 v[24:27], v[162:165], v[202:205], v[24:27]
	v_mfma_f32_16x16x32_bf16 v[12:15], v[154:157], v[210:213], v[12:15]
	v_mfma_f32_16x16x32_bf16 v[8:11], v[162:165], v[210:213], v[8:11]
	v_mfma_f32_16x16x32_bf16 v[52:55], v[166:169], v[182:185], v[52:55]
	v_mfma_f32_16x16x32_bf16 v[48:51], v[174:177], v[182:185], v[48:51]
	v_mfma_f32_16x16x32_bf16 v[36:39], v[166:169], v[190:193], v[36:39]
	v_mfma_f32_16x16x32_bf16 v[32:35], v[174:177], v[190:193], v[32:35]
	v_mfma_f32_16x16x32_bf16 v[20:23], v[166:169], v[198:201], v[20:23]
	v_mfma_f32_16x16x32_bf16 v[16:19], v[174:177], v[198:201], v[16:19]
	v_mfma_f32_16x16x32_bf16 v[4:7], v[166:169], v[206:209], v[4:7]
	v_mfma_f32_16x16x32_bf16 v[0:3], v[174:177], v[206:209], v[0:3]
	v_mfma_f32_16x16x32_bf16 v[52:55], v[170:173], v[186:189], v[52:55]
	v_mfma_f32_16x16x32_bf16 v[48:51], v[178:181], v[186:189], v[48:51]
	v_mfma_f32_16x16x32_bf16 v[36:39], v[170:173], v[194:197], v[36:39]
	v_mfma_f32_16x16x32_bf16 v[32:35], v[178:181], v[194:197], v[32:35]
	v_mfma_f32_16x16x32_bf16 v[20:23], v[170:173], v[202:205], v[20:23]
	v_mfma_f32_16x16x32_bf16 v[16:19], v[178:181], v[202:205], v[16:19]
	v_mfma_f32_16x16x32_bf16 v[4:7], v[170:173], v[210:213], v[4:7]
	v_mfma_f32_16x16x32_bf16 v[0:3], v[178:181], v[210:213], v[0:3]
	s_barrier
	v_add_u32_e32 v132, s89, v143
	ds_read_b128 v[150:153], v132
	ds_read_b128 v[154:157], v132 offset:1024
	ds_read_b128 v[158:161], v132 offset:2048
	ds_read_b128 v[162:165], v132 offset:3072
	v_add_u32_e32 v132, s88, v143
	ds_read_b128 v[166:169], v132
	ds_read_b128 v[170:173], v132 offset:1024
	ds_read_b128 v[174:177], v132 offset:2048
	ds_read_b128 v[178:181], v132 offset:3072
	s_mov_b32 m0, s63
	v_lshl_add_u64 v[220:221], s[48:49], 0, v[130:131]
	ds_read_b128 v[182:185], v146 offset:32768
	ds_read_b128 v[186:189], v146 offset:33792
	ds_read_b128 v[190:193], v146 offset:34816
	ds_read_b128 v[194:197], v146 offset:35840
	ds_read_b128 v[198:201], v146 offset:36864
	ds_read_b128 v[202:205], v146 offset:37888
	ds_read_b128 v[206:209], v146 offset:38912
	ds_read_b128 v[210:213], v146 offset:39936
	global_load_lds_dwordx4 v[220:221], off
	v_lshl_add_u64 v[220:221], s[48:49], 0, v[128:129]
	s_mov_b32 m0, s64
	s_nop 0
	global_load_lds_dwordx4 v[220:221], off
	s_waitcnt vmcnt(8)
	s_waitcnt lgkmcnt(0)
	s_barrier
	v_mfma_f32_16x16x32_bf16 v[124:127], v[150:153], v[182:185], v[124:127]
	v_mfma_f32_16x16x32_bf16 v[120:123], v[158:161], v[182:185], v[120:123]
	v_mfma_f32_16x16x32_bf16 v[108:111], v[150:153], v[190:193], v[108:111]
	v_mfma_f32_16x16x32_bf16 v[104:107], v[158:161], v[190:193], v[104:107]
	v_mfma_f32_16x16x32_bf16 v[92:95], v[150:153], v[198:201], v[92:95]
	v_mfma_f32_16x16x32_bf16 v[88:91], v[158:161], v[198:201], v[88:91]
	v_mfma_f32_16x16x32_bf16 v[76:79], v[150:153], v[206:209], v[76:79]
	v_mfma_f32_16x16x32_bf16 v[72:75], v[158:161], v[206:209], v[72:75]
	v_mfma_f32_16x16x32_bf16 v[124:127], v[154:157], v[186:189], v[124:127]
	v_mfma_f32_16x16x32_bf16 v[120:123], v[162:165], v[186:189], v[120:123]
	v_mfma_f32_16x16x32_bf16 v[108:111], v[154:157], v[194:197], v[108:111]
	v_mfma_f32_16x16x32_bf16 v[104:107], v[162:165], v[194:197], v[104:107]
	v_mfma_f32_16x16x32_bf16 v[92:95], v[154:157], v[202:205], v[92:95]
	v_mfma_f32_16x16x32_bf16 v[88:91], v[162:165], v[202:205], v[88:91]
	v_mfma_f32_16x16x32_bf16 v[76:79], v[154:157], v[210:213], v[76:79]
	v_mfma_f32_16x16x32_bf16 v[72:75], v[162:165], v[210:213], v[72:75]
	v_mfma_f32_16x16x32_bf16 v[116:119], v[166:169], v[182:185], v[116:119]
	v_mfma_f32_16x16x32_bf16 v[112:115], v[174:177], v[182:185], v[112:115]
	v_mfma_f32_16x16x32_bf16 v[100:103], v[166:169], v[190:193], v[100:103]
	v_mfma_f32_16x16x32_bf16 v[96:99], v[174:177], v[190:193], v[96:99]
	v_mfma_f32_16x16x32_bf16 v[84:87], v[166:169], v[198:201], v[84:87]
	v_mfma_f32_16x16x32_bf16 v[80:83], v[174:177], v[198:201], v[80:83]
	v_mfma_f32_16x16x32_bf16 v[68:71], v[166:169], v[206:209], v[68:71]
	v_mfma_f32_16x16x32_bf16 v[64:67], v[174:177], v[206:209], v[64:67]
	v_mfma_f32_16x16x32_bf16 v[116:119], v[170:173], v[186:189], v[116:119]
	v_mfma_f32_16x16x32_bf16 v[112:115], v[178:181], v[186:189], v[112:115]
	v_mfma_f32_16x16x32_bf16 v[100:103], v[170:173], v[194:197], v[100:103]
	v_mfma_f32_16x16x32_bf16 v[96:99], v[178:181], v[194:197], v[96:99]
	v_mfma_f32_16x16x32_bf16 v[84:87], v[170:173], v[202:205], v[84:87]
	v_mfma_f32_16x16x32_bf16 v[80:83], v[178:181], v[202:205], v[80:83]
	v_mfma_f32_16x16x32_bf16 v[68:71], v[170:173], v[210:213], v[68:71]
	v_mfma_f32_16x16x32_bf16 v[64:67], v[178:181], v[210:213], v[64:67]
	s_barrier
	s_mov_b32 m0, s87
	v_lshl_add_u64 v[138:139], v[138:139], 0, s[16:17]
	ds_read_b128 v[182:185], v146 offset:49152
	ds_read_b128 v[186:189], v146 offset:50176
	ds_read_b128 v[190:193], v146 offset:51200
	ds_read_b128 v[194:197], v146 offset:52224
	ds_read_b128 v[198:201], v146 offset:53248
	ds_read_b128 v[202:205], v146 offset:54272
	ds_read_b128 v[206:209], v146 offset:55296
	ds_read_b128 v[210:213], v146 offset:56320
	global_load_lds_dwordx4 v[138:139], off
	v_lshl_add_u64 v[138:139], v[214:215], 0, s[16:17]
	s_mov_b32 m0, s85
	s_nop 0
	global_load_lds_dwordx4 v[138:139], off
	v_lshl_add_u64 v[138:139], s[46:47], 0, v[130:131]
	s_mov_b32 m0, s86
	s_nop 0
	global_load_lds_dwordx4 v[138:139], off
	v_lshl_add_u64 v[138:139], s[46:47], 0, v[128:129]
	s_mov_b32 m0, s84
	s_nop 0
	global_load_lds_dwordx4 v[138:139], off
	v_lshl_add_u64 v[138:139], v[216:217], 0, s[16:17]
	s_mov_b32 m0, s70
	s_nop 0
	global_load_lds_dwordx4 v[138:139], off
	v_lshl_add_u64 v[138:139], v[218:219], 0, s[16:17]
	s_mov_b32 m0, s71
	s_nop 0
	global_load_lds_dwordx4 v[138:139], off
	s_waitcnt vmcnt(8)
	s_waitcnt lgkmcnt(0)
	s_barrier
	v_mfma_f32_16x16x32_bf16 v[60:63], v[150:153], v[182:185], v[60:63]
	v_mfma_f32_16x16x32_bf16 v[56:59], v[158:161], v[182:185], v[56:59]
	v_mfma_f32_16x16x32_bf16 v[44:47], v[150:153], v[190:193], v[44:47]
	v_mfma_f32_16x16x32_bf16 v[40:43], v[158:161], v[190:193], v[40:43]
	v_mfma_f32_16x16x32_bf16 v[28:31], v[150:153], v[198:201], v[28:31]
	v_mfma_f32_16x16x32_bf16 v[24:27], v[158:161], v[198:201], v[24:27]
	v_mfma_f32_16x16x32_bf16 v[12:15], v[150:153], v[206:209], v[12:15]
	v_mfma_f32_16x16x32_bf16 v[8:11], v[158:161], v[206:209], v[8:11]
	v_mfma_f32_16x16x32_bf16 v[60:63], v[154:157], v[186:189], v[60:63]
	v_mfma_f32_16x16x32_bf16 v[56:59], v[162:165], v[186:189], v[56:59]
	v_mfma_f32_16x16x32_bf16 v[44:47], v[154:157], v[194:197], v[44:47]
	v_mfma_f32_16x16x32_bf16 v[40:43], v[162:165], v[194:197], v[40:43]
	v_mfma_f32_16x16x32_bf16 v[28:31], v[154:157], v[202:205], v[28:31]
	v_mfma_f32_16x16x32_bf16 v[24:27], v[162:165], v[202:205], v[24:27]
	v_mfma_f32_16x16x32_bf16 v[12:15], v[154:157], v[210:213], v[12:15]
	v_mfma_f32_16x16x32_bf16 v[8:11], v[162:165], v[210:213], v[8:11]
	v_mfma_f32_16x16x32_bf16 v[52:55], v[166:169], v[182:185], v[52:55]
	v_mfma_f32_16x16x32_bf16 v[48:51], v[174:177], v[182:185], v[48:51]
	v_mfma_f32_16x16x32_bf16 v[36:39], v[166:169], v[190:193], v[36:39]
	v_mfma_f32_16x16x32_bf16 v[32:35], v[174:177], v[190:193], v[32:35]
	v_mfma_f32_16x16x32_bf16 v[20:23], v[166:169], v[198:201], v[20:23]
	v_mfma_f32_16x16x32_bf16 v[16:19], v[174:177], v[198:201], v[16:19]
	v_mfma_f32_16x16x32_bf16 v[4:7], v[166:169], v[206:209], v[4:7]
	v_mfma_f32_16x16x32_bf16 v[0:3], v[174:177], v[206:209], v[0:3]
	v_mfma_f32_16x16x32_bf16 v[52:55], v[170:173], v[186:189], v[52:55]
	v_mfma_f32_16x16x32_bf16 v[48:51], v[178:181], v[186:189], v[48:51]
	v_mfma_f32_16x16x32_bf16 v[36:39], v[170:173], v[194:197], v[36:39]
	v_mfma_f32_16x16x32_bf16 v[32:35], v[178:181], v[194:197], v[32:35]
	v_mfma_f32_16x16x32_bf16 v[20:23], v[170:173], v[202:205], v[20:23]
	v_mfma_f32_16x16x32_bf16 v[16:19], v[178:181], v[202:205], v[16:19]
	v_mfma_f32_16x16x32_bf16 v[4:7], v[170:173], v[210:213], v[4:7]
	v_mfma_f32_16x16x32_bf16 v[0:3], v[178:181], v[210:213], v[0:3]
	s_barrier
	s_andn2_b64 vcc, exec, s[44:45]
	s_mov_b64 s[46:47], -1
	s_mov_b64 s[44:45], 0
	s_mov_b64 s[48:49], 0x100
	s_cbranch_vccz .LBB0_744

.LBB0_770:
	s_add_u32 s81, s38, 0x100
	s_addc_u32 s82, s39, 0
	s_mov_b32 s83, -2
	ds_read_b128 v[84:87], v208
	ds_read_b128 v[100:103], v208 offset:1024
	ds_read_b128 v[120:123], v208 offset:2048
	ds_read_b128 v[140:143], v208 offset:3072
	ds_read_b128 v[144:147], v209
	ds_read_b128 v[148:151], v209 offset:1024
	ds_read_b128 v[152:155], v209 offset:2048
	ds_read_b128 v[170:173], v209 offset:3072
	s_add_u32 s6, s8, 0x100
	s_addc_u32 s7, s9, 0
	s_cmp_eq_u32 s83, 2
	s_cselect_b32 s41, s35, s7
	s_cselect_b32 s40, s34, s6
	s_cselect_b32 s39, s37, s82
	s_cselect_b32 s38, s36, s81
	s_add_i32 m0, s42, 0xc000
	ds_read_b128 v[174:177], v210
	ds_read_b128 v[178:181], v210 offset:1024
	ds_read_b128 v[182:185], v210 offset:2048
	ds_read_b128 v[186:189], v210 offset:3072
	ds_read_b128 v[190:193], v210 offset:4096
	ds_read_b128 v[194:197], v210 offset:5120
	ds_read_b128 v[198:201], v210 offset:6144
	ds_read_b128 v[202:205], v210 offset:7168
	global_load_lds_dwordx4 v162, s[8:9]
	s_add_i32 m0, s42, 0xe000
	s_nop 0
	global_load_lds_dwordx4 v164, s[8:9]
	s_waitcnt vmcnt(8)
	s_waitcnt lgkmcnt(0)
	s_barrier
	v_mfma_f32_16x16x32_bf16 v[136:139], v[84:87], v[174:177], 0
	v_mfma_f32_16x16x32_bf16 v[132:135], v[120:123], v[174:177], 0
	v_mfma_f32_16x16x32_bf16 v[116:119], v[84:87], v[182:185], 0
	v_mfma_f32_16x16x32_bf16 v[112:115], v[120:123], v[182:185], 0
	v_mfma_f32_16x16x32_bf16 v[96:99], v[84:87], v[190:193], 0
	v_mfma_f32_16x16x32_bf16 v[92:95], v[120:123], v[190:193], 0
	v_mfma_f32_16x16x32_bf16 v[76:79], v[84:87], v[198:201], 0
	v_mfma_f32_16x16x32_bf16 v[72:75], v[120:123], v[198:201], 0
	v_mfma_f32_16x16x32_bf16 v[136:139], v[100:103], v[178:181], v[136:139]
	v_mfma_f32_16x16x32_bf16 v[132:135], v[140:143], v[178:181], v[132:135]
	v_mfma_f32_16x16x32_bf16 v[116:119], v[100:103], v[186:189], v[116:119]
	v_mfma_f32_16x16x32_bf16 v[112:115], v[140:143], v[186:189], v[112:115]
	v_mfma_f32_16x16x32_bf16 v[96:99], v[100:103], v[194:197], v[96:99]
	v_mfma_f32_16x16x32_bf16 v[92:95], v[140:143], v[194:197], v[92:95]
	v_mfma_f32_16x16x32_bf16 v[76:79], v[100:103], v[202:205], v[76:79]
	v_mfma_f32_16x16x32_bf16 v[72:75], v[140:143], v[202:205], v[72:75]
	v_mfma_f32_16x16x32_bf16 v[128:131], v[144:147], v[174:177], 0
	v_mfma_f32_16x16x32_bf16 v[124:127], v[152:155], v[174:177], 0
	v_mfma_f32_16x16x32_bf16 v[108:111], v[144:147], v[182:185], 0
	v_mfma_f32_16x16x32_bf16 v[104:107], v[152:155], v[182:185], 0
	v_mfma_f32_16x16x32_bf16 v[88:91], v[144:147], v[190:193], 0
	v_mfma_f32_16x16x32_bf16 v[80:83], v[152:155], v[190:193], 0
	v_mfma_f32_16x16x32_bf16 v[68:71], v[144:147], v[198:201], 0
	v_mfma_f32_16x16x32_bf16 v[64:67], v[152:155], v[198:201], 0
	v_mfma_f32_16x16x32_bf16 v[128:131], v[148:151], v[178:181], v[128:131]
	v_mfma_f32_16x16x32_bf16 v[124:127], v[170:173], v[178:181], v[124:127]
	v_mfma_f32_16x16x32_bf16 v[108:111], v[148:151], v[186:189], v[108:111]
	v_mfma_f32_16x16x32_bf16 v[104:107], v[170:173], v[186:189], v[104:107]
	v_mfma_f32_16x16x32_bf16 v[88:91], v[148:151], v[194:197], v[88:91]
	v_mfma_f32_16x16x32_bf16 v[80:83], v[170:173], v[194:197], v[80:83]
	v_mfma_f32_16x16x32_bf16 v[68:71], v[148:151], v[202:205], v[68:71]
	v_mfma_f32_16x16x32_bf16 v[64:67], v[170:173], v[202:205], v[64:67]
	s_barrier
	s_add_i32 s8, s61, s3
	s_add_u32 s98, s38, 0x80
	s_addc_u32 s99, s39, 0
	s_mov_b32 m0, s8
	ds_read_b128 v[174:177], v210 offset:16384
	ds_read_b128 v[178:181], v210 offset:17408
	ds_read_b128 v[182:185], v210 offset:18432
	ds_read_b128 v[186:189], v210 offset:19456
	ds_read_b128 v[190:193], v210 offset:20480
	ds_read_b128 v[194:197], v210 offset:21504
	ds_read_b128 v[198:201], v210 offset:22528
	ds_read_b128 v[202:205], v210 offset:23552
	global_load_lds_dwordx4 v156, s[38:39]
	s_add_i32 m0, s8, 0x2000
	s_add_u32 s8, s38, 0x18000
	s_addc_u32 s9, s39, 0
	s_add_i32 s84, s62, s3
	global_load_lds_dwordx4 v158, s[38:39]
	s_mov_b32 m0, s84
	s_add_u32 s100, s40, 0x80
	s_addc_u32 s101, s41, 0
	global_load_lds_dwordx4 v156, s[8:9]
	s_add_i32 m0, s84, 0x2000
	s_nop 0
	global_load_lds_dwordx4 v158, s[8:9]
	s_mov_b32 m0, s42
	s_nop 0
	global_load_lds_dwordx4 v156, s[40:41]
	s_mov_b32 m0, s43
	s_nop 0
	global_load_lds_dwordx4 v158, s[40:41]
	s_waitcnt vmcnt(8)
	s_waitcnt lgkmcnt(0)
	s_barrier
	v_mfma_f32_16x16x32_bf16 v[60:63], v[84:87], v[174:177], 0
	v_mfma_f32_16x16x32_bf16 v[56:59], v[120:123], v[174:177], 0
	v_mfma_f32_16x16x32_bf16 v[44:47], v[84:87], v[182:185], 0
	v_mfma_f32_16x16x32_bf16 v[40:43], v[120:123], v[182:185], 0
	v_mfma_f32_16x16x32_bf16 v[28:31], v[84:87], v[190:193], 0
	v_mfma_f32_16x16x32_bf16 v[24:27], v[120:123], v[190:193], 0
	v_mfma_f32_16x16x32_bf16 v[12:15], v[84:87], v[198:201], 0
	v_mfma_f32_16x16x32_bf16 v[8:11], v[120:123], v[198:201], 0
	v_mfma_f32_16x16x32_bf16 v[60:63], v[100:103], v[178:181], v[60:63]
	v_mfma_f32_16x16x32_bf16 v[56:59], v[140:143], v[178:181], v[56:59]
	v_mfma_f32_16x16x32_bf16 v[44:47], v[100:103], v[186:189], v[44:47]
	v_mfma_f32_16x16x32_bf16 v[40:43], v[140:143], v[186:189], v[40:43]
	v_mfma_f32_16x16x32_bf16 v[28:31], v[100:103], v[194:197], v[28:31]
	v_mfma_f32_16x16x32_bf16 v[24:27], v[140:143], v[194:197], v[24:27]
	v_mfma_f32_16x16x32_bf16 v[12:15], v[100:103], v[202:205], v[12:15]
	v_mfma_f32_16x16x32_bf16 v[8:11], v[140:143], v[202:205], v[8:11]
	v_mfma_f32_16x16x32_bf16 v[52:55], v[144:147], v[174:177], 0
	v_mfma_f32_16x16x32_bf16 v[48:51], v[152:155], v[174:177], 0
	v_mfma_f32_16x16x32_bf16 v[36:39], v[144:147], v[182:185], 0
	v_mfma_f32_16x16x32_bf16 v[32:35], v[152:155], v[182:185], 0
	v_mfma_f32_16x16x32_bf16 v[20:23], v[144:147], v[190:193], 0
	v_mfma_f32_16x16x32_bf16 v[16:19], v[152:155], v[190:193], 0
	v_mfma_f32_16x16x32_bf16 v[4:7], v[144:147], v[198:201], 0
	v_mfma_f32_16x16x32_bf16 v[0:3], v[152:155], v[198:201], 0
	v_mfma_f32_16x16x32_bf16 v[52:55], v[148:151], v[178:181], v[52:55]
	v_mfma_f32_16x16x32_bf16 v[48:51], v[170:173], v[178:181], v[48:51]
	v_mfma_f32_16x16x32_bf16 v[36:39], v[148:151], v[186:189], v[36:39]
	v_mfma_f32_16x16x32_bf16 v[32:35], v[170:173], v[186:189], v[32:35]
	v_mfma_f32_16x16x32_bf16 v[20:23], v[148:151], v[194:197], v[20:23]
	v_mfma_f32_16x16x32_bf16 v[16:19], v[170:173], v[194:197], v[16:19]
	v_mfma_f32_16x16x32_bf16 v[4:7], v[148:151], v[202:205], v[4:7]
	v_mfma_f32_16x16x32_bf16 v[0:3], v[170:173], v[202:205], v[0:3]
	s_barrier
	s_add_i32 s84, 0, 0x18000
	s_add_i32 s85, 0, 0x1c000
	v_add_u32_e32 v140, s84, v207
	v_add_u32_e32 v160, s85, v207
	ds_read_b128 v[84:87], v140
	ds_read_b128 v[100:103], v140 offset:1024
	ds_read_b128 v[120:123], v140 offset:2048
	ds_read_b128 v[140:143], v140 offset:3072
	ds_read_b128 v[144:147], v160
	ds_read_b128 v[148:151], v160 offset:1024
	ds_read_b128 v[152:155], v160 offset:2048
	ds_read_b128 v[170:173], v160 offset:3072
	s_add_u32 s8, s40, 0x18000
	s_addc_u32 s9, s41, 0
	s_mov_b32 m0, s44
	ds_read_b128 v[174:177], v210 offset:32768
	ds_read_b128 v[178:181], v210 offset:33792
	ds_read_b128 v[182:185], v210 offset:34816
	ds_read_b128 v[186:189], v210 offset:35840
	ds_read_b128 v[190:193], v210 offset:36864
	ds_read_b128 v[194:197], v210 offset:37888
	ds_read_b128 v[198:201], v210 offset:38912
	ds_read_b128 v[202:205], v210 offset:39936
	global_load_lds_dwordx4 v156, s[8:9]
	s_mov_b32 m0, s45
	s_nop 0
	global_load_lds_dwordx4 v158, s[8:9]
	s_waitcnt vmcnt(8)
	s_waitcnt lgkmcnt(0)
	s_barrier
	v_mfma_f32_16x16x32_bf16 v[136:139], v[84:87], v[174:177], v[136:139]
	v_mfma_f32_16x16x32_bf16 v[132:135], v[120:123], v[174:177], v[132:135]
	v_mfma_f32_16x16x32_bf16 v[116:119], v[84:87], v[182:185], v[116:119]
	v_mfma_f32_16x16x32_bf16 v[112:115], v[120:123], v[182:185], v[112:115]
	v_mfma_f32_16x16x32_bf16 v[96:99], v[84:87], v[190:193], v[96:99]
	v_mfma_f32_16x16x32_bf16 v[92:95], v[120:123], v[190:193], v[92:95]
	v_mfma_f32_16x16x32_bf16 v[76:79], v[84:87], v[198:201], v[76:79]
	v_mfma_f32_16x16x32_bf16 v[72:75], v[120:123], v[198:201], v[72:75]
	v_mfma_f32_16x16x32_bf16 v[136:139], v[100:103], v[178:181], v[136:139]
	v_mfma_f32_16x16x32_bf16 v[132:135], v[140:143], v[178:181], v[132:135]
	v_mfma_f32_16x16x32_bf16 v[116:119], v[100:103], v[186:189], v[116:119]
	v_mfma_f32_16x16x32_bf16 v[112:115], v[140:143], v[186:189], v[112:115]
	v_mfma_f32_16x16x32_bf16 v[96:99], v[100:103], v[194:197], v[96:99]
	v_mfma_f32_16x16x32_bf16 v[92:95], v[140:143], v[194:197], v[92:95]
	v_mfma_f32_16x16x32_bf16 v[76:79], v[100:103], v[202:205], v[76:79]
	v_mfma_f32_16x16x32_bf16 v[72:75], v[140:143], v[202:205], v[72:75]
	v_mfma_f32_16x16x32_bf16 v[128:131], v[144:147], v[174:177], v[128:131]
	v_mfma_f32_16x16x32_bf16 v[124:127], v[152:155], v[174:177], v[124:127]
	v_mfma_f32_16x16x32_bf16 v[108:111], v[144:147], v[182:185], v[108:111]
	v_mfma_f32_16x16x32_bf16 v[104:107], v[152:155], v[182:185], v[104:107]
	v_mfma_f32_16x16x32_bf16 v[88:91], v[144:147], v[190:193], v[88:91]
	v_mfma_f32_16x16x32_bf16 v[80:83], v[152:155], v[190:193], v[80:83]
	v_mfma_f32_16x16x32_bf16 v[68:71], v[144:147], v[198:201], v[68:71]
	v_mfma_f32_16x16x32_bf16 v[64:67], v[152:155], v[198:201], v[64:67]
	v_mfma_f32_16x16x32_bf16 v[128:131], v[148:151], v[178:181], v[128:131]
	v_mfma_f32_16x16x32_bf16 v[124:127], v[170:173], v[178:181], v[124:127]
	v_mfma_f32_16x16x32_bf16 v[108:111], v[148:151], v[186:189], v[108:111]
	v_mfma_f32_16x16x32_bf16 v[104:107], v[170:173], v[186:189], v[104:107]
	v_mfma_f32_16x16x32_bf16 v[88:91], v[148:151], v[194:197], v[88:91]
	v_mfma_f32_16x16x32_bf16 v[80:83], v[170:173], v[194:197], v[80:83]
	v_mfma_f32_16x16x32_bf16 v[68:71], v[148:151], v[202:205], v[68:71]
	v_mfma_f32_16x16x32_bf16 v[64:67], v[170:173], v[202:205], v[64:67]
	s_barrier
	s_add_i32 s8, s84, s3
	s_mov_b32 m0, s8
	ds_read_b128 v[174:177], v210 offset:49152
	ds_read_b128 v[178:181], v210 offset:50176
	ds_read_b128 v[182:185], v210 offset:51200
	ds_read_b128 v[186:189], v210 offset:52224
	ds_read_b128 v[190:193], v210 offset:53248
	ds_read_b128 v[194:197], v210 offset:54272
	ds_read_b128 v[198:201], v210 offset:55296
	ds_read_b128 v[202:205], v210 offset:56320
	global_load_lds_dwordx4 v156, s[98:99]
	s_add_i32 m0, s8, 0x2000
	s_add_u32 s8, s38, 0x18080
	s_addc_u32 s9, s39, 0
	s_add_i32 s38, s85, s3
	global_load_lds_dwordx4 v158, s[98:99]
	s_mov_b32 m0, s38
	s_nop 0
	global_load_lds_dwordx4 v156, s[8:9]
	s_add_i32 m0, s38, 0x2000
	s_nop 0
	global_load_lds_dwordx4 v158, s[8:9]
	s_mov_b32 m0, s51
	s_nop 0
	global_load_lds_dwordx4 v156, s[100:101]
	s_mov_b32 m0, s52
	s_nop 0
	global_load_lds_dwordx4 v158, s[100:101]
	s_waitcnt vmcnt(8)
	s_waitcnt lgkmcnt(0)
	s_barrier
	v_mfma_f32_16x16x32_bf16 v[60:63], v[84:87], v[174:177], v[60:63]
	v_mfma_f32_16x16x32_bf16 v[56:59], v[120:123], v[174:177], v[56:59]
	v_mfma_f32_16x16x32_bf16 v[44:47], v[84:87], v[182:185], v[44:47]
	v_mfma_f32_16x16x32_bf16 v[40:43], v[120:123], v[182:185], v[40:43]
	v_mfma_f32_16x16x32_bf16 v[28:31], v[84:87], v[190:193], v[28:31]
	v_mfma_f32_16x16x32_bf16 v[24:27], v[120:123], v[190:193], v[24:27]
	v_mfma_f32_16x16x32_bf16 v[12:15], v[84:87], v[198:201], v[12:15]
	v_mfma_f32_16x16x32_bf16 v[8:11], v[120:123], v[198:201], v[8:11]
	v_mfma_f32_16x16x32_bf16 v[60:63], v[100:103], v[178:181], v[60:63]
	v_mfma_f32_16x16x32_bf16 v[56:59], v[140:143], v[178:181], v[56:59]
	v_mfma_f32_16x16x32_bf16 v[44:47], v[100:103], v[186:189], v[44:47]
	v_mfma_f32_16x16x32_bf16 v[40:43], v[140:143], v[186:189], v[40:43]
	v_mfma_f32_16x16x32_bf16 v[28:31], v[100:103], v[194:197], v[28:31]
	v_mfma_f32_16x16x32_bf16 v[24:27], v[140:143], v[194:197], v[24:27]
	v_mfma_f32_16x16x32_bf16 v[12:15], v[100:103], v[202:205], v[12:15]
	v_mfma_f32_16x16x32_bf16 v[8:11], v[140:143], v[202:205], v[8:11]
	v_mfma_f32_16x16x32_bf16 v[52:55], v[144:147], v[174:177], v[52:55]
	v_mfma_f32_16x16x32_bf16 v[48:51], v[152:155], v[174:177], v[48:51]
	v_mfma_f32_16x16x32_bf16 v[36:39], v[144:147], v[182:185], v[36:39]
	v_mfma_f32_16x16x32_bf16 v[32:35], v[152:155], v[182:185], v[32:35]
	v_mfma_f32_16x16x32_bf16 v[20:23], v[144:147], v[190:193], v[20:23]
	v_mfma_f32_16x16x32_bf16 v[16:19], v[152:155], v[190:193], v[16:19]
	v_mfma_f32_16x16x32_bf16 v[4:7], v[144:147], v[198:201], v[4:7]
	v_mfma_f32_16x16x32_bf16 v[0:3], v[152:155], v[198:201], v[0:3]
	v_mfma_f32_16x16x32_bf16 v[52:55], v[148:151], v[178:181], v[52:55]
	v_mfma_f32_16x16x32_bf16 v[48:51], v[170:173], v[178:181], v[48:51]
	v_mfma_f32_16x16x32_bf16 v[36:39], v[148:151], v[186:189], v[36:39]
	v_mfma_f32_16x16x32_bf16 v[32:35], v[170:173], v[186:189], v[32:35]
	v_mfma_f32_16x16x32_bf16 v[20:23], v[148:151], v[194:197], v[20:23]
	v_mfma_f32_16x16x32_bf16 v[16:19], v[170:173], v[194:197], v[16:19]
	v_mfma_f32_16x16x32_bf16 v[4:7], v[148:151], v[202:205], v[4:7]
	v_mfma_f32_16x16x32_bf16 v[0:3], v[170:173], v[202:205], v[0:3]
	s_barrier
	s_add_i32 s83, s83, 2
	s_add_u32 s81, s81, 0x100
	s_addc_u32 s82, s82, 0
	s_cmp_gt_u32 s83, 3
	s_mov_b64 s[8:9], s[6:7]
	s_cbranch_scc1 .Lkx_771
.LBB0_771:
	ds_read_b128 v[84:87], v208
	ds_read_b128 v[100:103], v208 offset:1024
	ds_read_b128 v[120:123], v208 offset:2048
	ds_read_b128 v[140:143], v208 offset:3072
	ds_read_b128 v[144:147], v209
	ds_read_b128 v[148:151], v209 offset:1024
	ds_read_b128 v[152:155], v209 offset:2048
	ds_read_b128 v[170:173], v209 offset:3072
	s_add_u32 s6, s8, 0x100
	s_addc_u32 s7, s9, 0
	s_cmp_eq_u32 s83, 2
	s_cselect_b32 s41, s35, s7
	s_cselect_b32 s40, s34, s6
	s_cselect_b32 s39, s37, s82
	s_cselect_b32 s38, s36, s81
	s_add_i32 m0, s42, 0xc000
	ds_read_b128 v[174:177], v210
	ds_read_b128 v[178:181], v210 offset:1024
	ds_read_b128 v[182:185], v210 offset:2048
	ds_read_b128 v[186:189], v210 offset:3072
	ds_read_b128 v[190:193], v210 offset:4096
	ds_read_b128 v[194:197], v210 offset:5120
	ds_read_b128 v[198:201], v210 offset:6144
	ds_read_b128 v[202:205], v210 offset:7168
	global_load_lds_dwordx4 v162, s[8:9]
	s_add_i32 m0, s42, 0xe000
	s_nop 0
	global_load_lds_dwordx4 v164, s[8:9]
	s_waitcnt vmcnt(8)
	s_waitcnt lgkmcnt(0)
	s_barrier
	v_mfma_f32_16x16x32_bf16 v[136:139], v[84:87], v[174:177], v[136:139]
	v_mfma_f32_16x16x32_bf16 v[132:135], v[120:123], v[174:177], v[132:135]
	v_mfma_f32_16x16x32_bf16 v[116:119], v[84:87], v[182:185], v[116:119]
	v_mfma_f32_16x16x32_bf16 v[112:115], v[120:123], v[182:185], v[112:115]
	v_mfma_f32_16x16x32_bf16 v[96:99], v[84:87], v[190:193], v[96:99]
	v_mfma_f32_16x16x32_bf16 v[92:95], v[120:123], v[190:193], v[92:95]
	v_mfma_f32_16x16x32_bf16 v[76:79], v[84:87], v[198:201], v[76:79]
	v_mfma_f32_16x16x32_bf16 v[72:75], v[120:123], v[198:201], v[72:75]
	v_mfma_f32_16x16x32_bf16 v[136:139], v[100:103], v[178:181], v[136:139]
	v_mfma_f32_16x16x32_bf16 v[132:135], v[140:143], v[178:181], v[132:135]
	v_mfma_f32_16x16x32_bf16 v[116:119], v[100:103], v[186:189], v[116:119]
	v_mfma_f32_16x16x32_bf16 v[112:115], v[140:143], v[186:189], v[112:115]
	v_mfma_f32_16x16x32_bf16 v[96:99], v[100:103], v[194:197], v[96:99]
	v_mfma_f32_16x16x32_bf16 v[92:95], v[140:143], v[194:197], v[92:95]
	v_mfma_f32_16x16x32_bf16 v[76:79], v[100:103], v[202:205], v[76:79]
	v_mfma_f32_16x16x32_bf16 v[72:75], v[140:143], v[202:205], v[72:75]
	v_mfma_f32_16x16x32_bf16 v[128:131], v[144:147], v[174:177], v[128:131]
	v_mfma_f32_16x16x32_bf16 v[124:127], v[152:155], v[174:177], v[124:127]
	v_mfma_f32_16x16x32_bf16 v[108:111], v[144:147], v[182:185], v[108:111]
	v_mfma_f32_16x16x32_bf16 v[104:107], v[152:155], v[182:185], v[104:107]
	v_mfma_f32_16x16x32_bf16 v[88:91], v[144:147], v[190:193], v[88:91]
	v_mfma_f32_16x16x32_bf16 v[80:83], v[152:155], v[190:193], v[80:83]
	v_mfma_f32_16x16x32_bf16 v[68:71], v[144:147], v[198:201], v[68:71]
	v_mfma_f32_16x16x32_bf16 v[64:67], v[152:155], v[198:201], v[64:67]
	v_mfma_f32_16x16x32_bf16 v[128:131], v[148:151], v[178:181], v[128:131]
	v_mfma_f32_16x16x32_bf16 v[124:127], v[170:173], v[178:181], v[124:127]
	v_mfma_f32_16x16x32_bf16 v[108:111], v[148:151], v[186:189], v[108:111]
	v_mfma_f32_16x16x32_bf16 v[104:107], v[170:173], v[186:189], v[104:107]
	v_mfma_f32_16x16x32_bf16 v[88:91], v[148:151], v[194:197], v[88:91]
	v_mfma_f32_16x16x32_bf16 v[80:83], v[170:173], v[194:197], v[80:83]
	v_mfma_f32_16x16x32_bf16 v[68:71], v[148:151], v[202:205], v[68:71]
	v_mfma_f32_16x16x32_bf16 v[64:67], v[170:173], v[202:205], v[64:67]
	s_barrier
	s_add_i32 s8, s61, s3
	s_add_u32 s98, s38, 0x80
	s_addc_u32 s99, s39, 0
	s_mov_b32 m0, s8
	ds_read_b128 v[174:177], v210 offset:16384
	ds_read_b128 v[178:181], v210 offset:17408
	ds_read_b128 v[182:185], v210 offset:18432
	ds_read_b128 v[186:189], v210 offset:19456
	ds_read_b128 v[190:193], v210 offset:20480
	ds_read_b128 v[194:197], v210 offset:21504
	ds_read_b128 v[198:201], v210 offset:22528
	ds_read_b128 v[202:205], v210 offset:23552
	global_load_lds_dwordx4 v156, s[38:39]
	s_add_i32 m0, s8, 0x2000
	s_add_u32 s8, s38, 0x18000
	s_addc_u32 s9, s39, 0
	s_add_i32 s84, s62, s3
	global_load_lds_dwordx4 v158, s[38:39]
	s_mov_b32 m0, s84
	s_add_u32 s100, s40, 0x80
	s_addc_u32 s101, s41, 0
	global_load_lds_dwordx4 v156, s[8:9]
	s_add_i32 m0, s84, 0x2000
	s_nop 0
	global_load_lds_dwordx4 v158, s[8:9]
	s_mov_b32 m0, s42
	s_nop 0
	global_load_lds_dwordx4 v156, s[40:41]
	s_mov_b32 m0, s43
	s_nop 0
	global_load_lds_dwordx4 v158, s[40:41]
	s_waitcnt vmcnt(8)
	s_waitcnt lgkmcnt(0)
	s_barrier
	v_mfma_f32_16x16x32_bf16 v[60:63], v[84:87], v[174:177], v[60:63]
	v_mfma_f32_16x16x32_bf16 v[56:59], v[120:123], v[174:177], v[56:59]
	v_mfma_f32_16x16x32_bf16 v[44:47], v[84:87], v[182:185], v[44:47]
	v_mfma_f32_16x16x32_bf16 v[40:43], v[120:123], v[182:185], v[40:43]
	v_mfma_f32_16x16x32_bf16 v[28:31], v[84:87], v[190:193], v[28:31]
	v_mfma_f32_16x16x32_bf16 v[24:27], v[120:123], v[190:193], v[24:27]
	v_mfma_f32_16x16x32_bf16 v[12:15], v[84:87], v[198:201], v[12:15]
	v_mfma_f32_16x16x32_bf16 v[8:11], v[120:123], v[198:201], v[8:11]
	v_mfma_f32_16x16x32_bf16 v[60:63], v[100:103], v[178:181], v[60:63]
	v_mfma_f32_16x16x32_bf16 v[56:59], v[140:143], v[178:181], v[56:59]
	v_mfma_f32_16x16x32_bf16 v[44:47], v[100:103], v[186:189], v[44:47]
	v_mfma_f32_16x16x32_bf16 v[40:43], v[140:143], v[186:189], v[40:43]
	v_mfma_f32_16x16x32_bf16 v[28:31], v[100:103], v[194:197], v[28:31]
	v_mfma_f32_16x16x32_bf16 v[24:27], v[140:143], v[194:197], v[24:27]
	v_mfma_f32_16x16x32_bf16 v[12:15], v[100:103], v[202:205], v[12:15]
	v_mfma_f32_16x16x32_bf16 v[8:11], v[140:143], v[202:205], v[8:11]
	v_mfma_f32_16x16x32_bf16 v[52:55], v[144:147], v[174:177], v[52:55]
	v_mfma_f32_16x16x32_bf16 v[48:51], v[152:155], v[174:177], v[48:51]
	v_mfma_f32_16x16x32_bf16 v[36:39], v[144:147], v[182:185], v[36:39]
	v_mfma_f32_16x16x32_bf16 v[32:35], v[152:155], v[182:185], v[32:35]
	v_mfma_f32_16x16x32_bf16 v[20:23], v[144:147], v[190:193], v[20:23]
	v_mfma_f32_16x16x32_bf16 v[16:19], v[152:155], v[190:193], v[16:19]
	v_mfma_f32_16x16x32_bf16 v[4:7], v[144:147], v[198:201], v[4:7]
	v_mfma_f32_16x16x32_bf16 v[0:3], v[152:155], v[198:201], v[0:3]
	v_mfma_f32_16x16x32_bf16 v[52:55], v[148:151], v[178:181], v[52:55]
	v_mfma_f32_16x16x32_bf16 v[48:51], v[170:173], v[178:181], v[48:51]
	v_mfma_f32_16x16x32_bf16 v[36:39], v[148:151], v[186:189], v[36:39]
	v_mfma_f32_16x16x32_bf16 v[32:35], v[170:173], v[186:189], v[32:35]
	v_mfma_f32_16x16x32_bf16 v[20:23], v[148:151], v[194:197], v[20:23]
	v_mfma_f32_16x16x32_bf16 v[16:19], v[170:173], v[194:197], v[16:19]
	v_mfma_f32_16x16x32_bf16 v[4:7], v[148:151], v[202:205], v[4:7]
	v_mfma_f32_16x16x32_bf16 v[0:3], v[170:173], v[202:205], v[0:3]
	s_barrier
	s_add_i32 s84, 0, 0x18000
	s_add_i32 s85, 0, 0x1c000
	v_add_u32_e32 v140, s84, v207
	v_add_u32_e32 v160, s85, v207
	ds_read_b128 v[84:87], v140
	ds_read_b128 v[100:103], v140 offset:1024
	ds_read_b128 v[120:123], v140 offset:2048
	ds_read_b128 v[140:143], v140 offset:3072
	ds_read_b128 v[144:147], v160
	ds_read_b128 v[148:151], v160 offset:1024
	ds_read_b128 v[152:155], v160 offset:2048
	ds_read_b128 v[170:173], v160 offset:3072
	s_add_u32 s8, s40, 0x18000
	s_addc_u32 s9, s41, 0
	s_mov_b32 m0, s44
	ds_read_b128 v[174:177], v210 offset:32768
	ds_read_b128 v[178:181], v210 offset:33792
	ds_read_b128 v[182:185], v210 offset:34816
	ds_read_b128 v[186:189], v210 offset:35840
	ds_read_b128 v[190:193], v210 offset:36864
	ds_read_b128 v[194:197], v210 offset:37888
	ds_read_b128 v[198:201], v210 offset:38912
	ds_read_b128 v[202:205], v210 offset:39936
	global_load_lds_dwordx4 v156, s[8:9]
	s_mov_b32 m0, s45
	s_nop 0
	global_load_lds_dwordx4 v158, s[8:9]
	s_waitcnt vmcnt(8)
	s_waitcnt lgkmcnt(0)
	s_barrier
	v_mfma_f32_16x16x32_bf16 v[136:139], v[84:87], v[174:177], v[136:139]
	v_mfma_f32_16x16x32_bf16 v[132:135], v[120:123], v[174:177], v[132:135]
	v_mfma_f32_16x16x32_bf16 v[116:119], v[84:87], v[182:185], v[116:119]
	v_mfma_f32_16x16x32_bf16 v[112:115], v[120:123], v[182:185], v[112:115]
	v_mfma_f32_16x16x32_bf16 v[96:99], v[84:87], v[190:193], v[96:99]
	v_mfma_f32_16x16x32_bf16 v[92:95], v[120:123], v[190:193], v[92:95]
	v_mfma_f32_16x16x32_bf16 v[76:79], v[84:87], v[198:201], v[76:79]
	v_mfma_f32_16x16x32_bf16 v[72:75], v[120:123], v[198:201], v[72:75]
	v_mfma_f32_16x16x32_bf16 v[136:139], v[100:103], v[178:181], v[136:139]
	v_mfma_f32_16x16x32_bf16 v[132:135], v[140:143], v[178:181], v[132:135]
	v_mfma_f32_16x16x32_bf16 v[116:119], v[100:103], v[186:189], v[116:119]
	v_mfma_f32_16x16x32_bf16 v[112:115], v[140:143], v[186:189], v[112:115]
	v_mfma_f32_16x16x32_bf16 v[96:99], v[100:103], v[194:197], v[96:99]
	v_mfma_f32_16x16x32_bf16 v[92:95], v[140:143], v[194:197], v[92:95]
	v_mfma_f32_16x16x32_bf16 v[76:79], v[100:103], v[202:205], v[76:79]
	v_mfma_f32_16x16x32_bf16 v[72:75], v[140:143], v[202:205], v[72:75]
	v_mfma_f32_16x16x32_bf16 v[128:131], v[144:147], v[174:177], v[128:131]
	v_mfma_f32_16x16x32_bf16 v[124:127], v[152:155], v[174:177], v[124:127]
	v_mfma_f32_16x16x32_bf16 v[108:111], v[144:147], v[182:185], v[108:111]
	v_mfma_f32_16x16x32_bf16 v[104:107], v[152:155], v[182:185], v[104:107]
	v_mfma_f32_16x16x32_bf16 v[88:91], v[144:147], v[190:193], v[88:91]
	v_mfma_f32_16x16x32_bf16 v[80:83], v[152:155], v[190:193], v[80:83]
	v_mfma_f32_16x16x32_bf16 v[68:71], v[144:147], v[198:201], v[68:71]
	v_mfma_f32_16x16x32_bf16 v[64:67], v[152:155], v[198:201], v[64:67]
	v_mfma_f32_16x16x32_bf16 v[128:131], v[148:151], v[178:181], v[128:131]
	v_mfma_f32_16x16x32_bf16 v[124:127], v[170:173], v[178:181], v[124:127]
	v_mfma_f32_16x16x32_bf16 v[108:111], v[148:151], v[186:189], v[108:111]
	v_mfma_f32_16x16x32_bf16 v[104:107], v[170:173], v[186:189], v[104:107]
	v_mfma_f32_16x16x32_bf16 v[88:91], v[148:151], v[194:197], v[88:91]
	v_mfma_f32_16x16x32_bf16 v[80:83], v[170:173], v[194:197], v[80:83]
	v_mfma_f32_16x16x32_bf16 v[68:71], v[148:151], v[202:205], v[68:71]
	v_mfma_f32_16x16x32_bf16 v[64:67], v[170:173], v[202:205], v[64:67]
	s_barrier
	s_add_i32 s8, s84, s3
	s_mov_b32 m0, s8
	ds_read_b128 v[174:177], v210 offset:49152
	ds_read_b128 v[178:181], v210 offset:50176
	ds_read_b128 v[182:185], v210 offset:51200
	ds_read_b128 v[186:189], v210 offset:52224
	ds_read_b128 v[190:193], v210 offset:53248
	ds_read_b128 v[194:197], v210 offset:54272
	ds_read_b128 v[198:201], v210 offset:55296
	ds_read_b128 v[202:205], v210 offset:56320
	global_load_lds_dwordx4 v156, s[98:99]
	s_add_i32 m0, s8, 0x2000
	s_add_u32 s8, s38, 0x18080
	s_addc_u32 s9, s39, 0
	s_add_i32 s38, s85, s3
	global_load_lds_dwordx4 v158, s[98:99]
	s_mov_b32 m0, s38
	s_nop 0
	global_load_lds_dwordx4 v156, s[8:9]
	s_add_i32 m0, s38, 0x2000
	s_nop 0
	global_load_lds_dwordx4 v158, s[8:9]
	s_mov_b32 m0, s51
	s_nop 0
	global_load_lds_dwordx4 v156, s[100:101]
	s_mov_b32 m0, s52
	s_nop 0
	global_load_lds_dwordx4 v158, s[100:101]
	s_waitcnt vmcnt(8)
	s_waitcnt lgkmcnt(0)
	s_barrier
	v_mfma_f32_16x16x32_bf16 v[60:63], v[84:87], v[174:177], v[60:63]
	v_mfma_f32_16x16x32_bf16 v[56:59], v[120:123], v[174:177], v[56:59]
	v_mfma_f32_16x16x32_bf16 v[44:47], v[84:87], v[182:185], v[44:47]
	v_mfma_f32_16x16x32_bf16 v[40:43], v[120:123], v[182:185], v[40:43]
	v_mfma_f32_16x16x32_bf16 v[28:31], v[84:87], v[190:193], v[28:31]
	v_mfma_f32_16x16x32_bf16 v[24:27], v[120:123], v[190:193], v[24:27]
	v_mfma_f32_16x16x32_bf16 v[12:15], v[84:87], v[198:201], v[12:15]
	v_mfma_f32_16x16x32_bf16 v[8:11], v[120:123], v[198:201], v[8:11]
	v_mfma_f32_16x16x32_bf16 v[60:63], v[100:103], v[178:181], v[60:63]
	v_mfma_f32_16x16x32_bf16 v[56:59], v[140:143], v[178:181], v[56:59]
	v_mfma_f32_16x16x32_bf16 v[44:47], v[100:103], v[186:189], v[44:47]
	v_mfma_f32_16x16x32_bf16 v[40:43], v[140:143], v[186:189], v[40:43]
	v_mfma_f32_16x16x32_bf16 v[28:31], v[100:103], v[194:197], v[28:31]
	v_mfma_f32_16x16x32_bf16 v[24:27], v[140:143], v[194:197], v[24:27]
	v_mfma_f32_16x16x32_bf16 v[12:15], v[100:103], v[202:205], v[12:15]
	v_mfma_f32_16x16x32_bf16 v[8:11], v[140:143], v[202:205], v[8:11]
	v_mfma_f32_16x16x32_bf16 v[52:55], v[144:147], v[174:177], v[52:55]
	v_mfma_f32_16x16x32_bf16 v[48:51], v[152:155], v[174:177], v[48:51]
	v_mfma_f32_16x16x32_bf16 v[36:39], v[144:147], v[182:185], v[36:39]
	v_mfma_f32_16x16x32_bf16 v[32:35], v[152:155], v[182:185], v[32:35]
	v_mfma_f32_16x16x32_bf16 v[20:23], v[144:147], v[190:193], v[20:23]
	v_mfma_f32_16x16x32_bf16 v[16:19], v[152:155], v[190:193], v[16:19]
	v_mfma_f32_16x16x32_bf16 v[4:7], v[144:147], v[198:201], v[4:7]
	v_mfma_f32_16x16x32_bf16 v[0:3], v[152:155], v[198:201], v[0:3]
	v_mfma_f32_16x16x32_bf16 v[52:55], v[148:151], v[178:181], v[52:55]
	v_mfma_f32_16x16x32_bf16 v[48:51], v[170:173], v[178:181], v[48:51]
	v_mfma_f32_16x16x32_bf16 v[36:39], v[148:151], v[186:189], v[36:39]
	v_mfma_f32_16x16x32_bf16 v[32:35], v[170:173], v[186:189], v[32:35]
	v_mfma_f32_16x16x32_bf16 v[20:23], v[148:151], v[194:197], v[20:23]
	v_mfma_f32_16x16x32_bf16 v[16:19], v[170:173], v[194:197], v[16:19]
	v_mfma_f32_16x16x32_bf16 v[4:7], v[148:151], v[202:205], v[4:7]
	v_mfma_f32_16x16x32_bf16 v[0:3], v[170:173], v[202:205], v[0:3]
	s_barrier
	s_add_i32 s83, s83, 2
	s_add_u32 s81, s81, 0x100
	s_addc_u32 s82, s82, 0
	s_cmp_gt_u32 s83, 3
	s_mov_b64 s[8:9], s[6:7]
	s_cbranch_scc0 .LBB0_771

.LBB0_937:
	s_ashr_i32 s27, s26, 31
	s_lshl_b64 s[28:29], s[26:27], 18
	s_add_u32 s28, s3, s28
	s_addc_u32 s29, s44, s29
	s_and_b64 s[30:31], s[4:5], exec
	s_cselect_b32 s9, s29, s7
	s_cselect_b32 s27, s28, s6
	s_ashr_i32 s23, s22, 31
	s_lshl_b64 s[30:31], s[22:23], 18
	s_add_u32 s30, s45, s30
	s_addc_u32 s31, s46, s31
	s_and_b64 s[38:39], s[4:5], exec
	s_cselect_b32 s23, s31, s37
	s_cselect_b32 s35, s30, s36
	s_add_u32 s6, s6, 0x20080
	s_addc_u32 s7, s7, 0
	s_add_u32 s40, s36, 0x100
	s_addc_u32 s41, s37, 0
	s_mov_b32 s42, -2
	ds_read_b128 v[128:131], v175
	ds_read_b128 v[132:135], v175 offset:1024
	ds_read_b128 v[136:139], v175 offset:2048
	ds_read_b128 v[140:143], v175 offset:3072
	ds_read_b128 v[144:147], v176
	ds_read_b128 v[148:151], v176 offset:1024
	ds_read_b128 v[168:171], v176 offset:2048
	ds_read_b128 v[182:185], v176 offset:3072
	s_add_u32 s36, s6, 0xfffe0080
	s_addc_u32 s37, s7, -1
	s_cmp_eq_u32 s42, 4
	s_cselect_b32 s39, s9, s37
	s_cselect_b32 s38, s27, s36
	s_cselect_b32 s37, s23, s41
	s_cselect_b32 s36, s35, s40
	s_add_i32 m0, s48, 0xc000
	ds_read_b128 v[186:189], v177
	ds_read_b128 v[190:193], v177 offset:1024
	ds_read_b128 v[194:197], v177 offset:2048
	ds_read_b128 v[198:201], v177 offset:3072
	ds_read_b128 v[202:205], v177 offset:4096
	ds_read_b128 v[206:209], v177 offset:5120
	ds_read_b128 v[210:213], v177 offset:6144
	ds_read_b128 v[214:217], v177 offset:7168
	global_load_lds_dwordx4 v158, s[6:7]
	s_add_i32 m0, s48, 0xe000
	s_nop 0
	global_load_lds_dwordx4 v160, s[6:7]
	s_waitcnt vmcnt(8)
	s_waitcnt lgkmcnt(0)
	s_barrier
	v_mfma_f32_16x16x32_bf16 v[124:127], v[128:131], v[186:189], 0
	v_mfma_f32_16x16x32_bf16 v[120:123], v[136:139], v[186:189], 0
	v_mfma_f32_16x16x32_bf16 v[112:115], v[128:131], v[194:197], 0
	v_mfma_f32_16x16x32_bf16 v[116:119], v[136:139], v[194:197], 0
	v_mfma_f32_16x16x32_bf16 v[96:99], v[128:131], v[202:205], 0
	v_mfma_f32_16x16x32_bf16 v[104:107], v[136:139], v[202:205], 0
	v_mfma_f32_16x16x32_bf16 v[76:79], v[128:131], v[210:213], 0
	v_mfma_f32_16x16x32_bf16 v[72:75], v[136:139], v[210:213], 0
	v_mfma_f32_16x16x32_bf16 v[124:127], v[132:135], v[190:193], v[124:127]
	v_mfma_f32_16x16x32_bf16 v[120:123], v[140:143], v[190:193], v[120:123]
	v_mfma_f32_16x16x32_bf16 v[112:115], v[132:135], v[198:201], v[112:115]
	v_mfma_f32_16x16x32_bf16 v[116:119], v[140:143], v[198:201], v[116:119]
	v_mfma_f32_16x16x32_bf16 v[96:99], v[132:135], v[206:209], v[96:99]
	v_mfma_f32_16x16x32_bf16 v[104:107], v[140:143], v[206:209], v[104:107]
	v_mfma_f32_16x16x32_bf16 v[76:79], v[132:135], v[214:217], v[76:79]
	v_mfma_f32_16x16x32_bf16 v[72:75], v[140:143], v[214:217], v[72:75]
	v_mfma_f32_16x16x32_bf16 v[108:111], v[144:147], v[186:189], 0
	v_mfma_f32_16x16x32_bf16 v[100:103], v[168:171], v[186:189], 0
	v_mfma_f32_16x16x32_bf16 v[88:91], v[144:147], v[194:197], 0
	v_mfma_f32_16x16x32_bf16 v[92:95], v[168:171], v[194:197], 0
	v_mfma_f32_16x16x32_bf16 v[84:87], v[144:147], v[202:205], 0
	v_mfma_f32_16x16x32_bf16 v[80:83], v[168:171], v[202:205], 0
	v_mfma_f32_16x16x32_bf16 v[68:71], v[144:147], v[210:213], 0
	v_mfma_f32_16x16x32_bf16 v[64:67], v[168:171], v[210:213], 0
	v_mfma_f32_16x16x32_bf16 v[108:111], v[148:151], v[190:193], v[108:111]
	v_mfma_f32_16x16x32_bf16 v[100:103], v[182:185], v[190:193], v[100:103]
	v_mfma_f32_16x16x32_bf16 v[88:91], v[148:151], v[198:201], v[88:91]
	v_mfma_f32_16x16x32_bf16 v[92:95], v[182:185], v[198:201], v[92:95]
	v_mfma_f32_16x16x32_bf16 v[84:87], v[148:151], v[206:209], v[84:87]
	v_mfma_f32_16x16x32_bf16 v[80:83], v[182:185], v[206:209], v[80:83]
	v_mfma_f32_16x16x32_bf16 v[68:71], v[148:151], v[214:217], v[68:71]
	v_mfma_f32_16x16x32_bf16 v[64:67], v[182:185], v[214:217], v[64:67]
	s_barrier
	s_add_i32 s43, s72, s47
	s_add_u32 s98, s36, 0x80
	s_addc_u32 s99, s37, 0
	s_mov_b32 m0, s43
	ds_read_b128 v[186:189], v177 offset:16384
	ds_read_b128 v[190:193], v177 offset:17408
	ds_read_b128 v[194:197], v177 offset:18432
	ds_read_b128 v[198:201], v177 offset:19456
	ds_read_b128 v[202:205], v177 offset:20480
	ds_read_b128 v[206:209], v177 offset:21504
	ds_read_b128 v[210:213], v177 offset:22528
	ds_read_b128 v[214:217], v177 offset:23552
	global_load_lds_dwordx4 v152, s[36:37]
	s_add_i32 m0, s43, 0x2000
	s_add_u32 s88, s36, 0x20000
	s_addc_u32 s89, s37, 0
	s_add_i32 s43, s73, s47
	global_load_lds_dwordx4 v154, s[36:37]
	s_mov_b32 m0, s43
	s_add_u32 s100, s38, 0x80
	s_addc_u32 s101, s39, 0
	global_load_lds_dwordx4 v152, s[88:89]
	s_add_i32 m0, s43, 0x2000
	s_nop 0
	global_load_lds_dwordx4 v154, s[88:89]
	s_mov_b32 m0, s48
	s_nop 0
	global_load_lds_dwordx4 v152, s[38:39]
	s_mov_b32 m0, s49
	s_nop 0
	global_load_lds_dwordx4 v154, s[38:39]
	s_waitcnt vmcnt(8)
	s_waitcnt lgkmcnt(0)
	s_barrier
	v_mfma_f32_16x16x32_bf16 v[60:63], v[128:131], v[186:189], 0
	v_mfma_f32_16x16x32_bf16 v[56:59], v[136:139], v[186:189], 0
	v_mfma_f32_16x16x32_bf16 v[44:47], v[128:131], v[194:197], 0
	v_mfma_f32_16x16x32_bf16 v[40:43], v[136:139], v[194:197], 0
	v_mfma_f32_16x16x32_bf16 v[28:31], v[128:131], v[202:205], 0
	v_mfma_f32_16x16x32_bf16 v[24:27], v[136:139], v[202:205], 0
	v_mfma_f32_16x16x32_bf16 v[12:15], v[128:131], v[210:213], 0
	v_mfma_f32_16x16x32_bf16 v[8:11], v[136:139], v[210:213], 0
	v_mfma_f32_16x16x32_bf16 v[60:63], v[132:135], v[190:193], v[60:63]
	v_mfma_f32_16x16x32_bf16 v[56:59], v[140:143], v[190:193], v[56:59]
	v_mfma_f32_16x16x32_bf16 v[44:47], v[132:135], v[198:201], v[44:47]
	v_mfma_f32_16x16x32_bf16 v[40:43], v[140:143], v[198:201], v[40:43]
	v_mfma_f32_16x16x32_bf16 v[28:31], v[132:135], v[206:209], v[28:31]
	v_mfma_f32_16x16x32_bf16 v[24:27], v[140:143], v[206:209], v[24:27]
	v_mfma_f32_16x16x32_bf16 v[12:15], v[132:135], v[214:217], v[12:15]
	v_mfma_f32_16x16x32_bf16 v[8:11], v[140:143], v[214:217], v[8:11]
	v_mfma_f32_16x16x32_bf16 v[52:55], v[144:147], v[186:189], 0
	v_mfma_f32_16x16x32_bf16 v[48:51], v[168:171], v[186:189], 0
	v_mfma_f32_16x16x32_bf16 v[36:39], v[144:147], v[194:197], 0
	v_mfma_f32_16x16x32_bf16 v[32:35], v[168:171], v[194:197], 0
	v_mfma_f32_16x16x32_bf16 v[20:23], v[144:147], v[202:205], 0
	v_mfma_f32_16x16x32_bf16 v[16:19], v[168:171], v[202:205], 0
	v_mfma_f32_16x16x32_bf16 v[4:7], v[144:147], v[210:213], 0
	v_mfma_f32_16x16x32_bf16 v[0:3], v[168:171], v[210:213], 0
	v_mfma_f32_16x16x32_bf16 v[52:55], v[148:151], v[190:193], v[52:55]
	v_mfma_f32_16x16x32_bf16 v[48:51], v[182:185], v[190:193], v[48:51]
	v_mfma_f32_16x16x32_bf16 v[36:39], v[148:151], v[198:201], v[36:39]
	v_mfma_f32_16x16x32_bf16 v[32:35], v[182:185], v[198:201], v[32:35]
	v_mfma_f32_16x16x32_bf16 v[20:23], v[148:151], v[206:209], v[20:23]
	v_mfma_f32_16x16x32_bf16 v[16:19], v[182:185], v[206:209], v[16:19]
	v_mfma_f32_16x16x32_bf16 v[4:7], v[148:151], v[214:217], v[4:7]
	v_mfma_f32_16x16x32_bf16 v[0:3], v[182:185], v[214:217], v[0:3]
	s_barrier
	s_add_i32 s43, 0, 0x18000
	s_add_i32 s88, 0, 0x1c000
	v_add_u32_e32 v140, s43, v173
	v_add_u32_e32 v156, s88, v173
	ds_read_b128 v[128:131], v140
	ds_read_b128 v[132:135], v140 offset:1024
	ds_read_b128 v[136:139], v140 offset:2048
	ds_read_b128 v[140:143], v140 offset:3072
	ds_read_b128 v[144:147], v156
	ds_read_b128 v[148:151], v156 offset:1024
	ds_read_b128 v[168:171], v156 offset:2048
	ds_read_b128 v[182:185], v156 offset:3072
	s_add_u32 s38, s38, 0x20000
	s_addc_u32 s39, s39, 0
	s_mov_b32 m0, s50
	ds_read_b128 v[186:189], v177 offset:32768
	ds_read_b128 v[190:193], v177 offset:33792
	ds_read_b128 v[194:197], v177 offset:34816
	ds_read_b128 v[198:201], v177 offset:35840
	ds_read_b128 v[202:205], v177 offset:36864
	ds_read_b128 v[206:209], v177 offset:37888
	ds_read_b128 v[210:213], v177 offset:38912
	ds_read_b128 v[214:217], v177 offset:39936
	global_load_lds_dwordx4 v152, s[38:39]
	s_mov_b32 m0, s51
	s_nop 0
	global_load_lds_dwordx4 v154, s[38:39]
	s_waitcnt vmcnt(8)
	s_waitcnt lgkmcnt(0)
	s_barrier
	v_mfma_f32_16x16x32_bf16 v[124:127], v[128:131], v[186:189], v[124:127]
	v_mfma_f32_16x16x32_bf16 v[120:123], v[136:139], v[186:189], v[120:123]
	v_mfma_f32_16x16x32_bf16 v[112:115], v[128:131], v[194:197], v[112:115]
	v_mfma_f32_16x16x32_bf16 v[116:119], v[136:139], v[194:197], v[116:119]
	v_mfma_f32_16x16x32_bf16 v[96:99], v[128:131], v[202:205], v[96:99]
	v_mfma_f32_16x16x32_bf16 v[104:107], v[136:139], v[202:205], v[104:107]
	v_mfma_f32_16x16x32_bf16 v[76:79], v[128:131], v[210:213], v[76:79]
	v_mfma_f32_16x16x32_bf16 v[72:75], v[136:139], v[210:213], v[72:75]
	v_mfma_f32_16x16x32_bf16 v[124:127], v[132:135], v[190:193], v[124:127]
	v_mfma_f32_16x16x32_bf16 v[120:123], v[140:143], v[190:193], v[120:123]
	v_mfma_f32_16x16x32_bf16 v[112:115], v[132:135], v[198:201], v[112:115]
	v_mfma_f32_16x16x32_bf16 v[116:119], v[140:143], v[198:201], v[116:119]
	v_mfma_f32_16x16x32_bf16 v[96:99], v[132:135], v[206:209], v[96:99]
	v_mfma_f32_16x16x32_bf16 v[104:107], v[140:143], v[206:209], v[104:107]
	v_mfma_f32_16x16x32_bf16 v[76:79], v[132:135], v[214:217], v[76:79]
	v_mfma_f32_16x16x32_bf16 v[72:75], v[140:143], v[214:217], v[72:75]
	v_mfma_f32_16x16x32_bf16 v[108:111], v[144:147], v[186:189], v[108:111]
	v_mfma_f32_16x16x32_bf16 v[100:103], v[168:171], v[186:189], v[100:103]
	v_mfma_f32_16x16x32_bf16 v[88:91], v[144:147], v[194:197], v[88:91]
	v_mfma_f32_16x16x32_bf16 v[92:95], v[168:171], v[194:197], v[92:95]
	v_mfma_f32_16x16x32_bf16 v[84:87], v[144:147], v[202:205], v[84:87]
	v_mfma_f32_16x16x32_bf16 v[80:83], v[168:171], v[202:205], v[80:83]
	v_mfma_f32_16x16x32_bf16 v[68:71], v[144:147], v[210:213], v[68:71]
	v_mfma_f32_16x16x32_bf16 v[64:67], v[168:171], v[210:213], v[64:67]
	v_mfma_f32_16x16x32_bf16 v[108:111], v[148:151], v[190:193], v[108:111]
	v_mfma_f32_16x16x32_bf16 v[100:103], v[182:185], v[190:193], v[100:103]
	v_mfma_f32_16x16x32_bf16 v[88:91], v[148:151], v[198:201], v[88:91]
	v_mfma_f32_16x16x32_bf16 v[92:95], v[182:185], v[198:201], v[92:95]
	v_mfma_f32_16x16x32_bf16 v[84:87], v[148:151], v[206:209], v[84:87]
	v_mfma_f32_16x16x32_bf16 v[80:83], v[182:185], v[206:209], v[80:83]
	v_mfma_f32_16x16x32_bf16 v[68:71], v[148:151], v[214:217], v[68:71]
	v_mfma_f32_16x16x32_bf16 v[64:67], v[182:185], v[214:217], v[64:67]
	s_barrier
	s_add_i32 s38, s43, s47
	s_mov_b32 m0, s38
	ds_read_b128 v[186:189], v177 offset:49152
	ds_read_b128 v[190:193], v177 offset:50176
	ds_read_b128 v[194:197], v177 offset:51200
	ds_read_b128 v[198:201], v177 offset:52224
	ds_read_b128 v[202:205], v177 offset:53248
	ds_read_b128 v[206:209], v177 offset:54272
	ds_read_b128 v[210:213], v177 offset:55296
	ds_read_b128 v[214:217], v177 offset:56320
	global_load_lds_dwordx4 v152, s[98:99]
	s_add_i32 m0, s38, 0x2000
	s_add_u32 s36, s36, 0x20080
	s_addc_u32 s37, s37, 0
	s_add_i32 s38, s88, s47
	global_load_lds_dwordx4 v154, s[98:99]
	s_mov_b32 m0, s38
	s_nop 0
	global_load_lds_dwordx4 v152, s[36:37]
	s_add_i32 m0, s38, 0x2000
	s_nop 0
	global_load_lds_dwordx4 v154, s[36:37]
	s_mov_b32 m0, s61
	s_nop 0
	global_load_lds_dwordx4 v152, s[100:101]
	s_mov_b32 m0, s62
	s_nop 0
	global_load_lds_dwordx4 v154, s[100:101]
	s_waitcnt vmcnt(8)
	s_waitcnt lgkmcnt(0)
	s_barrier
	v_mfma_f32_16x16x32_bf16 v[60:63], v[128:131], v[186:189], v[60:63]
	v_mfma_f32_16x16x32_bf16 v[56:59], v[136:139], v[186:189], v[56:59]
	v_mfma_f32_16x16x32_bf16 v[44:47], v[128:131], v[194:197], v[44:47]
	v_mfma_f32_16x16x32_bf16 v[40:43], v[136:139], v[194:197], v[40:43]
	v_mfma_f32_16x16x32_bf16 v[28:31], v[128:131], v[202:205], v[28:31]
	v_mfma_f32_16x16x32_bf16 v[24:27], v[136:139], v[202:205], v[24:27]
	v_mfma_f32_16x16x32_bf16 v[12:15], v[128:131], v[210:213], v[12:15]
	v_mfma_f32_16x16x32_bf16 v[8:11], v[136:139], v[210:213], v[8:11]
	v_mfma_f32_16x16x32_bf16 v[60:63], v[132:135], v[190:193], v[60:63]
	v_mfma_f32_16x16x32_bf16 v[56:59], v[140:143], v[190:193], v[56:59]
	v_mfma_f32_16x16x32_bf16 v[44:47], v[132:135], v[198:201], v[44:47]
	v_mfma_f32_16x16x32_bf16 v[40:43], v[140:143], v[198:201], v[40:43]
	v_mfma_f32_16x16x32_bf16 v[28:31], v[132:135], v[206:209], v[28:31]
	v_mfma_f32_16x16x32_bf16 v[24:27], v[140:143], v[206:209], v[24:27]
	v_mfma_f32_16x16x32_bf16 v[12:15], v[132:135], v[214:217], v[12:15]
	v_mfma_f32_16x16x32_bf16 v[8:11], v[140:143], v[214:217], v[8:11]
	v_mfma_f32_16x16x32_bf16 v[52:55], v[144:147], v[186:189], v[52:55]
	v_mfma_f32_16x16x32_bf16 v[48:51], v[168:171], v[186:189], v[48:51]
	v_mfma_f32_16x16x32_bf16 v[36:39], v[144:147], v[194:197], v[36:39]
	v_mfma_f32_16x16x32_bf16 v[32:35], v[168:171], v[194:197], v[32:35]
	v_mfma_f32_16x16x32_bf16 v[20:23], v[144:147], v[202:205], v[20:23]
	v_mfma_f32_16x16x32_bf16 v[16:19], v[168:171], v[202:205], v[16:19]
	v_mfma_f32_16x16x32_bf16 v[4:7], v[144:147], v[210:213], v[4:7]
	v_mfma_f32_16x16x32_bf16 v[0:3], v[168:171], v[210:213], v[0:3]
	v_mfma_f32_16x16x32_bf16 v[52:55], v[148:151], v[190:193], v[52:55]
	v_mfma_f32_16x16x32_bf16 v[48:51], v[182:185], v[190:193], v[48:51]
	v_mfma_f32_16x16x32_bf16 v[36:39], v[148:151], v[198:201], v[36:39]
	v_mfma_f32_16x16x32_bf16 v[32:35], v[182:185], v[198:201], v[32:35]
	v_mfma_f32_16x16x32_bf16 v[20:23], v[148:151], v[206:209], v[20:23]
	v_mfma_f32_16x16x32_bf16 v[16:19], v[182:185], v[206:209], v[16:19]
	v_mfma_f32_16x16x32_bf16 v[4:7], v[148:151], v[214:217], v[4:7]
	v_mfma_f32_16x16x32_bf16 v[0:3], v[182:185], v[214:217], v[0:3]
	s_barrier
	s_add_i32 s42, s42, 2
	s_add_u32 s6, s6, 0x100
	s_addc_u32 s7, s7, 0
	s_add_u32 s40, s40, 0x100
	s_addc_u32 s41, s41, 0
	s_cmp_gt_u32 s42, 5
	s_cbranch_scc1 .Lkx_938
.LBB0_938:
	ds_read_b128 v[128:131], v175
	ds_read_b128 v[132:135], v175 offset:1024
	ds_read_b128 v[136:139], v175 offset:2048
	ds_read_b128 v[140:143], v175 offset:3072
	ds_read_b128 v[144:147], v176
	ds_read_b128 v[148:151], v176 offset:1024
	ds_read_b128 v[168:171], v176 offset:2048
	ds_read_b128 v[182:185], v176 offset:3072
	s_add_u32 s36, s6, 0xfffe0080
	s_addc_u32 s37, s7, -1
	s_cmp_eq_u32 s42, 4
	s_cselect_b32 s39, s9, s37
	s_cselect_b32 s38, s27, s36
	s_cselect_b32 s37, s23, s41
	s_cselect_b32 s36, s35, s40
	s_add_i32 m0, s48, 0xc000
	ds_read_b128 v[186:189], v177
	ds_read_b128 v[190:193], v177 offset:1024
	ds_read_b128 v[194:197], v177 offset:2048
	ds_read_b128 v[198:201], v177 offset:3072
	ds_read_b128 v[202:205], v177 offset:4096
	ds_read_b128 v[206:209], v177 offset:5120
	ds_read_b128 v[210:213], v177 offset:6144
	ds_read_b128 v[214:217], v177 offset:7168
	global_load_lds_dwordx4 v158, s[6:7]
	s_add_i32 m0, s48, 0xe000
	s_nop 0
	global_load_lds_dwordx4 v160, s[6:7]
	s_waitcnt vmcnt(8)
	s_waitcnt lgkmcnt(0)
	s_barrier
	v_mfma_f32_16x16x32_bf16 v[124:127], v[128:131], v[186:189], v[124:127]
	v_mfma_f32_16x16x32_bf16 v[120:123], v[136:139], v[186:189], v[120:123]
	v_mfma_f32_16x16x32_bf16 v[112:115], v[128:131], v[194:197], v[112:115]
	v_mfma_f32_16x16x32_bf16 v[116:119], v[136:139], v[194:197], v[116:119]
	v_mfma_f32_16x16x32_bf16 v[96:99], v[128:131], v[202:205], v[96:99]
	v_mfma_f32_16x16x32_bf16 v[104:107], v[136:139], v[202:205], v[104:107]
	v_mfma_f32_16x16x32_bf16 v[76:79], v[128:131], v[210:213], v[76:79]
	v_mfma_f32_16x16x32_bf16 v[72:75], v[136:139], v[210:213], v[72:75]
	v_mfma_f32_16x16x32_bf16 v[124:127], v[132:135], v[190:193], v[124:127]
	v_mfma_f32_16x16x32_bf16 v[120:123], v[140:143], v[190:193], v[120:123]
	v_mfma_f32_16x16x32_bf16 v[112:115], v[132:135], v[198:201], v[112:115]
	v_mfma_f32_16x16x32_bf16 v[116:119], v[140:143], v[198:201], v[116:119]
	v_mfma_f32_16x16x32_bf16 v[96:99], v[132:135], v[206:209], v[96:99]
	v_mfma_f32_16x16x32_bf16 v[104:107], v[140:143], v[206:209], v[104:107]
	v_mfma_f32_16x16x32_bf16 v[76:79], v[132:135], v[214:217], v[76:79]
	v_mfma_f32_16x16x32_bf16 v[72:75], v[140:143], v[214:217], v[72:75]
	v_mfma_f32_16x16x32_bf16 v[108:111], v[144:147], v[186:189], v[108:111]
	v_mfma_f32_16x16x32_bf16 v[100:103], v[168:171], v[186:189], v[100:103]
	v_mfma_f32_16x16x32_bf16 v[88:91], v[144:147], v[194:197], v[88:91]
	v_mfma_f32_16x16x32_bf16 v[92:95], v[168:171], v[194:197], v[92:95]
	v_mfma_f32_16x16x32_bf16 v[84:87], v[144:147], v[202:205], v[84:87]
	v_mfma_f32_16x16x32_bf16 v[80:83], v[168:171], v[202:205], v[80:83]
	v_mfma_f32_16x16x32_bf16 v[68:71], v[144:147], v[210:213], v[68:71]
	v_mfma_f32_16x16x32_bf16 v[64:67], v[168:171], v[210:213], v[64:67]
	v_mfma_f32_16x16x32_bf16 v[108:111], v[148:151], v[190:193], v[108:111]
	v_mfma_f32_16x16x32_bf16 v[100:103], v[182:185], v[190:193], v[100:103]
	v_mfma_f32_16x16x32_bf16 v[88:91], v[148:151], v[198:201], v[88:91]
	v_mfma_f32_16x16x32_bf16 v[92:95], v[182:185], v[198:201], v[92:95]
	v_mfma_f32_16x16x32_bf16 v[84:87], v[148:151], v[206:209], v[84:87]
	v_mfma_f32_16x16x32_bf16 v[80:83], v[182:185], v[206:209], v[80:83]
	v_mfma_f32_16x16x32_bf16 v[68:71], v[148:151], v[214:217], v[68:71]
	v_mfma_f32_16x16x32_bf16 v[64:67], v[182:185], v[214:217], v[64:67]
	s_barrier
	s_add_i32 s43, s72, s47
	s_add_u32 s98, s36, 0x80
	s_addc_u32 s99, s37, 0
	s_mov_b32 m0, s43
	ds_read_b128 v[186:189], v177 offset:16384
	ds_read_b128 v[190:193], v177 offset:17408
	ds_read_b128 v[194:197], v177 offset:18432
	ds_read_b128 v[198:201], v177 offset:19456
	ds_read_b128 v[202:205], v177 offset:20480
	ds_read_b128 v[206:209], v177 offset:21504
	ds_read_b128 v[210:213], v177 offset:22528
	ds_read_b128 v[214:217], v177 offset:23552
	global_load_lds_dwordx4 v152, s[36:37]
	s_add_i32 m0, s43, 0x2000
	s_add_u32 s88, s36, 0x20000
	s_addc_u32 s89, s37, 0
	s_add_i32 s43, s73, s47
	global_load_lds_dwordx4 v154, s[36:37]
	s_mov_b32 m0, s43
	s_add_u32 s100, s38, 0x80
	s_addc_u32 s101, s39, 0
	global_load_lds_dwordx4 v152, s[88:89]
	s_add_i32 m0, s43, 0x2000
	s_nop 0
	global_load_lds_dwordx4 v154, s[88:89]
	s_mov_b32 m0, s48
	s_nop 0
	global_load_lds_dwordx4 v152, s[38:39]
	s_mov_b32 m0, s49
	s_nop 0
	global_load_lds_dwordx4 v154, s[38:39]
	s_waitcnt vmcnt(8)
	s_waitcnt lgkmcnt(0)
	s_barrier
	v_mfma_f32_16x16x32_bf16 v[60:63], v[128:131], v[186:189], v[60:63]
	v_mfma_f32_16x16x32_bf16 v[56:59], v[136:139], v[186:189], v[56:59]
	v_mfma_f32_16x16x32_bf16 v[44:47], v[128:131], v[194:197], v[44:47]
	v_mfma_f32_16x16x32_bf16 v[40:43], v[136:139], v[194:197], v[40:43]
	v_mfma_f32_16x16x32_bf16 v[28:31], v[128:131], v[202:205], v[28:31]
	v_mfma_f32_16x16x32_bf16 v[24:27], v[136:139], v[202:205], v[24:27]
	v_mfma_f32_16x16x32_bf16 v[12:15], v[128:131], v[210:213], v[12:15]
	v_mfma_f32_16x16x32_bf16 v[8:11], v[136:139], v[210:213], v[8:11]
	v_mfma_f32_16x16x32_bf16 v[60:63], v[132:135], v[190:193], v[60:63]
	v_mfma_f32_16x16x32_bf16 v[56:59], v[140:143], v[190:193], v[56:59]
	v_mfma_f32_16x16x32_bf16 v[44:47], v[132:135], v[198:201], v[44:47]
	v_mfma_f32_16x16x32_bf16 v[40:43], v[140:143], v[198:201], v[40:43]
	v_mfma_f32_16x16x32_bf16 v[28:31], v[132:135], v[206:209], v[28:31]
	v_mfma_f32_16x16x32_bf16 v[24:27], v[140:143], v[206:209], v[24:27]
	v_mfma_f32_16x16x32_bf16 v[12:15], v[132:135], v[214:217], v[12:15]
	v_mfma_f32_16x16x32_bf16 v[8:11], v[140:143], v[214:217], v[8:11]
	v_mfma_f32_16x16x32_bf16 v[52:55], v[144:147], v[186:189], v[52:55]
	v_mfma_f32_16x16x32_bf16 v[48:51], v[168:171], v[186:189], v[48:51]
	v_mfma_f32_16x16x32_bf16 v[36:39], v[144:147], v[194:197], v[36:39]
	v_mfma_f32_16x16x32_bf16 v[32:35], v[168:171], v[194:197], v[32:35]
	v_mfma_f32_16x16x32_bf16 v[20:23], v[144:147], v[202:205], v[20:23]
	v_mfma_f32_16x16x32_bf16 v[16:19], v[168:171], v[202:205], v[16:19]
	v_mfma_f32_16x16x32_bf16 v[4:7], v[144:147], v[210:213], v[4:7]
	v_mfma_f32_16x16x32_bf16 v[0:3], v[168:171], v[210:213], v[0:3]
	v_mfma_f32_16x16x32_bf16 v[52:55], v[148:151], v[190:193], v[52:55]
	v_mfma_f32_16x16x32_bf16 v[48:51], v[182:185], v[190:193], v[48:51]
	v_mfma_f32_16x16x32_bf16 v[36:39], v[148:151], v[198:201], v[36:39]
	v_mfma_f32_16x16x32_bf16 v[32:35], v[182:185], v[198:201], v[32:35]
	v_mfma_f32_16x16x32_bf16 v[20:23], v[148:151], v[206:209], v[20:23]
	v_mfma_f32_16x16x32_bf16 v[16:19], v[182:185], v[206:209], v[16:19]
	v_mfma_f32_16x16x32_bf16 v[4:7], v[148:151], v[214:217], v[4:7]
	v_mfma_f32_16x16x32_bf16 v[0:3], v[182:185], v[214:217], v[0:3]
	s_barrier
	s_add_i32 s43, 0, 0x18000
	s_add_i32 s88, 0, 0x1c000
	v_add_u32_e32 v140, s43, v173
	v_add_u32_e32 v156, s88, v173
	ds_read_b128 v[128:131], v140
	ds_read_b128 v[132:135], v140 offset:1024
	ds_read_b128 v[136:139], v140 offset:2048
	ds_read_b128 v[140:143], v140 offset:3072
	ds_read_b128 v[144:147], v156
	ds_read_b128 v[148:151], v156 offset:1024
	ds_read_b128 v[168:171], v156 offset:2048
	ds_read_b128 v[182:185], v156 offset:3072
	s_add_u32 s38, s38, 0x20000
	s_addc_u32 s39, s39, 0
	s_mov_b32 m0, s50
	ds_read_b128 v[186:189], v177 offset:32768
	ds_read_b128 v[190:193], v177 offset:33792
	ds_read_b128 v[194:197], v177 offset:34816
	ds_read_b128 v[198:201], v177 offset:35840
	ds_read_b128 v[202:205], v177 offset:36864
	ds_read_b128 v[206:209], v177 offset:37888
	ds_read_b128 v[210:213], v177 offset:38912
	ds_read_b128 v[214:217], v177 offset:39936
	global_load_lds_dwordx4 v152, s[38:39]
	s_mov_b32 m0, s51
	s_nop 0
	global_load_lds_dwordx4 v154, s[38:39]
	s_waitcnt vmcnt(8)
	s_waitcnt lgkmcnt(0)
	s_barrier
	v_mfma_f32_16x16x32_bf16 v[124:127], v[128:131], v[186:189], v[124:127]
	v_mfma_f32_16x16x32_bf16 v[120:123], v[136:139], v[186:189], v[120:123]
	v_mfma_f32_16x16x32_bf16 v[112:115], v[128:131], v[194:197], v[112:115]
	v_mfma_f32_16x16x32_bf16 v[116:119], v[136:139], v[194:197], v[116:119]
	v_mfma_f32_16x16x32_bf16 v[96:99], v[128:131], v[202:205], v[96:99]
	v_mfma_f32_16x16x32_bf16 v[104:107], v[136:139], v[202:205], v[104:107]
	v_mfma_f32_16x16x32_bf16 v[76:79], v[128:131], v[210:213], v[76:79]
	v_mfma_f32_16x16x32_bf16 v[72:75], v[136:139], v[210:213], v[72:75]
	v_mfma_f32_16x16x32_bf16 v[124:127], v[132:135], v[190:193], v[124:127]
	v_mfma_f32_16x16x32_bf16 v[120:123], v[140:143], v[190:193], v[120:123]
	v_mfma_f32_16x16x32_bf16 v[112:115], v[132:135], v[198:201], v[112:115]
	v_mfma_f32_16x16x32_bf16 v[116:119], v[140:143], v[198:201], v[116:119]
	v_mfma_f32_16x16x32_bf16 v[96:99], v[132:135], v[206:209], v[96:99]
	v_mfma_f32_16x16x32_bf16 v[104:107], v[140:143], v[206:209], v[104:107]
	v_mfma_f32_16x16x32_bf16 v[76:79], v[132:135], v[214:217], v[76:79]
	v_mfma_f32_16x16x32_bf16 v[72:75], v[140:143], v[214:217], v[72:75]
	v_mfma_f32_16x16x32_bf16 v[108:111], v[144:147], v[186:189], v[108:111]
	v_mfma_f32_16x16x32_bf16 v[100:103], v[168:171], v[186:189], v[100:103]
	v_mfma_f32_16x16x32_bf16 v[88:91], v[144:147], v[194:197], v[88:91]
	v_mfma_f32_16x16x32_bf16 v[92:95], v[168:171], v[194:197], v[92:95]
	v_mfma_f32_16x16x32_bf16 v[84:87], v[144:147], v[202:205], v[84:87]
	v_mfma_f32_16x16x32_bf16 v[80:83], v[168:171], v[202:205], v[80:83]
	v_mfma_f32_16x16x32_bf16 v[68:71], v[144:147], v[210:213], v[68:71]
	v_mfma_f32_16x16x32_bf16 v[64:67], v[168:171], v[210:213], v[64:67]
	v_mfma_f32_16x16x32_bf16 v[108:111], v[148:151], v[190:193], v[108:111]
	v_mfma_f32_16x16x32_bf16 v[100:103], v[182:185], v[190:193], v[100:103]
	v_mfma_f32_16x16x32_bf16 v[88:91], v[148:151], v[198:201], v[88:91]
	v_mfma_f32_16x16x32_bf16 v[92:95], v[182:185], v[198:201], v[92:95]
	v_mfma_f32_16x16x32_bf16 v[84:87], v[148:151], v[206:209], v[84:87]
	v_mfma_f32_16x16x32_bf16 v[80:83], v[182:185], v[206:209], v[80:83]
	v_mfma_f32_16x16x32_bf16 v[68:71], v[148:151], v[214:217], v[68:71]
	v_mfma_f32_16x16x32_bf16 v[64:67], v[182:185], v[214:217], v[64:67]
	s_barrier
	s_add_i32 s38, s43, s47
	s_mov_b32 m0, s38
	ds_read_b128 v[186:189], v177 offset:49152
	ds_read_b128 v[190:193], v177 offset:50176
	ds_read_b128 v[194:197], v177 offset:51200
	ds_read_b128 v[198:201], v177 offset:52224
	ds_read_b128 v[202:205], v177 offset:53248
	ds_read_b128 v[206:209], v177 offset:54272
	ds_read_b128 v[210:213], v177 offset:55296
	ds_read_b128 v[214:217], v177 offset:56320
	global_load_lds_dwordx4 v152, s[98:99]
	s_add_i32 m0, s38, 0x2000
	s_add_u32 s36, s36, 0x20080
	s_addc_u32 s37, s37, 0
	s_add_i32 s38, s88, s47
	global_load_lds_dwordx4 v154, s[98:99]
	s_mov_b32 m0, s38
	s_nop 0
	global_load_lds_dwordx4 v152, s[36:37]
	s_add_i32 m0, s38, 0x2000
	s_nop 0
	global_load_lds_dwordx4 v154, s[36:37]
	s_mov_b32 m0, s61
	s_nop 0
	global_load_lds_dwordx4 v152, s[100:101]
	s_mov_b32 m0, s62
	s_nop 0
	global_load_lds_dwordx4 v154, s[100:101]
	s_waitcnt vmcnt(8)
	s_waitcnt lgkmcnt(0)
	s_barrier
	v_mfma_f32_16x16x32_bf16 v[60:63], v[128:131], v[186:189], v[60:63]
	v_mfma_f32_16x16x32_bf16 v[56:59], v[136:139], v[186:189], v[56:59]
	v_mfma_f32_16x16x32_bf16 v[44:47], v[128:131], v[194:197], v[44:47]
	v_mfma_f32_16x16x32_bf16 v[40:43], v[136:139], v[194:197], v[40:43]
	v_mfma_f32_16x16x32_bf16 v[28:31], v[128:131], v[202:205], v[28:31]
	v_mfma_f32_16x16x32_bf16 v[24:27], v[136:139], v[202:205], v[24:27]
	v_mfma_f32_16x16x32_bf16 v[12:15], v[128:131], v[210:213], v[12:15]
	v_mfma_f32_16x16x32_bf16 v[8:11], v[136:139], v[210:213], v[8:11]
	v_mfma_f32_16x16x32_bf16 v[60:63], v[132:135], v[190:193], v[60:63]
	v_mfma_f32_16x16x32_bf16 v[56:59], v[140:143], v[190:193], v[56:59]
	v_mfma_f32_16x16x32_bf16 v[44:47], v[132:135], v[198:201], v[44:47]
	v_mfma_f32_16x16x32_bf16 v[40:43], v[140:143], v[198:201], v[40:43]
	v_mfma_f32_16x16x32_bf16 v[28:31], v[132:135], v[206:209], v[28:31]
	v_mfma_f32_16x16x32_bf16 v[24:27], v[140:143], v[206:209], v[24:27]
	v_mfma_f32_16x16x32_bf16 v[12:15], v[132:135], v[214:217], v[12:15]
	v_mfma_f32_16x16x32_bf16 v[8:11], v[140:143], v[214:217], v[8:11]
	v_mfma_f32_16x16x32_bf16 v[52:55], v[144:147], v[186:189], v[52:55]
	v_mfma_f32_16x16x32_bf16 v[48:51], v[168:171], v[186:189], v[48:51]
	v_mfma_f32_16x16x32_bf16 v[36:39], v[144:147], v[194:197], v[36:39]
	v_mfma_f32_16x16x32_bf16 v[32:35], v[168:171], v[194:197], v[32:35]
	v_mfma_f32_16x16x32_bf16 v[20:23], v[144:147], v[202:205], v[20:23]
	v_mfma_f32_16x16x32_bf16 v[16:19], v[168:171], v[202:205], v[16:19]
	v_mfma_f32_16x16x32_bf16 v[4:7], v[144:147], v[210:213], v[4:7]
	v_mfma_f32_16x16x32_bf16 v[0:3], v[168:171], v[210:213], v[0:3]
	v_mfma_f32_16x16x32_bf16 v[52:55], v[148:151], v[190:193], v[52:55]
	v_mfma_f32_16x16x32_bf16 v[48:51], v[182:185], v[190:193], v[48:51]
	v_mfma_f32_16x16x32_bf16 v[36:39], v[148:151], v[198:201], v[36:39]
	v_mfma_f32_16x16x32_bf16 v[32:35], v[182:185], v[198:201], v[32:35]
	v_mfma_f32_16x16x32_bf16 v[20:23], v[148:151], v[206:209], v[20:23]
	v_mfma_f32_16x16x32_bf16 v[16:19], v[182:185], v[206:209], v[16:19]
	v_mfma_f32_16x16x32_bf16 v[4:7], v[148:151], v[214:217], v[4:7]
	v_mfma_f32_16x16x32_bf16 v[0:3], v[182:185], v[214:217], v[0:3]
	s_barrier
	s_add_i32 s42, s42, 2
	s_add_u32 s6, s6, 0x100
	s_addc_u32 s7, s7, 0
	s_add_u32 s40, s40, 0x100
	s_addc_u32 s41, s41, 0
	s_cmp_gt_u32 s42, 5
	s_cbranch_scc0 .LBB0_938
